# GEMM main loops: LDS-DMA loads switched to scalar-base addressing (per-lane 32-bit offset + SGPR base), removing the 16 per-iteration 64-bit VALU address adds; kstep variants get their base from SALU
# baseline (speedup 1.0000x reference)
; #define PG8_STAGE(bufoff, gbase, voff) do { _Pragma("unroll") for (int _i = 0; _i < 2; ++_i) \
;         __builtin_amdgcn_global_load_lds((const unsigned*)((const char*)(gbase) + (voff)[_i]), (LAS unsigned*)(lds + (bufoff) + ldsw + _i * 8192), 16, 0, 0); } while (0)
; #define PG8_LDA(dst, b, h) do { _Pragma("unroll") for (int m = 0; m < 4; ++m) _Pragma("unroll") for (int k = 0; k < 2; ++k) dst[m][k] = *(const LAS bf16x8*)(lds + PG8_SA(b, h) + aoff + m * 2048 + k * 1024); } while (0)
; #define PG8_LDB(dst, b, h) do { _Pragma("unroll") for (int n = 0; n < 2; ++n) _Pragma("unroll") for (int k = 0; k < 2; ++k) dst[n][k] = *(const LAS bf16x8*)(lds + PG8_SB(b, h) + boff + n * 2048 + k * 1024); } while (0)
; #define PG8_MMA(ai, bj, At, Bt) do { __builtin_amdgcn_s_setprio(1); _Pragma("unroll") for (int m = 0; m < 4; ++m) _Pragma("unroll") for (int n = 0; n < 2; ++n) _Pragma("unroll") for (int k = 0; k < 2; ++k) \
;         acc[ai][bj][m][n] = __builtin_amdgcn_mfma_f32_16x16x32_bf16(Bt[n][k], At[m][k], acc[ai][bj][m][n], 0, 0, 0); __builtin_amdgcn_s_setprio(0); } while (0)
; #define PG8_WAIT_V(n) asm volatile("s_waitcnt vmcnt(" #n ")" ::: "memory")
; #define PG8_WAIT_L(n) asm volatile("s_waitcnt lgkmcnt(" #n ")" ::: "memory")
; #define PG8_BAR __builtin_amdgcn_s_barrier()
; #define PG8_SCHED __builtin_amdgcn_sched_barrier(0)
; template <class Epi>
; __device__ __forceinline__ void gemm_phase(LAS unsigned char* lds, const Gemm g, const Epi& E) {
;     ...
;             PG8_LDB(B0, 0, 0); PG8_SCHED; PG8_LDA(At, 0, 0); PG8_STAGE(PG8_SA(1, 1), a1 + hstep, voffA);
;             PG8_WAIT_L(8); PG8_BAR; PG8_WAIT_L(0); PG8_MMA(0, 0, At, B0); PG8_BAR; PG8_SCHED;
;             PG8_LDB(B1, 0, 1); PG8_STAGE(PG8_SB(0, 0), b2, voffB);
;             PG8_BAR; PG8_WAIT_L(0); PG8_MMA(0, 1, At, B1); PG8_BAR;
;             PG8_LDA(At, 0, 1); PG8_STAGE(PG8_SA(0, 0), a2, voffA);
;             PG8_BAR; PG8_WAIT_L(0); PG8_MMA(1, 0, At, B0); PG8_BAR; PG8_SCHED;
;             PG8_STAGE(PG8_SB(0, 1), b2 + hstep, voffB);
;             PG8_WAIT_V(6); PG8_BAR; PG8_MMA(1, 1, At, B1); PG8_BAR;
.LBB0_30:
	s_add_u32 s28, s26, 0xfff80080
	s_addc_u32 s29, s27, -1
	s_add_i32 s34, 0, 0x10000
	v_add_u32_e32 v143, s34, v141
	ds_read_b128 v[144:147], v143
	ds_read_b128 v[148:151], v143 offset:1024
	ds_read_b128 v[152:155], v143 offset:2048
	ds_read_b128 v[156:159], v143 offset:3072
	s_cmp_eq_u32 s89, 28
	s_cselect_b32 s37, s45, s29
	s_cselect_b32 s36, s78, s28
	s_cselect_b32 s29, s43, s83
	s_cselect_b32 s28, s79, s82
	s_add_i32 m0, s39, 0xc000
	ds_read_b128 v[160:163], v142
	ds_read_b128 v[164:167], v142 offset:1024
	ds_read_b128 v[168:171], v142 offset:2048
	ds_read_b128 v[172:175], v142 offset:3072
	ds_read_b128 v[176:179], v142 offset:4096
	ds_read_b128 v[180:183], v142 offset:5120
	ds_read_b128 v[184:187], v142 offset:6144
	ds_read_b128 v[188:191], v142 offset:7168
	global_load_lds_dwordx4 v136, s[26:27]
	s_add_i32 m0, s39, 0xe000
	s_nop 0
	global_load_lds_dwordx4 v138, s[26:27]
	s_waitcnt lgkmcnt(8)
	s_barrier
	s_waitcnt lgkmcnt(0)
	s_setprio 1
	v_mfma_f32_16x16x32_bf16 v[124:127], v[144:147], v[160:163], v[124:127]
	v_mfma_f32_16x16x32_bf16 v[116:119], v[152:155], v[160:163], v[116:119]
	v_mfma_f32_16x16x32_bf16 v[108:111], v[144:147], v[168:171], v[108:111]
	v_mfma_f32_16x16x32_bf16 v[100:103], v[152:155], v[168:171], v[100:103]
	v_mfma_f32_16x16x32_bf16 v[92:95], v[144:147], v[176:179], v[92:95]
	v_mfma_f32_16x16x32_bf16 v[84:87], v[152:155], v[176:179], v[84:87]
	v_mfma_f32_16x16x32_bf16 v[76:79], v[144:147], v[184:187], v[76:79]
	v_mfma_f32_16x16x32_bf16 v[68:71], v[152:155], v[184:187], v[68:71]
	v_mfma_f32_16x16x32_bf16 v[124:127], v[148:151], v[164:167], v[124:127]
	v_mfma_f32_16x16x32_bf16 v[116:119], v[156:159], v[164:167], v[116:119]
	v_mfma_f32_16x16x32_bf16 v[108:111], v[148:151], v[172:175], v[108:111]
	v_mfma_f32_16x16x32_bf16 v[100:103], v[156:159], v[172:175], v[100:103]
	v_mfma_f32_16x16x32_bf16 v[92:95], v[148:151], v[180:183], v[92:95]
	v_mfma_f32_16x16x32_bf16 v[84:87], v[156:159], v[180:183], v[84:87]
	v_mfma_f32_16x16x32_bf16 v[76:79], v[148:151], v[188:191], v[76:79]
	v_mfma_f32_16x16x32_bf16 v[68:71], v[156:159], v[188:191], v[68:71]
	s_setprio 0
	s_barrier
	s_add_i32 s46, 0, 0x14000
	s_add_i32 s34, s34, s31
	v_add_u32_e32 v143, s46, v141
	s_mov_b32 m0, s34
	ds_read_b128 v[192:195], v143
	ds_read_b128 v[196:199], v143 offset:1024
	ds_read_b128 v[200:203], v143 offset:2048
	ds_read_b128 v[204:207], v143 offset:3072
	global_load_lds_dwordx4 v132, s[28:29]
	s_add_i32 m0, s34, 0x2000
	s_nop 0
	global_load_lds_dwordx4 v128, s[28:29]
	s_barrier
	s_waitcnt lgkmcnt(0)
	s_setprio 1
	v_mfma_f32_16x16x32_bf16 v[120:123], v[192:195], v[160:163], v[120:123]
	v_mfma_f32_16x16x32_bf16 v[112:115], v[200:203], v[160:163], v[112:115]
	v_mfma_f32_16x16x32_bf16 v[104:107], v[192:195], v[168:171], v[104:107]
	v_mfma_f32_16x16x32_bf16 v[96:99], v[200:203], v[168:171], v[96:99]
	v_mfma_f32_16x16x32_bf16 v[88:91], v[192:195], v[176:179], v[88:91]
	v_mfma_f32_16x16x32_bf16 v[80:83], v[200:203], v[176:179], v[80:83]
	v_mfma_f32_16x16x32_bf16 v[72:75], v[192:195], v[184:187], v[72:75]
	v_mfma_f32_16x16x32_bf16 v[64:67], v[200:203], v[184:187], v[64:67]
	v_mfma_f32_16x16x32_bf16 v[120:123], v[196:199], v[164:167], v[120:123]
	v_mfma_f32_16x16x32_bf16 v[112:115], v[204:207], v[164:167], v[112:115]
	v_mfma_f32_16x16x32_bf16 v[104:107], v[196:199], v[172:175], v[104:107]
	v_mfma_f32_16x16x32_bf16 v[96:99], v[204:207], v[172:175], v[96:99]
	v_mfma_f32_16x16x32_bf16 v[88:91], v[196:199], v[180:183], v[88:91]
	v_mfma_f32_16x16x32_bf16 v[80:83], v[204:207], v[180:183], v[80:83]
	v_mfma_f32_16x16x32_bf16 v[72:75], v[196:199], v[188:191], v[72:75]
	v_mfma_f32_16x16x32_bf16 v[64:67], v[204:207], v[188:191], v[64:67]
	s_setprio 0
	s_mov_b32 m0, s39
	s_barrier
	ds_read_b128 v[160:163], v142 offset:16384
	ds_read_b128 v[164:167], v142 offset:17408
	ds_read_b128 v[168:171], v142 offset:18432
	ds_read_b128 v[172:175], v142 offset:19456
	ds_read_b128 v[176:179], v142 offset:20480
	ds_read_b128 v[180:183], v142 offset:21504
	ds_read_b128 v[184:187], v142 offset:22528
	ds_read_b128 v[188:191], v142 offset:23552
	global_load_lds_dwordx4 v134, s[36:37]
	s_mov_b32 m0, s68
	s_nop 0
	global_load_lds_dwordx4 v130, s[36:37]
	s_barrier
	s_waitcnt lgkmcnt(0)
	s_setprio 1
	v_mfma_f32_16x16x32_bf16 v[60:63], v[144:147], v[160:163], v[60:63]
	v_mfma_f32_16x16x32_bf16 v[52:55], v[152:155], v[160:163], v[52:55]
	v_mfma_f32_16x16x32_bf16 v[44:47], v[144:147], v[168:171], v[44:47]
	v_mfma_f32_16x16x32_bf16 v[36:39], v[152:155], v[168:171], v[36:39]
	v_mfma_f32_16x16x32_bf16 v[28:31], v[144:147], v[176:179], v[28:31]
	v_mfma_f32_16x16x32_bf16 v[20:23], v[152:155], v[176:179], v[20:23]
	v_mfma_f32_16x16x32_bf16 v[12:15], v[144:147], v[184:187], v[12:15]
	v_mfma_f32_16x16x32_bf16 v[4:7], v[152:155], v[184:187], v[4:7]
	v_mfma_f32_16x16x32_bf16 v[60:63], v[148:151], v[164:167], v[60:63]
	v_mfma_f32_16x16x32_bf16 v[52:55], v[156:159], v[164:167], v[52:55]
	v_mfma_f32_16x16x32_bf16 v[44:47], v[148:151], v[172:175], v[44:47]
	v_mfma_f32_16x16x32_bf16 v[36:39], v[156:159], v[172:175], v[36:39]
	v_mfma_f32_16x16x32_bf16 v[28:31], v[148:151], v[180:183], v[28:31]
	v_mfma_f32_16x16x32_bf16 v[20:23], v[156:159], v[180:183], v[20:23]
	v_mfma_f32_16x16x32_bf16 v[12:15], v[148:151], v[188:191], v[12:15]
	v_mfma_f32_16x16x32_bf16 v[4:7], v[156:159], v[188:191], v[4:7]
	s_setprio 0
	s_barrier
	s_add_u32 s34, s28, 0x80000
	s_addc_u32 s35, s29, 0
	s_add_i32 s46, s46, s31
	s_mov_b32 m0, s46
	s_nop 0
	global_load_lds_dwordx4 v132, s[34:35]
	s_add_i32 m0, s46, 0x2000
	s_nop 0
	global_load_lds_dwordx4 v128, s[34:35]
	s_waitcnt vmcnt(6)
	s_barrier
; #define PG8_STAGE(bufoff, gbase, voff) do { _Pragma("unroll") for (int _i = 0; _i < 2; ++_i) \
;         __builtin_amdgcn_global_load_lds((const unsigned*)((const char*)(gbase) + (voff)[_i]), (LAS unsigned*)(lds + (bufoff) + ldsw + _i * 8192), 16, 0, 0); } while (0)
; #define PG8_LDA(dst, b, h) do { _Pragma("unroll") for (int m = 0; m < 4; ++m) _Pragma("unroll") for (int k = 0; k < 2; ++k) dst[m][k] = *(const LAS bf16x8*)(lds + PG8_SA(b, h) + aoff + m * 2048 + k * 1024); } while (0)
; #define PG8_LDB(dst, b, h) do { _Pragma("unroll") for (int n = 0; n < 2; ++n) _Pragma("unroll") for (int k = 0; k < 2; ++k) dst[n][k] = *(const LAS bf16x8*)(lds + PG8_SB(b, h) + boff + n * 2048 + k * 1024); } while (0)
; #define PG8_MMA(ai, bj, At, Bt) do { __builtin_amdgcn_s_setprio(1); _Pragma("unroll") for (int m = 0; m < 4; ++m) _Pragma("unroll") for (int n = 0; n < 2; ++n) _Pragma("unroll") for (int k = 0; k < 2; ++k) \
;         acc[ai][bj][m][n] = __builtin_amdgcn_mfma_f32_16x16x32_bf16(Bt[n][k], At[m][k], acc[ai][bj][m][n], 0, 0, 0); __builtin_amdgcn_s_setprio(0); } while (0)
; #define PG8_WAIT_V(n) asm volatile("s_waitcnt vmcnt(" #n ")" ::: "memory")
; #define PG8_WAIT_L(n) asm volatile("s_waitcnt lgkmcnt(" #n ")" ::: "memory")
; #define PG8_BAR __builtin_amdgcn_s_barrier()
; #define PG8_SCHED __builtin_amdgcn_sched_barrier(0)
; template <class Epi>
; __device__ __forceinline__ void gemm_phase(LAS unsigned char* lds, const Gemm g, const Epi& E) {
;     ...
;             PG8_WAIT_V(6); PG8_BAR; PG8_MMA(1, 1, At, B1); PG8_BAR;
;             PG8_LDB(B0, 1, 0); PG8_SCHED; PG8_LDA(At, 1, 0); PG8_STAGE(PG8_SA(0, 1), a2 + hstep, voffA);
;             PG8_WAIT_L(8); PG8_BAR; PG8_WAIT_L(0); PG8_MMA(0, 0, At, B0); PG8_BAR; PG8_SCHED;
;             PG8_LDB(B1, 1, 1); PG8_STAGE(PG8_SB(1, 0), b3, voffB);
;             PG8_BAR; PG8_WAIT_L(0); PG8_MMA(0, 1, At, B1); PG8_BAR;
;             PG8_LDA(At, 1, 1); PG8_STAGE(PG8_SA(1, 0), a3, voffA);
;             PG8_BAR; PG8_WAIT_L(0); PG8_MMA(1, 0, At, B0); PG8_BAR; PG8_SCHED;
	s_setprio 1
	v_mfma_f32_16x16x32_bf16 v[56:59], v[192:195], v[160:163], v[56:59]
	v_mfma_f32_16x16x32_bf16 v[48:51], v[200:203], v[160:163], v[48:51]
	v_mfma_f32_16x16x32_bf16 v[40:43], v[192:195], v[168:171], v[40:43]
	v_mfma_f32_16x16x32_bf16 v[32:35], v[200:203], v[168:171], v[32:35]
	v_mfma_f32_16x16x32_bf16 v[24:27], v[192:195], v[176:179], v[24:27]
	v_mfma_f32_16x16x32_bf16 v[16:19], v[200:203], v[176:179], v[16:19]
	v_mfma_f32_16x16x32_bf16 v[8:11], v[192:195], v[184:187], v[8:11]
	v_mfma_f32_16x16x32_bf16 v[0:3], v[200:203], v[184:187], v[0:3]
	v_mfma_f32_16x16x32_bf16 v[56:59], v[196:199], v[164:167], v[56:59]
	v_mfma_f32_16x16x32_bf16 v[48:51], v[204:207], v[164:167], v[48:51]
	v_mfma_f32_16x16x32_bf16 v[40:43], v[196:199], v[172:175], v[40:43]
	v_mfma_f32_16x16x32_bf16 v[32:35], v[204:207], v[172:175], v[32:35]
	v_mfma_f32_16x16x32_bf16 v[24:27], v[196:199], v[180:183], v[24:27]
	v_mfma_f32_16x16x32_bf16 v[16:19], v[204:207], v[180:183], v[16:19]
	v_mfma_f32_16x16x32_bf16 v[8:11], v[196:199], v[188:191], v[8:11]
	v_mfma_f32_16x16x32_bf16 v[0:3], v[204:207], v[188:191], v[0:3]
	s_setprio 0
	s_add_i32 s46, 0, 0x18000
	v_add_u32_e32 v143, s46, v141
	s_barrier
	ds_read_b128 v[144:147], v143
	ds_read_b128 v[148:151], v143 offset:1024
	ds_read_b128 v[152:155], v143 offset:2048
	ds_read_b128 v[156:159], v143 offset:3072
	s_add_u32 s34, s36, 0x80000
	s_addc_u32 s35, s37, 0
	s_mov_b32 m0, s69
	ds_read_b128 v[160:163], v142 offset:32768
	ds_read_b128 v[164:167], v142 offset:33792
	ds_read_b128 v[168:171], v142 offset:34816
	ds_read_b128 v[172:175], v142 offset:35840
	ds_read_b128 v[176:179], v142 offset:36864
	ds_read_b128 v[180:183], v142 offset:37888
	ds_read_b128 v[184:187], v142 offset:38912
	ds_read_b128 v[188:191], v142 offset:39936
	global_load_lds_dwordx4 v134, s[34:35]
	s_mov_b32 m0, s70
	s_nop 0
	global_load_lds_dwordx4 v130, s[34:35]
	s_waitcnt lgkmcnt(8)
	s_barrier
	s_waitcnt lgkmcnt(0)
	s_setprio 1
	v_mfma_f32_16x16x32_bf16 v[124:127], v[144:147], v[160:163], v[124:127]
	v_mfma_f32_16x16x32_bf16 v[116:119], v[152:155], v[160:163], v[116:119]
	v_mfma_f32_16x16x32_bf16 v[108:111], v[144:147], v[168:171], v[108:111]
	v_mfma_f32_16x16x32_bf16 v[100:103], v[152:155], v[168:171], v[100:103]
	v_mfma_f32_16x16x32_bf16 v[92:95], v[144:147], v[176:179], v[92:95]
	v_mfma_f32_16x16x32_bf16 v[84:87], v[152:155], v[176:179], v[84:87]
	v_mfma_f32_16x16x32_bf16 v[76:79], v[144:147], v[184:187], v[76:79]
	v_mfma_f32_16x16x32_bf16 v[68:71], v[152:155], v[184:187], v[68:71]
	v_mfma_f32_16x16x32_bf16 v[124:127], v[148:151], v[164:167], v[124:127]
	v_mfma_f32_16x16x32_bf16 v[116:119], v[156:159], v[164:167], v[116:119]
	v_mfma_f32_16x16x32_bf16 v[108:111], v[148:151], v[172:175], v[108:111]
	v_mfma_f32_16x16x32_bf16 v[100:103], v[156:159], v[172:175], v[100:103]
	v_mfma_f32_16x16x32_bf16 v[92:95], v[148:151], v[180:183], v[92:95]
	v_mfma_f32_16x16x32_bf16 v[84:87], v[156:159], v[180:183], v[84:87]
	v_mfma_f32_16x16x32_bf16 v[76:79], v[148:151], v[188:191], v[76:79]
	v_mfma_f32_16x16x32_bf16 v[68:71], v[156:159], v[188:191], v[68:71]
	s_setprio 0
	s_barrier
	s_add_i32 s34, 0, 0x1c000
	s_add_i32 s35, s46, s31
	v_add_u32_e32 v143, s34, v141
	s_mov_b32 m0, s35
	ds_read_b128 v[192:195], v143
	ds_read_b128 v[196:199], v143 offset:1024
	ds_read_b128 v[200:203], v143 offset:2048
	ds_read_b128 v[204:207], v143 offset:3072
	s_add_u32 s98, s28, 0x80
	s_addc_u32 s99, s29, 0
	global_load_lds_dwordx4 v132, s[98:99]
	s_add_i32 m0, s35, 0x2000
	s_add_u32 s100, s28, 0x80
	s_addc_u32 s101, s29, 0
	global_load_lds_dwordx4 v128, s[100:101]
	s_barrier
	s_waitcnt lgkmcnt(0)
	s_setprio 1
	v_mfma_f32_16x16x32_bf16 v[120:123], v[192:195], v[160:163], v[120:123]
	v_mfma_f32_16x16x32_bf16 v[112:115], v[200:203], v[160:163], v[112:115]
	v_mfma_f32_16x16x32_bf16 v[104:107], v[192:195], v[168:171], v[104:107]
	v_mfma_f32_16x16x32_bf16 v[96:99], v[200:203], v[168:171], v[96:99]
	v_mfma_f32_16x16x32_bf16 v[88:91], v[192:195], v[176:179], v[88:91]
	v_mfma_f32_16x16x32_bf16 v[80:83], v[200:203], v[176:179], v[80:83]
	v_mfma_f32_16x16x32_bf16 v[72:75], v[192:195], v[184:187], v[72:75]
	v_mfma_f32_16x16x32_bf16 v[64:67], v[200:203], v[184:187], v[64:67]
	v_mfma_f32_16x16x32_bf16 v[120:123], v[196:199], v[164:167], v[120:123]
	v_mfma_f32_16x16x32_bf16 v[112:115], v[204:207], v[164:167], v[112:115]
	v_mfma_f32_16x16x32_bf16 v[104:107], v[196:199], v[172:175], v[104:107]
	v_mfma_f32_16x16x32_bf16 v[96:99], v[204:207], v[172:175], v[96:99]
	v_mfma_f32_16x16x32_bf16 v[88:91], v[196:199], v[180:183], v[88:91]
	v_mfma_f32_16x16x32_bf16 v[80:83], v[204:207], v[180:183], v[80:83]
	v_mfma_f32_16x16x32_bf16 v[72:75], v[196:199], v[188:191], v[72:75]
	v_mfma_f32_16x16x32_bf16 v[64:67], v[204:207], v[188:191], v[64:67]
	s_setprio 0
	s_mov_b32 m0, s2
	s_barrier
	ds_read_b128 v[160:163], v142 offset:49152
	ds_read_b128 v[164:167], v142 offset:50176
	ds_read_b128 v[168:171], v142 offset:51200
	ds_read_b128 v[172:175], v142 offset:52224
	ds_read_b128 v[176:179], v142 offset:53248
	ds_read_b128 v[180:183], v142 offset:54272
	ds_read_b128 v[184:187], v142 offset:55296
	ds_read_b128 v[188:191], v142 offset:56320
	s_add_u32 s98, s36, 0x80
	s_addc_u32 s99, s37, 0
	global_load_lds_dwordx4 v134, s[98:99]
	s_mov_b32 m0, s71
	s_add_u32 s100, s36, 0x80
	s_addc_u32 s101, s37, 0
	global_load_lds_dwordx4 v130, s[100:101]
	s_barrier
; __device__ __forceinline__ u32x4 pack8u(f32x4 a, f32x4 b) { u32x4 w = {cvt_pk_bf16(a[0], a[1]), cvt_pk_bf16(a[2], a[3]), cvt_pk_bf16(b[0], b[1]), cvt_pk_bf16(b[2], b[3])}; return w; }
; __device__ __forceinline__ float siluf_(float x) { return x * __builtin_amdgcn_rcpf(1.0f + __expf(-x)); }
; #define PG8_STAGE(bufoff, gbase, voff) do { _Pragma("unroll") for (int _i = 0; _i < 2; ++_i) \
;         __builtin_amdgcn_global_load_lds((const unsigned*)((const char*)(gbase) + (voff)[_i]), (LAS unsigned*)(lds + (bufoff) + ldsw + _i * 8192), 16, 0, 0); } while (0)
; #define PG8_MMA(ai, bj, At, Bt) do { __builtin_amdgcn_s_setprio(1); _Pragma("unroll") for (int m = 0; m < 4; ++m) _Pragma("unroll") for (int n = 0; n < 2; ++n) _Pragma("unroll") for (int k = 0; k < 2; ++k) \
;         acc[ai][bj][m][n] = __builtin_amdgcn_mfma_f32_16x16x32_bf16(Bt[n][k], At[m][k], acc[ai][bj][m][n], 0, 0, 0); __builtin_amdgcn_s_setprio(0); } while (0)
; #define PG8_WAIT_V(n) asm volatile("s_waitcnt vmcnt(" #n ")" ::: "memory")
; #define PG8_WAIT_L(n) asm volatile("s_waitcnt lgkmcnt(" #n ")" ::: "memory")
; #define PG8_BAR __builtin_amdgcn_s_barrier()
; #define PG8_SCHED __builtin_amdgcn_sched_barrier(0)
; template <class Epi>
; __device__ __forceinline__ void gemm_phase(LAS unsigned char* lds, const Gemm g, const Epi& E) {
;     ...
;             PG8_BAR; PG8_WAIT_L(0); PG8_MMA(1, 0, At, B0); PG8_BAR; PG8_SCHED;
;             PG8_STAGE(PG8_SB(1, 1), b3 + hstep, voffB);
;             PG8_WAIT_V(6); PG8_BAR; PG8_MMA(1, 1, At, B1); PG8_BAR;
;     __device__ __forceinline__ void operator()(const AccT& acc, const Unit& u, int wr, int wc, int fr, int fq) const {
;     ...
;                 const int row = u.pm * 256 + ai * 128 + wr * 64 + m * 16 + fr;
;                 f32x4 o0, o1;
; #pragma unroll
;                 for (int j = 0; j < 4; ++j) { o0[j] = siluf_(acc[ai][0][m][0][j]) * acc[ai][1][m][0][j]; o1[j] = siluf_(acc[ai][0][m][1][j]) * acc[ai][1][m][1][j]; }
;                 *(u32x4*)(ACT + (size_t)row * DFF + u.pn * 128 + wc * 32 + fq * 8) = pack8u(o0, o1);
	s_waitcnt lgkmcnt(0)
	s_setprio 1
	v_mfma_f32_16x16x32_bf16 v[60:63], v[144:147], v[160:163], v[60:63]
	v_mfma_f32_16x16x32_bf16 v[52:55], v[152:155], v[160:163], v[52:55]
	v_mfma_f32_16x16x32_bf16 v[44:47], v[144:147], v[168:171], v[44:47]
	v_mfma_f32_16x16x32_bf16 v[36:39], v[152:155], v[168:171], v[36:39]
	v_mfma_f32_16x16x32_bf16 v[28:31], v[144:147], v[176:179], v[28:31]
	v_mfma_f32_16x16x32_bf16 v[20:23], v[152:155], v[176:179], v[20:23]
	v_mfma_f32_16x16x32_bf16 v[12:15], v[144:147], v[184:187], v[12:15]
	v_mfma_f32_16x16x32_bf16 v[4:7], v[152:155], v[184:187], v[4:7]
	v_mfma_f32_16x16x32_bf16 v[60:63], v[148:151], v[164:167], v[60:63]
	v_mfma_f32_16x16x32_bf16 v[52:55], v[156:159], v[164:167], v[52:55]
	v_mfma_f32_16x16x32_bf16 v[44:47], v[148:151], v[172:175], v[44:47]
	v_mfma_f32_16x16x32_bf16 v[36:39], v[156:159], v[172:175], v[36:39]
	v_mfma_f32_16x16x32_bf16 v[28:31], v[148:151], v[180:183], v[28:31]
	v_mfma_f32_16x16x32_bf16 v[20:23], v[156:159], v[180:183], v[20:23]
	v_mfma_f32_16x16x32_bf16 v[12:15], v[148:151], v[188:191], v[12:15]
	v_mfma_f32_16x16x32_bf16 v[4:7], v[156:159], v[188:191], v[4:7]
	s_setprio 0
	s_barrier
	s_add_u32 s28, s28, 0x80080
	s_addc_u32 s29, s29, 0
	s_add_i32 s34, s34, s31
	s_mov_b32 m0, s34
	s_nop 0
	global_load_lds_dwordx4 v132, s[28:29]
	s_add_i32 m0, s34, 0x2000
	s_nop 0
	global_load_lds_dwordx4 v128, s[28:29]
	s_waitcnt vmcnt(6)
	s_barrier
	s_setprio 1
	v_mfma_f32_16x16x32_bf16 v[56:59], v[192:195], v[160:163], v[56:59]
	v_mfma_f32_16x16x32_bf16 v[48:51], v[200:203], v[160:163], v[48:51]
	v_mfma_f32_16x16x32_bf16 v[40:43], v[192:195], v[168:171], v[40:43]
	v_mfma_f32_16x16x32_bf16 v[32:35], v[200:203], v[168:171], v[32:35]
	v_mfma_f32_16x16x32_bf16 v[24:27], v[192:195], v[176:179], v[24:27]
	v_mfma_f32_16x16x32_bf16 v[16:19], v[200:203], v[176:179], v[16:19]
	v_mfma_f32_16x16x32_bf16 v[8:11], v[192:195], v[184:187], v[8:11]
	v_mfma_f32_16x16x32_bf16 v[0:3], v[200:203], v[184:187], v[0:3]
	v_mfma_f32_16x16x32_bf16 v[56:59], v[196:199], v[164:167], v[56:59]
	v_mfma_f32_16x16x32_bf16 v[48:51], v[204:207], v[164:167], v[48:51]
	v_mfma_f32_16x16x32_bf16 v[40:43], v[196:199], v[172:175], v[40:43]
	v_mfma_f32_16x16x32_bf16 v[32:35], v[204:207], v[172:175], v[32:35]
	v_mfma_f32_16x16x32_bf16 v[24:27], v[196:199], v[180:183], v[24:27]
	v_mfma_f32_16x16x32_bf16 v[16:19], v[204:207], v[180:183], v[16:19]
	v_mfma_f32_16x16x32_bf16 v[8:11], v[196:199], v[188:191], v[8:11]
	v_mfma_f32_16x16x32_bf16 v[0:3], v[204:207], v[188:191], v[0:3]
	s_setprio 0
	s_add_i32 s89, s89, 2
	s_add_u32 s26, s26, 0x100
	s_addc_u32 s27, s27, 0
	s_add_u32 s82, s82, 0x100
	s_addc_u32 s83, s83, 0
	s_cmp_gt_u32 s89, 29
	s_barrier
	s_cbranch_scc0 .LBB0_30
	v_mul_f32_e32 v145, 0xbfb8aa3b, v116
	v_exp_f32_e32 v145, v145
	v_mul_f32_e32 v144, 0xbfb8aa3b, v124
	v_exp_f32_e32 v144, v144
	v_readlane_b32 s28, v252, 37
	v_add_f32_e32 v145, 1.0, v145
	v_rcp_f32_e32 v146, v145
	v_mul_f32_e32 v145, 0xbfb8aa3b, v125
	v_exp_f32_e32 v145, v145
	v_add_f32_e32 v144, 1.0, v144
	v_rcp_f32_e32 v144, v144
	s_lshl_b32 s26, s76, 7
	v_add_f32_e32 v145, 1.0, v145
	v_rcp_f32_e32 v145, v145
	v_readlane_b32 s29, v252, 38
	v_lshl_add_u32 v143, s88, 8, v140
	s_ashr_i32 s27, s26, 31
	v_pk_mul_f32 v[124:125], v[124:125], v[144:145]
	s_movk_i32 s34, 0x2c00
	v_pk_mul_f32 v[120:121], v[124:125], v[120:121]
	v_mul_f32_e32 v124, 0xbfb8aa3b, v117
	v_exp_f32_e32 v124, v124
	s_lshl_b64 s[88:89], s[26:27], 1
	s_and_b64 vcc, exec, s[40:41]
	s_mov_b32 s76, s42
	v_add_f32_e32 v124, 1.0, v124
	v_rcp_f32_e32 v147, v124
	s_nop 0
	v_pk_mul_f32 v[116:117], v[116:117], v[146:147]
	s_nop 0
	v_pk_mul_f32 v[112:113], v[116:117], v[112:113]
	v_mul_f32_e32 v117, 0xbfb8aa3b, v118
	v_exp_f32_e32 v117, v117
	v_mul_f32_e32 v116, 0xbfb8aa3b, v126
	v_exp_f32_e32 v116, v116
	v_add_f32_e32 v117, 1.0, v117
	v_rcp_f32_e32 v124, v117
	v_mul_f32_e32 v117, 0xbfb8aa3b, v127
	v_exp_f32_e32 v117, v117
	v_add_f32_e32 v116, 1.0, v116
	v_rcp_f32_e32 v116, v116
	v_add_f32_e32 v117, 1.0, v117
	v_rcp_f32_e32 v117, v117
	s_nop 0
	v_pk_mul_f32 v[116:117], v[126:127], v[116:117]
	s_nop 0
	v_pk_mul_f32 v[116:117], v[116:117], v[122:123]
	v_mul_f32_e32 v122, 0xbfb8aa3b, v119
	v_exp_f32_e32 v122, v122
	s_nop 0
	v_add_f32_e32 v122, 1.0, v122
	v_rcp_f32_e32 v125, v122
	s_nop 0
	v_pk_mul_f32 v[118:119], v[118:119], v[124:125]
	s_nop 0
	v_pk_mul_f32 v[118:119], v[118:119], v[114:115]
	v_cvt_pk_bf16_f32 v115, v116, v117
	v_cvt_pk_bf16_f32 v116, v112, v113
	v_mov_b64_e32 v[112:113], s[28:29]
	v_cvt_pk_bf16_f32 v117, v118, v119
	v_mad_i64_i32 v[118:119], s[28:29], v143, s34, v[112:113]
	v_lshl_add_u64 v[118:119], v[118:119], 0, s[88:89]
	s_mov_b64 s[28:29], s[90:91]
	v_lshl_add_u64 v[118:119], v[118:119], 0, s[28:29]
	v_cvt_pk_bf16_f32 v114, v120, v121
	v_lshl_add_u64 v[118:119], v[118:119], 0, v[208:209]
	global_store_dwordx4 v[118:119], v[114:117], off
	s_nop 1
	v_mul_f32_e32 v115, 0xbfb8aa3b, v100
	v_exp_f32_e32 v115, v115
	v_mul_f32_e32 v114, 0xbfb8aa3b, v108
	v_exp_f32_e32 v114, v114
	v_add_f32_e32 v115, 1.0, v115
	v_rcp_f32_e32 v116, v115
	v_mul_f32_e32 v115, 0xbfb8aa3b, v109
	v_exp_f32_e32 v115, v115
	v_add_f32_e32 v114, 1.0, v114
	v_rcp_f32_e32 v114, v114
	v_add_f32_e32 v115, 1.0, v115
	v_rcp_f32_e32 v115, v115
	s_nop 0
	v_pk_mul_f32 v[108:109], v[108:109], v[114:115]
	s_nop 0
	v_pk_mul_f32 v[104:105], v[108:109], v[104:105]
	v_mul_f32_e32 v108, 0xbfb8aa3b, v101
	v_exp_f32_e32 v108, v108
	s_nop 0
	v_add_f32_e32 v108, 1.0, v108
	v_rcp_f32_e32 v117, v108
	s_nop 0
	v_pk_mul_f32 v[100:101], v[100:101], v[116:117]
	s_nop 0
	v_pk_mul_f32 v[100:101], v[100:101], v[96:97]
	v_mul_f32_e32 v97, 0xbfb8aa3b, v102
; __device__ __forceinline__ u32x4 pack8u(f32x4 a, f32x4 b) { u32x4 w = {cvt_pk_bf16(a[0], a[1]), cvt_pk_bf16(a[2], a[3]), cvt_pk_bf16(b[0], b[1]), cvt_pk_bf16(b[2], b[3])}; return w; }
; __device__ __forceinline__ float siluf_(float x) { return x * __builtin_amdgcn_rcpf(1.0f + __expf(-x)); }
;     __device__ __forceinline__ void operator()(const AccT& acc, const Unit& u, int wr, int wc, int fr, int fq) const {
;     ...
;                 const int row = u.pm * 256 + ai * 128 + wr * 64 + m * 16 + fr;
;                 f32x4 o0, o1;
; #pragma unroll
;                 for (int j = 0; j < 4; ++j) { o0[j] = siluf_(acc[ai][0][m][0][j]) * acc[ai][1][m][0][j]; o1[j] = siluf_(acc[ai][0][m][1][j]) * acc[ai][1][m][1][j]; }
;                 *(u32x4*)(ACT + (size_t)row * DFF + u.pn * 128 + wc * 32 + fq * 8) = pack8u(o0, o1);
	v_exp_f32_e32 v97, v97
	v_mul_f32_e32 v96, 0xbfb8aa3b, v110
	v_exp_f32_e32 v96, v96
	v_add_f32_e32 v97, 1.0, v97
	v_rcp_f32_e32 v108, v97
	v_mul_f32_e32 v97, 0xbfb8aa3b, v111
	v_exp_f32_e32 v97, v97
	v_add_f32_e32 v96, 1.0, v96
	v_rcp_f32_e32 v96, v96
	v_add_f32_e32 v97, 1.0, v97
	v_rcp_f32_e32 v97, v97
	s_nop 0
	v_pk_mul_f32 v[96:97], v[110:111], v[96:97]
	s_nop 0
	v_pk_mul_f32 v[106:107], v[96:97], v[106:107]
	v_mul_f32_e32 v96, 0xbfb8aa3b, v103
	v_exp_f32_e32 v96, v96
	s_nop 0
	v_add_f32_e32 v96, 1.0, v96
	v_rcp_f32_e32 v109, v96
	s_nop 0
	v_pk_mul_f32 v[96:97], v[102:103], v[108:109]
	v_or_b32_e32 v108, 16, v143
	v_pk_mul_f32 v[102:103], v[96:97], v[98:99]
	v_cvt_pk_bf16_f32 v98, v100, v101
	v_mad_i64_i32 v[100:101], s[26:27], v108, s34, v[112:113]
	v_lshl_add_u64 v[100:101], v[100:101], 0, s[88:89]
	v_lshl_add_u64 v[100:101], v[100:101], 0, s[28:29]
	v_cvt_pk_bf16_f32 v96, v104, v105
	v_cvt_pk_bf16_f32 v97, v106, v107
	v_cvt_pk_bf16_f32 v99, v102, v103
	v_lshl_add_u64 v[100:101], v[100:101], 0, v[208:209]
	global_store_dwordx4 v[100:101], v[96:99], off
	s_nop 1
	v_mul_f32_e32 v97, 0xbfb8aa3b, v84
	v_exp_f32_e32 v97, v97
	v_mul_f32_e32 v96, 0xbfb8aa3b, v92
	v_exp_f32_e32 v96, v96
	v_add_f32_e32 v97, 1.0, v97
	v_rcp_f32_e32 v98, v97
	v_mul_f32_e32 v97, 0xbfb8aa3b, v93
	v_exp_f32_e32 v97, v97
	v_add_f32_e32 v96, 1.0, v96
	v_rcp_f32_e32 v96, v96
	v_add_f32_e32 v97, 1.0, v97
	v_rcp_f32_e32 v97, v97
	s_nop 0
	v_pk_mul_f32 v[92:93], v[92:93], v[96:97]
	s_nop 0
	v_pk_mul_f32 v[88:89], v[92:93], v[88:89]
	v_mul_f32_e32 v92, 0xbfb8aa3b, v85
	v_exp_f32_e32 v92, v92
	s_nop 0
	v_add_f32_e32 v92, 1.0, v92
	v_rcp_f32_e32 v99, v92
	s_nop 0
	v_pk_mul_f32 v[84:85], v[84:85], v[98:99]
	s_nop 0
	v_pk_mul_f32 v[84:85], v[84:85], v[80:81]
	v_mul_f32_e32 v81, 0xbfb8aa3b, v86
	v_exp_f32_e32 v81, v81
	v_mul_f32_e32 v80, 0xbfb8aa3b, v94
	v_exp_f32_e32 v80, v80
	v_add_f32_e32 v81, 1.0, v81
	v_rcp_f32_e32 v92, v81
	v_mul_f32_e32 v81, 0xbfb8aa3b, v95
	v_exp_f32_e32 v81, v81
	v_add_f32_e32 v80, 1.0, v80
	v_rcp_f32_e32 v80, v80
	v_add_f32_e32 v81, 1.0, v81
	v_rcp_f32_e32 v81, v81
	s_nop 0
	v_pk_mul_f32 v[80:81], v[94:95], v[80:81]
	s_nop 0
	v_pk_mul_f32 v[90:91], v[80:81], v[90:91]
	v_mul_f32_e32 v80, 0xbfb8aa3b, v87
	v_exp_f32_e32 v80, v80
	s_nop 0
	v_add_f32_e32 v80, 1.0, v80
	v_rcp_f32_e32 v93, v80
	s_nop 0
	v_pk_mul_f32 v[80:81], v[86:87], v[92:93]
	v_or_b32_e32 v92, 32, v143
	v_pk_mul_f32 v[86:87], v[80:81], v[82:83]
	v_cvt_pk_bf16_f32 v82, v84, v85
	v_mad_i64_i32 v[84:85], s[26:27], v92, s34, v[112:113]
	v_lshl_add_u64 v[84:85], v[84:85], 0, s[88:89]
	v_lshl_add_u64 v[84:85], v[84:85], 0, s[28:29]
	v_cvt_pk_bf16_f32 v80, v88, v89
	v_cvt_pk_bf16_f32 v81, v90, v91
	v_cvt_pk_bf16_f32 v83, v86, v87
	v_lshl_add_u64 v[84:85], v[84:85], 0, v[208:209]
	global_store_dwordx4 v[84:85], v[80:83], off
	s_nop 1
	v_mul_f32_e32 v81, 0xbfb8aa3b, v68
	v_exp_f32_e32 v81, v81
	v_mul_f32_e32 v80, 0xbfb8aa3b, v76
	v_exp_f32_e32 v80, v80
	v_add_f32_e32 v81, 1.0, v81
	v_rcp_f32_e32 v82, v81
	v_mul_f32_e32 v81, 0xbfb8aa3b, v77
	v_exp_f32_e32 v81, v81
	v_add_f32_e32 v80, 1.0, v80
	v_rcp_f32_e32 v80, v80
	v_add_f32_e32 v81, 1.0, v81
	v_rcp_f32_e32 v81, v81
	s_nop 0
	v_pk_mul_f32 v[76:77], v[76:77], v[80:81]
	s_nop 0
	v_pk_mul_f32 v[72:73], v[76:77], v[72:73]
	v_mul_f32_e32 v76, 0xbfb8aa3b, v69
	v_exp_f32_e32 v76, v76
	s_nop 0
	v_add_f32_e32 v76, 1.0, v76
	v_rcp_f32_e32 v83, v76
	s_nop 0
	v_pk_mul_f32 v[68:69], v[68:69], v[82:83]
	s_nop 0
	v_pk_mul_f32 v[68:69], v[68:69], v[64:65]
	v_mul_f32_e32 v65, 0xbfb8aa3b, v70
	v_exp_f32_e32 v65, v65
	v_mul_f32_e32 v64, 0xbfb8aa3b, v78
	v_exp_f32_e32 v64, v64
	v_add_f32_e32 v65, 1.0, v65
	v_rcp_f32_e32 v76, v65
	v_mul_f32_e32 v65, 0xbfb8aa3b, v79
	v_exp_f32_e32 v65, v65
	v_add_f32_e32 v64, 1.0, v64
	v_rcp_f32_e32 v64, v64
	v_add_f32_e32 v65, 1.0, v65
	v_rcp_f32_e32 v65, v65
	s_nop 0
	v_pk_mul_f32 v[64:65], v[78:79], v[64:65]
	s_nop 0
	v_pk_mul_f32 v[74:75], v[64:65], v[74:75]
	v_mul_f32_e32 v64, 0xbfb8aa3b, v71
	v_exp_f32_e32 v64, v64
	s_nop 0
	v_add_f32_e32 v64, 1.0, v64
	v_rcp_f32_e32 v77, v64
	s_nop 0
	v_pk_mul_f32 v[64:65], v[70:71], v[76:77]
	v_or_b32_e32 v76, 48, v143
	v_pk_mul_f32 v[70:71], v[64:65], v[66:67]
	v_cvt_pk_bf16_f32 v66, v68, v69
	v_mad_i64_i32 v[68:69], s[26:27], v76, s34, v[112:113]
	v_lshl_add_u64 v[68:69], v[68:69], 0, s[88:89]
	v_lshl_add_u64 v[68:69], v[68:69], 0, s[28:29]
	v_cvt_pk_bf16_f32 v64, v72, v73
	v_cvt_pk_bf16_f32 v65, v74, v75
	v_cvt_pk_bf16_f32 v67, v70, v71
	v_lshl_add_u64 v[68:69], v[68:69], 0, v[208:209]
	global_store_dwordx4 v[68:69], v[64:67], off
	v_add_u32_e32 v68, 0x80, v143
	s_nop 0
	v_mul_f32_e32 v65, 0xbfb8aa3b, v52
	v_exp_f32_e32 v65, v65
	v_mul_f32_e32 v64, 0xbfb8aa3b, v60
	v_exp_f32_e32 v64, v64
	v_add_f32_e32 v65, 1.0, v65
	v_rcp_f32_e32 v66, v65
	v_mul_f32_e32 v65, 0xbfb8aa3b, v61
	v_exp_f32_e32 v65, v65
	v_add_f32_e32 v64, 1.0, v64
	v_rcp_f32_e32 v64, v64
	v_add_f32_e32 v65, 1.0, v65
	v_rcp_f32_e32 v65, v65
	s_nop 0
	v_pk_mul_f32 v[60:61], v[60:61], v[64:65]
	s_nop 0
	v_pk_mul_f32 v[56:57], v[60:61], v[56:57]
	v_mul_f32_e32 v60, 0xbfb8aa3b, v53
	v_exp_f32_e32 v60, v60
	s_nop 0
	v_add_f32_e32 v60, 1.0, v60
	v_rcp_f32_e32 v67, v60
	s_nop 0
	v_pk_mul_f32 v[52:53], v[52:53], v[66:67]
	s_nop 0
	v_pk_mul_f32 v[52:53], v[52:53], v[48:49]
	v_mul_f32_e32 v49, 0xbfb8aa3b, v54
	v_exp_f32_e32 v49, v49
	v_mul_f32_e32 v48, 0xbfb8aa3b, v62
	v_exp_f32_e32 v48, v48
	v_add_f32_e32 v49, 1.0, v49
	v_rcp_f32_e32 v60, v49
	v_mul_f32_e32 v49, 0xbfb8aa3b, v63
	v_exp_f32_e32 v49, v49
	v_add_f32_e32 v48, 1.0, v48
	v_rcp_f32_e32 v48, v48
	v_add_f32_e32 v49, 1.0, v49
	v_rcp_f32_e32 v49, v49
	s_nop 0
; __device__ __forceinline__ u32x4 pack8u(f32x4 a, f32x4 b) { u32x4 w = {cvt_pk_bf16(a[0], a[1]), cvt_pk_bf16(a[2], a[3]), cvt_pk_bf16(b[0], b[1]), cvt_pk_bf16(b[2], b[3])}; return w; }
; __device__ __forceinline__ float siluf_(float x) { return x * __builtin_amdgcn_rcpf(1.0f + __expf(-x)); }
; #define PG8_WAIT_V(n) asm volatile("s_waitcnt vmcnt(" #n ")" ::: "memory")
; #define PG8_BAR __builtin_amdgcn_s_barrier()
; template <class Epi>
; __device__ __forceinline__ void gemm_phase(LAS unsigned char* lds, const Gemm g, const Epi& E) {
;     ...
;         E(acc, cur, wr, wc, fr, fq);
;         if (!has_next) break;
; #pragma unroll
;         for (int a = 0; a < 2; ++a)
; #pragma unroll
;             for (int b = 0; b < 2; ++b)
; #pragma unroll
;                 for (int m = 0; m < 4; ++m)
; #pragma unroll
;                     for (int n = 0; n < 2; ++n) acc[a][b][m][n] = (f32x4){0.f, 0.f, 0.f, 0.f};
;         cur = nxt; cA = nA; cB = nB; ++ui;
;     }
;     PG8_WAIT_V(0);
;     if (wr == 0) PG8_BAR;
;     PG8_BAR;
;     __device__ __forceinline__ void operator()(const AccT& acc, const Unit& u, int wr, int wc, int fr, int fq) const {
;     ...
;                 const int row = u.pm * 256 + ai * 128 + wr * 64 + m * 16 + fr;
;                 f32x4 o0, o1;
; #pragma unroll
;                 for (int j = 0; j < 4; ++j) { o0[j] = siluf_(acc[ai][0][m][0][j]) * acc[ai][1][m][0][j]; o1[j] = siluf_(acc[ai][0][m][1][j]) * acc[ai][1][m][1][j]; }
;                 *(u32x4*)(ACT + (size_t)row * DFF + u.pn * 128 + wc * 32 + fq * 8) = pack8u(o0, o1);
	v_pk_mul_f32 v[48:49], v[62:63], v[48:49]
	s_nop 0
	v_pk_mul_f32 v[58:59], v[48:49], v[58:59]
	v_mul_f32_e32 v48, 0xbfb8aa3b, v55
	v_exp_f32_e32 v48, v48
	s_nop 0
	v_add_f32_e32 v48, 1.0, v48
	v_rcp_f32_e32 v61, v48
	s_nop 0
	v_pk_mul_f32 v[48:49], v[54:55], v[60:61]
	s_nop 0
	v_pk_mul_f32 v[54:55], v[48:49], v[50:51]
	v_cvt_pk_bf16_f32 v50, v52, v53
	v_mad_i64_i32 v[52:53], s[26:27], v68, s34, v[112:113]
	v_lshl_add_u64 v[52:53], v[52:53], 0, s[88:89]
	v_lshl_add_u64 v[52:53], v[52:53], 0, s[28:29]
	v_cvt_pk_bf16_f32 v48, v56, v57
	v_cvt_pk_bf16_f32 v49, v58, v59
	v_cvt_pk_bf16_f32 v51, v54, v55
	v_lshl_add_u64 v[52:53], v[52:53], 0, v[208:209]
	global_store_dwordx4 v[52:53], v[48:51], off
	s_nop 1
	v_mul_f32_e32 v49, 0xbfb8aa3b, v36
	v_exp_f32_e32 v49, v49
	v_mul_f32_e32 v48, 0xbfb8aa3b, v44
	v_exp_f32_e32 v48, v48
	v_add_f32_e32 v49, 1.0, v49
	v_rcp_f32_e32 v50, v49
	v_mul_f32_e32 v49, 0xbfb8aa3b, v45
	v_exp_f32_e32 v49, v49
	v_add_f32_e32 v48, 1.0, v48
	v_rcp_f32_e32 v48, v48
	v_add_f32_e32 v49, 1.0, v49
	v_rcp_f32_e32 v49, v49
	s_nop 0
	v_pk_mul_f32 v[44:45], v[44:45], v[48:49]
	s_nop 0
	v_pk_mul_f32 v[40:41], v[44:45], v[40:41]
	v_mul_f32_e32 v44, 0xbfb8aa3b, v37
	v_exp_f32_e32 v44, v44
	s_nop 0
	v_add_f32_e32 v44, 1.0, v44
	v_rcp_f32_e32 v51, v44
	s_nop 0
	v_pk_mul_f32 v[36:37], v[36:37], v[50:51]
	s_nop 0
	v_pk_mul_f32 v[36:37], v[36:37], v[32:33]
	v_mul_f32_e32 v33, 0xbfb8aa3b, v38
	v_exp_f32_e32 v33, v33
	v_mul_f32_e32 v32, 0xbfb8aa3b, v46
	v_exp_f32_e32 v32, v32
	v_add_f32_e32 v33, 1.0, v33
	v_rcp_f32_e32 v44, v33
	v_mul_f32_e32 v33, 0xbfb8aa3b, v47
	v_exp_f32_e32 v33, v33
	v_add_f32_e32 v32, 1.0, v32
	v_rcp_f32_e32 v32, v32
	v_add_f32_e32 v33, 1.0, v33
	v_rcp_f32_e32 v33, v33
	s_nop 0
	v_pk_mul_f32 v[32:33], v[46:47], v[32:33]
	s_nop 0
	v_pk_mul_f32 v[42:43], v[32:33], v[42:43]
	v_mul_f32_e32 v32, 0xbfb8aa3b, v39
	v_exp_f32_e32 v32, v32
	s_nop 0
	v_add_f32_e32 v32, 1.0, v32
	v_rcp_f32_e32 v45, v32
	s_nop 0
	v_pk_mul_f32 v[32:33], v[38:39], v[44:45]
	v_add_u32_e32 v44, 0x90, v143
	v_pk_mul_f32 v[38:39], v[32:33], v[34:35]
	v_cvt_pk_bf16_f32 v34, v36, v37
	v_mad_i64_i32 v[36:37], s[26:27], v44, s34, v[112:113]
	v_lshl_add_u64 v[36:37], v[36:37], 0, s[88:89]
	v_lshl_add_u64 v[36:37], v[36:37], 0, s[28:29]
	v_cvt_pk_bf16_f32 v32, v40, v41
	v_cvt_pk_bf16_f32 v33, v42, v43
	v_cvt_pk_bf16_f32 v35, v38, v39
	v_lshl_add_u64 v[36:37], v[36:37], 0, v[208:209]
	global_store_dwordx4 v[36:37], v[32:35], off
	s_nop 1
	v_mul_f32_e32 v33, 0xbfb8aa3b, v20
	v_exp_f32_e32 v33, v33
	v_mul_f32_e32 v32, 0xbfb8aa3b, v28
	v_exp_f32_e32 v32, v32
	v_add_f32_e32 v33, 1.0, v33
	v_rcp_f32_e32 v34, v33
	v_mul_f32_e32 v33, 0xbfb8aa3b, v29
	v_exp_f32_e32 v33, v33
	v_add_f32_e32 v32, 1.0, v32
	v_rcp_f32_e32 v32, v32
	v_add_f32_e32 v33, 1.0, v33
	v_rcp_f32_e32 v33, v33
	s_nop 0
	v_pk_mul_f32 v[28:29], v[28:29], v[32:33]
	s_nop 0
	v_pk_mul_f32 v[24:25], v[28:29], v[24:25]
	v_mul_f32_e32 v28, 0xbfb8aa3b, v21
	v_exp_f32_e32 v28, v28
	s_nop 0
	v_add_f32_e32 v28, 1.0, v28
	v_rcp_f32_e32 v35, v28
	s_nop 0
	v_pk_mul_f32 v[20:21], v[20:21], v[34:35]
	s_nop 0
	v_pk_mul_f32 v[20:21], v[20:21], v[16:17]
	v_mul_f32_e32 v17, 0xbfb8aa3b, v22
	v_exp_f32_e32 v17, v17
	v_mul_f32_e32 v16, 0xbfb8aa3b, v30
	v_exp_f32_e32 v16, v16
	v_add_f32_e32 v17, 1.0, v17
	v_rcp_f32_e32 v28, v17
	v_mul_f32_e32 v17, 0xbfb8aa3b, v31
	v_exp_f32_e32 v17, v17
	v_add_f32_e32 v16, 1.0, v16
	v_rcp_f32_e32 v16, v16
	v_add_f32_e32 v17, 1.0, v17
	v_rcp_f32_e32 v17, v17
	s_nop 0
	v_pk_mul_f32 v[16:17], v[30:31], v[16:17]
	s_nop 0
	v_pk_mul_f32 v[26:27], v[16:17], v[26:27]
	v_mul_f32_e32 v16, 0xbfb8aa3b, v23
	v_exp_f32_e32 v16, v16
	s_nop 0
	v_add_f32_e32 v16, 1.0, v16
	v_rcp_f32_e32 v29, v16
	s_nop 0
	v_pk_mul_f32 v[16:17], v[22:23], v[28:29]
	v_add_u32_e32 v28, 0xa0, v143
	v_pk_mul_f32 v[22:23], v[16:17], v[18:19]
	v_cvt_pk_bf16_f32 v18, v20, v21
	v_mad_i64_i32 v[20:21], s[26:27], v28, s34, v[112:113]
	v_lshl_add_u64 v[20:21], v[20:21], 0, s[88:89]
	v_lshl_add_u64 v[20:21], v[20:21], 0, s[28:29]
	v_cvt_pk_bf16_f32 v16, v24, v25
	v_cvt_pk_bf16_f32 v17, v26, v27
	v_cvt_pk_bf16_f32 v19, v22, v23
	v_lshl_add_u64 v[20:21], v[20:21], 0, v[208:209]
	global_store_dwordx4 v[20:21], v[16:19], off
	s_nop 1
	v_mul_f32_e32 v17, 0xbfb8aa3b, v4
	v_exp_f32_e32 v17, v17
	v_mul_f32_e32 v16, 0xbfb8aa3b, v12
	v_exp_f32_e32 v16, v16
	v_add_f32_e32 v17, 1.0, v17
	v_rcp_f32_e32 v18, v17
	v_mul_f32_e32 v17, 0xbfb8aa3b, v13
	v_exp_f32_e32 v17, v17
	v_add_f32_e32 v16, 1.0, v16
	v_rcp_f32_e32 v16, v16
	v_add_f32_e32 v17, 1.0, v17
	v_rcp_f32_e32 v17, v17
	s_nop 0
	v_pk_mul_f32 v[12:13], v[12:13], v[16:17]
	s_nop 0
	v_pk_mul_f32 v[8:9], v[12:13], v[8:9]
	v_mul_f32_e32 v12, 0xbfb8aa3b, v5
	v_exp_f32_e32 v12, v12
	s_nop 0
	v_add_f32_e32 v12, 1.0, v12
	v_rcp_f32_e32 v19, v12
	s_nop 0
	v_pk_mul_f32 v[4:5], v[4:5], v[18:19]
	s_nop 0
	v_pk_mul_f32 v[4:5], v[4:5], v[0:1]
	v_mul_f32_e32 v1, 0xbfb8aa3b, v6
	v_exp_f32_e32 v1, v1
	v_mul_f32_e32 v0, 0xbfb8aa3b, v14
	v_exp_f32_e32 v0, v0
	v_add_f32_e32 v1, 1.0, v1
	v_rcp_f32_e32 v12, v1
	v_mul_f32_e32 v1, 0xbfb8aa3b, v15
	v_exp_f32_e32 v1, v1
	v_add_f32_e32 v0, 1.0, v0
	v_rcp_f32_e32 v0, v0
	v_add_f32_e32 v1, 1.0, v1
	v_rcp_f32_e32 v1, v1
	s_nop 0
	v_pk_mul_f32 v[0:1], v[14:15], v[0:1]
	s_nop 0
	v_pk_mul_f32 v[10:11], v[0:1], v[10:11]
	v_mul_f32_e32 v0, 0xbfb8aa3b, v7
	v_exp_f32_e32 v0, v0
	s_nop 0
	v_add_f32_e32 v0, 1.0, v0
	v_rcp_f32_e32 v13, v0
	s_nop 0
	v_pk_mul_f32 v[0:1], v[6:7], v[12:13]
	v_add_u32_e32 v12, 0xb0, v143
	v_pk_mul_f32 v[6:7], v[0:1], v[2:3]
	v_cvt_pk_bf16_f32 v2, v4, v5
	v_mad_i64_i32 v[4:5], s[26:27], v12, s34, v[112:113]
	v_lshl_add_u64 v[4:5], v[4:5], 0, s[88:89]
	v_lshl_add_u64 v[4:5], v[4:5], 0, s[28:29]
	v_cvt_pk_bf16_f32 v0, v8, v9
	v_cvt_pk_bf16_f32 v1, v10, v11
	v_cvt_pk_bf16_f32 v3, v6, v7
	v_lshl_add_u64 v[4:5], v[4:5], 0, v[208:209]
	s_mov_b32 s88, s44
	s_mov_b64 s[28:29], s[64:65]
	s_mov_b64 s[26:27], s[48:49]
	global_store_dwordx4 v[4:5], v[0:3], off
	s_cbranch_vccz .LBB0_27
	s_waitcnt vmcnt(0)
	s_cmpk_gt_u32 s30, 0xff
	s_mov_b32 s89, 0xc000
	s_mov_b64 s[34:35], 0
	s_cbranch_scc1 .LBB0_34
	s_barrier

; #define PG8_STAGE(bufoff, gbase, voff) do { _Pragma("unroll") for (int _i = 0; _i < 2; ++_i) \
;         __builtin_amdgcn_global_load_lds((const unsigned*)((const char*)(gbase) + (voff)[_i]), (LAS unsigned*)(lds + (bufoff) + ldsw + _i * 8192), 16, 0, 0); } while (0)
; #define PG8_LDA(dst, b, h) do { _Pragma("unroll") for (int m = 0; m < 4; ++m) _Pragma("unroll") for (int k = 0; k < 2; ++k) dst[m][k] = *(const LAS bf16x8*)(lds + PG8_SA(b, h) + aoff + m * 2048 + k * 1024); } while (0)
; #define PG8_LDB(dst, b, h) do { _Pragma("unroll") for (int n = 0; n < 2; ++n) _Pragma("unroll") for (int k = 0; k < 2; ++k) dst[n][k] = *(const LAS bf16x8*)(lds + PG8_SB(b, h) + boff + n * 2048 + k * 1024); } while (0)
; #define PG8_MMA(ai, bj, At, Bt) do { __builtin_amdgcn_s_setprio(1); _Pragma("unroll") for (int m = 0; m < 4; ++m) _Pragma("unroll") for (int n = 0; n < 2; ++n) _Pragma("unroll") for (int k = 0; k < 2; ++k) \
;         acc[ai][bj][m][n] = __builtin_amdgcn_mfma_f32_16x16x32_bf16(Bt[n][k], At[m][k], acc[ai][bj][m][n], 0, 0, 0); __builtin_amdgcn_s_setprio(0); } while (0)
; #define PG8_WAIT_V(n) asm volatile("s_waitcnt vmcnt(" #n ")" ::: "memory")
; #define PG8_WAIT_L(n) asm volatile("s_waitcnt lgkmcnt(" #n ")" ::: "memory")
; #define PG8_BAR __builtin_amdgcn_s_barrier()
; #define PG8_SCHED __builtin_amdgcn_sched_barrier(0)
; template <class Epi>
; __device__ __forceinline__ void gemm_phase(LAS unsigned char* lds, const Gemm g, const Epi& E) {
;     ...
;             PG8_LDB(B0, 0, 0); PG8_SCHED; PG8_LDA(At, 0, 0); PG8_STAGE(PG8_SA(1, 1), a1 + hstep, voffA);
;             PG8_WAIT_L(8); PG8_BAR; PG8_WAIT_L(0); PG8_MMA(0, 0, At, B0); PG8_BAR; PG8_SCHED;
;             PG8_LDB(B1, 0, 1); PG8_STAGE(PG8_SB(0, 0), b2, voffB);
;             PG8_BAR; PG8_WAIT_L(0); PG8_MMA(0, 1, At, B1); PG8_BAR;
;             PG8_LDA(At, 0, 1); PG8_STAGE(PG8_SA(0, 0), a2, voffA);
;             PG8_BAR; PG8_WAIT_L(0); PG8_MMA(1, 0, At, B0); PG8_BAR; PG8_SCHED;
;             PG8_STAGE(PG8_SB(0, 1), b2 + hstep, voffB);
;             PG8_WAIT_V(6); PG8_BAR; PG8_MMA(1, 1, At, B1); PG8_BAR;
.LBB0_120:
	s_add_u32 s28, s26, 0xfff80080
	s_addc_u32 s29, s27, -1
	s_add_i32 s34, 0, 0x10000
	v_add_u32_e32 v92, s34, v174
	ds_read_b128 v[72:75], v92
	ds_read_b128 v[76:79], v92 offset:1024
	ds_read_b128 v[84:87], v92 offset:2048
	ds_read_b128 v[92:95], v92 offset:3072
	s_cmp_eq_u32 vcc_lo, 28
	s_cselect_b32 s37, s38, s29
	s_cselect_b32 s36, s39, s28
	s_cselect_b32 s29, s43, s97
	s_cselect_b32 s28, s49, s65
	s_add_i32 m0, s68, 0xc000
	ds_read_b128 v[144:147], v175
	ds_read_b128 v[148:151], v175 offset:1024
	ds_read_b128 v[164:167], v175 offset:2048
	ds_read_b128 v[168:171], v175 offset:3072
	ds_read_b128 v[178:181], v175 offset:4096
	ds_read_b128 v[182:185], v175 offset:5120
	ds_read_b128 v[186:189], v175 offset:6144
	ds_read_b128 v[190:193], v175 offset:7168
	global_load_lds_dwordx4 v160, s[26:27]
	s_add_i32 m0, s68, 0xe000
	s_nop 0
	global_load_lds_dwordx4 v162, s[26:27]
	s_waitcnt lgkmcnt(8)
	s_barrier
	s_waitcnt lgkmcnt(0)
	s_setprio 1
	v_mfma_f32_16x16x32_bf16 v[140:143], v[72:75], v[144:147], v[140:143]
	v_mfma_f32_16x16x32_bf16 v[136:139], v[84:87], v[144:147], v[136:139]
	v_mfma_f32_16x16x32_bf16 v[124:127], v[72:75], v[164:167], v[124:127]
	v_mfma_f32_16x16x32_bf16 v[120:123], v[84:87], v[164:167], v[120:123]
	v_mfma_f32_16x16x32_bf16 v[108:111], v[72:75], v[178:181], v[108:111]
	v_mfma_f32_16x16x32_bf16 v[104:107], v[84:87], v[178:181], v[104:107]
	v_mfma_f32_16x16x32_bf16 v[88:91], v[72:75], v[186:189], v[88:91]
	v_mfma_f32_16x16x32_bf16 v[80:83], v[84:87], v[186:189], v[80:83]
	v_mfma_f32_16x16x32_bf16 v[140:143], v[76:79], v[148:151], v[140:143]
	v_mfma_f32_16x16x32_bf16 v[136:139], v[92:95], v[148:151], v[136:139]
	v_mfma_f32_16x16x32_bf16 v[124:127], v[76:79], v[168:171], v[124:127]
	v_mfma_f32_16x16x32_bf16 v[120:123], v[92:95], v[168:171], v[120:123]
	v_mfma_f32_16x16x32_bf16 v[108:111], v[76:79], v[182:185], v[108:111]
	v_mfma_f32_16x16x32_bf16 v[104:107], v[92:95], v[182:185], v[104:107]
	v_mfma_f32_16x16x32_bf16 v[88:91], v[76:79], v[190:193], v[88:91]
	v_mfma_f32_16x16x32_bf16 v[80:83], v[92:95], v[190:193], v[80:83]
	s_setprio 0
	s_barrier
	s_add_i32 s46, 0, 0x14000
	v_add_u32_e32 v172, s46, v174
	s_add_i32 s34, s34, s31
	ds_read_b128 v[194:197], v172
	ds_read_b128 v[198:201], v172 offset:1024
	ds_read_b128 v[202:205], v172 offset:2048
	ds_read_b128 v[228:231], v172 offset:3072
	s_mov_b32 m0, s34
	s_nop 0
	global_load_lds_dwordx4 v208, s[28:29]
	s_add_i32 m0, s34, 0x2000
	s_nop 0
	global_load_lds_dwordx4 v156, s[28:29]
	s_barrier
	s_waitcnt lgkmcnt(0)
	s_setprio 1
	v_mfma_f32_16x16x32_bf16 v[132:135], v[194:197], v[144:147], v[132:135]
	v_mfma_f32_16x16x32_bf16 v[128:131], v[202:205], v[144:147], v[128:131]
	v_mfma_f32_16x16x32_bf16 v[116:119], v[194:197], v[164:167], v[116:119]
	v_mfma_f32_16x16x32_bf16 v[112:115], v[202:205], v[164:167], v[112:115]
	v_mfma_f32_16x16x32_bf16 v[100:103], v[194:197], v[178:181], v[100:103]
	v_mfma_f32_16x16x32_bf16 v[96:99], v[202:205], v[178:181], v[96:99]
	v_mfma_f32_16x16x32_bf16 v[68:71], v[194:197], v[186:189], v[68:71]
	v_mfma_f32_16x16x32_bf16 v[64:67], v[202:205], v[186:189], v[64:67]
	v_mfma_f32_16x16x32_bf16 v[132:135], v[198:201], v[148:151], v[132:135]
	v_mfma_f32_16x16x32_bf16 v[128:131], v[228:231], v[148:151], v[128:131]
	v_mfma_f32_16x16x32_bf16 v[116:119], v[198:201], v[168:171], v[116:119]
	v_mfma_f32_16x16x32_bf16 v[112:115], v[228:231], v[168:171], v[112:115]
	v_mfma_f32_16x16x32_bf16 v[100:103], v[198:201], v[182:185], v[100:103]
	v_mfma_f32_16x16x32_bf16 v[96:99], v[228:231], v[182:185], v[96:99]
	v_mfma_f32_16x16x32_bf16 v[68:71], v[198:201], v[190:193], v[68:71]
	v_mfma_f32_16x16x32_bf16 v[64:67], v[228:231], v[190:193], v[64:67]
	s_setprio 0
	s_mov_b32 m0, s68
	s_barrier
	ds_read_b128 v[144:147], v175 offset:16384
	ds_read_b128 v[148:151], v175 offset:17408
	ds_read_b128 v[164:167], v175 offset:18432
	ds_read_b128 v[168:171], v175 offset:19456
	ds_read_b128 v[178:181], v175 offset:20480
	ds_read_b128 v[182:185], v175 offset:21504
	ds_read_b128 v[186:189], v175 offset:22528
	ds_read_b128 v[190:193], v175 offset:23552
	global_load_lds_dwordx4 v152, s[36:37]
	s_mov_b32 m0, s69
	s_nop 0
	global_load_lds_dwordx4 v154, s[36:37]
	s_barrier
	s_waitcnt lgkmcnt(0)
	s_setprio 1
	v_mfma_f32_16x16x32_bf16 v[60:63], v[72:75], v[144:147], v[60:63]
	v_mfma_f32_16x16x32_bf16 v[56:59], v[84:87], v[144:147], v[56:59]
	v_mfma_f32_16x16x32_bf16 v[44:47], v[72:75], v[164:167], v[44:47]
	v_mfma_f32_16x16x32_bf16 v[40:43], v[84:87], v[164:167], v[40:43]
	v_mfma_f32_16x16x32_bf16 v[28:31], v[72:75], v[178:181], v[28:31]
	v_mfma_f32_16x16x32_bf16 v[24:27], v[84:87], v[178:181], v[24:27]
	v_mfma_f32_16x16x32_bf16 v[12:15], v[72:75], v[186:189], v[12:15]
	v_mfma_f32_16x16x32_bf16 v[8:11], v[84:87], v[186:189], v[8:11]
	v_mfma_f32_16x16x32_bf16 v[60:63], v[76:79], v[148:151], v[60:63]
	v_mfma_f32_16x16x32_bf16 v[56:59], v[92:95], v[148:151], v[56:59]
	v_mfma_f32_16x16x32_bf16 v[44:47], v[76:79], v[168:171], v[44:47]
	v_mfma_f32_16x16x32_bf16 v[40:43], v[92:95], v[168:171], v[40:43]
	v_mfma_f32_16x16x32_bf16 v[28:31], v[76:79], v[182:185], v[28:31]
	v_mfma_f32_16x16x32_bf16 v[24:27], v[92:95], v[182:185], v[24:27]
	v_mfma_f32_16x16x32_bf16 v[12:15], v[76:79], v[190:193], v[12:15]
	v_mfma_f32_16x16x32_bf16 v[8:11], v[92:95], v[190:193], v[8:11]
	s_setprio 0
	s_barrier
	s_add_u32 s34, s28, 0x80000
	s_addc_u32 s35, s29, 0
	s_add_i32 s46, s46, s31
	s_mov_b32 m0, s46
	s_nop 0
	global_load_lds_dwordx4 v208, s[34:35]
	s_add_i32 m0, s46, 0x2000
	s_nop 0
	global_load_lds_dwordx4 v156, s[34:35]
	s_waitcnt vmcnt(6)
	s_barrier
; #define PG8_STAGE(bufoff, gbase, voff) do { _Pragma("unroll") for (int _i = 0; _i < 2; ++_i) \
;         __builtin_amdgcn_global_load_lds((const unsigned*)((const char*)(gbase) + (voff)[_i]), (LAS unsigned*)(lds + (bufoff) + ldsw + _i * 8192), 16, 0, 0); } while (0)
; #define PG8_LDA(dst, b, h) do { _Pragma("unroll") for (int m = 0; m < 4; ++m) _Pragma("unroll") for (int k = 0; k < 2; ++k) dst[m][k] = *(const LAS bf16x8*)(lds + PG8_SA(b, h) + aoff + m * 2048 + k * 1024); } while (0)
; #define PG8_LDB(dst, b, h) do { _Pragma("unroll") for (int n = 0; n < 2; ++n) _Pragma("unroll") for (int k = 0; k < 2; ++k) dst[n][k] = *(const LAS bf16x8*)(lds + PG8_SB(b, h) + boff + n * 2048 + k * 1024); } while (0)
; #define PG8_MMA(ai, bj, At, Bt) do { __builtin_amdgcn_s_setprio(1); _Pragma("unroll") for (int m = 0; m < 4; ++m) _Pragma("unroll") for (int n = 0; n < 2; ++n) _Pragma("unroll") for (int k = 0; k < 2; ++k) \
;         acc[ai][bj][m][n] = __builtin_amdgcn_mfma_f32_16x16x32_bf16(Bt[n][k], At[m][k], acc[ai][bj][m][n], 0, 0, 0); __builtin_amdgcn_s_setprio(0); } while (0)
; #define PG8_WAIT_V(n) asm volatile("s_waitcnt vmcnt(" #n ")" ::: "memory")
; #define PG8_WAIT_L(n) asm volatile("s_waitcnt lgkmcnt(" #n ")" ::: "memory")
; #define PG8_BAR __builtin_amdgcn_s_barrier()
; #define PG8_SCHED __builtin_amdgcn_sched_barrier(0)
; template <class Epi>
; __device__ __forceinline__ void gemm_phase(LAS unsigned char* lds, const Gemm g, const Epi& E) {
;     ...
;             PG8_WAIT_V(6); PG8_BAR; PG8_MMA(1, 1, At, B1); PG8_BAR;
;             PG8_LDB(B0, 1, 0); PG8_SCHED; PG8_LDA(At, 1, 0); PG8_STAGE(PG8_SA(0, 1), a2 + hstep, voffA);
;             PG8_WAIT_L(8); PG8_BAR; PG8_WAIT_L(0); PG8_MMA(0, 0, At, B0); PG8_BAR; PG8_SCHED;
;             PG8_LDB(B1, 1, 1); PG8_STAGE(PG8_SB(1, 0), b3, voffB);
;             PG8_BAR; PG8_WAIT_L(0); PG8_MMA(0, 1, At, B1); PG8_BAR;
;             PG8_LDA(At, 1, 1); PG8_STAGE(PG8_SA(1, 0), a3, voffA);
;             PG8_BAR; PG8_WAIT_L(0); PG8_MMA(1, 0, At, B0); PG8_BAR; PG8_SCHED;
	s_setprio 1
	v_mfma_f32_16x16x32_bf16 v[52:55], v[194:197], v[144:147], v[52:55]
	v_mfma_f32_16x16x32_bf16 v[48:51], v[202:205], v[144:147], v[48:51]
	v_mfma_f32_16x16x32_bf16 v[36:39], v[194:197], v[164:167], v[36:39]
	v_mfma_f32_16x16x32_bf16 v[32:35], v[202:205], v[164:167], v[32:35]
	v_mfma_f32_16x16x32_bf16 v[20:23], v[194:197], v[178:181], v[20:23]
	v_mfma_f32_16x16x32_bf16 v[16:19], v[202:205], v[178:181], v[16:19]
	v_mfma_f32_16x16x32_bf16 v[4:7], v[194:197], v[186:189], v[4:7]
	v_mfma_f32_16x16x32_bf16 v[0:3], v[202:205], v[186:189], v[0:3]
	v_mfma_f32_16x16x32_bf16 v[52:55], v[198:201], v[148:151], v[52:55]
	v_mfma_f32_16x16x32_bf16 v[48:51], v[228:231], v[148:151], v[48:51]
	v_mfma_f32_16x16x32_bf16 v[36:39], v[198:201], v[168:171], v[36:39]
	v_mfma_f32_16x16x32_bf16 v[32:35], v[228:231], v[168:171], v[32:35]
	v_mfma_f32_16x16x32_bf16 v[20:23], v[198:201], v[182:185], v[20:23]
	v_mfma_f32_16x16x32_bf16 v[16:19], v[228:231], v[182:185], v[16:19]
	v_mfma_f32_16x16x32_bf16 v[4:7], v[198:201], v[190:193], v[4:7]
	v_mfma_f32_16x16x32_bf16 v[0:3], v[228:231], v[190:193], v[0:3]
	s_setprio 0
	s_add_i32 s46, 0, 0x18000
	v_add_u32_e32 v92, s46, v174
	s_barrier
	ds_read_b128 v[72:75], v92
	ds_read_b128 v[76:79], v92 offset:1024
	ds_read_b128 v[84:87], v92 offset:2048
	ds_read_b128 v[92:95], v92 offset:3072
	s_add_u32 s34, s36, 0x80000
	s_addc_u32 s35, s37, 0
	s_mov_b32 m0, s70
	ds_read_b128 v[144:147], v175 offset:32768
	ds_read_b128 v[148:151], v175 offset:33792
	ds_read_b128 v[164:167], v175 offset:34816
	ds_read_b128 v[168:171], v175 offset:35840
	ds_read_b128 v[178:181], v175 offset:36864
	ds_read_b128 v[182:185], v175 offset:37888
	ds_read_b128 v[186:189], v175 offset:38912
	ds_read_b128 v[190:193], v175 offset:39936
	global_load_lds_dwordx4 v152, s[34:35]
	s_mov_b32 m0, s71
	s_nop 0
	global_load_lds_dwordx4 v154, s[34:35]
	s_waitcnt lgkmcnt(8)
	s_barrier
	s_waitcnt lgkmcnt(0)
	s_setprio 1
	v_mfma_f32_16x16x32_bf16 v[140:143], v[72:75], v[144:147], v[140:143]
	v_mfma_f32_16x16x32_bf16 v[136:139], v[84:87], v[144:147], v[136:139]
	v_mfma_f32_16x16x32_bf16 v[124:127], v[72:75], v[164:167], v[124:127]
	v_mfma_f32_16x16x32_bf16 v[120:123], v[84:87], v[164:167], v[120:123]
	v_mfma_f32_16x16x32_bf16 v[108:111], v[72:75], v[178:181], v[108:111]
	v_mfma_f32_16x16x32_bf16 v[104:107], v[84:87], v[178:181], v[104:107]
	v_mfma_f32_16x16x32_bf16 v[88:91], v[72:75], v[186:189], v[88:91]
	v_mfma_f32_16x16x32_bf16 v[80:83], v[84:87], v[186:189], v[80:83]
	v_mfma_f32_16x16x32_bf16 v[140:143], v[76:79], v[148:151], v[140:143]
	v_mfma_f32_16x16x32_bf16 v[136:139], v[92:95], v[148:151], v[136:139]
	v_mfma_f32_16x16x32_bf16 v[124:127], v[76:79], v[168:171], v[124:127]
	v_mfma_f32_16x16x32_bf16 v[120:123], v[92:95], v[168:171], v[120:123]
	v_mfma_f32_16x16x32_bf16 v[108:111], v[76:79], v[182:185], v[108:111]
	v_mfma_f32_16x16x32_bf16 v[104:107], v[92:95], v[182:185], v[104:107]
	v_mfma_f32_16x16x32_bf16 v[88:91], v[76:79], v[190:193], v[88:91]
	v_mfma_f32_16x16x32_bf16 v[80:83], v[92:95], v[190:193], v[80:83]
	s_setprio 0
	s_barrier
	s_add_i32 s34, 0, 0x1c000
	s_add_i32 s35, s46, s31
	v_add_u32_e32 v177, s34, v174
	s_mov_b32 m0, s35
	ds_read_b128 v[194:197], v177
	ds_read_b128 v[198:201], v177 offset:1024
	ds_read_b128 v[202:205], v177 offset:2048
	ds_read_b128 v[228:231], v177 offset:3072
	s_add_u32 s98, s28, 0x80
	s_addc_u32 s99, s29, 0
	global_load_lds_dwordx4 v208, s[98:99]
	s_add_i32 m0, s35, 0x2000
	s_add_u32 s100, s28, 0x80
	s_addc_u32 s101, s29, 0
	global_load_lds_dwordx4 v156, s[100:101]
	s_barrier
	s_waitcnt lgkmcnt(0)
	s_setprio 1
	v_mfma_f32_16x16x32_bf16 v[132:135], v[194:197], v[144:147], v[132:135]
	v_mfma_f32_16x16x32_bf16 v[128:131], v[202:205], v[144:147], v[128:131]
	v_mfma_f32_16x16x32_bf16 v[116:119], v[194:197], v[164:167], v[116:119]
	v_mfma_f32_16x16x32_bf16 v[112:115], v[202:205], v[164:167], v[112:115]
	v_mfma_f32_16x16x32_bf16 v[100:103], v[194:197], v[178:181], v[100:103]
	v_mfma_f32_16x16x32_bf16 v[96:99], v[202:205], v[178:181], v[96:99]
	v_mfma_f32_16x16x32_bf16 v[68:71], v[194:197], v[186:189], v[68:71]
	v_mfma_f32_16x16x32_bf16 v[64:67], v[202:205], v[186:189], v[64:67]
	v_mfma_f32_16x16x32_bf16 v[132:135], v[198:201], v[148:151], v[132:135]
	v_mfma_f32_16x16x32_bf16 v[128:131], v[228:231], v[148:151], v[128:131]
	v_mfma_f32_16x16x32_bf16 v[116:119], v[198:201], v[168:171], v[116:119]
	v_mfma_f32_16x16x32_bf16 v[112:115], v[228:231], v[168:171], v[112:115]
	v_mfma_f32_16x16x32_bf16 v[100:103], v[198:201], v[182:185], v[100:103]
	v_mfma_f32_16x16x32_bf16 v[96:99], v[228:231], v[182:185], v[96:99]
	v_mfma_f32_16x16x32_bf16 v[68:71], v[198:201], v[190:193], v[68:71]
	v_mfma_f32_16x16x32_bf16 v[64:67], v[228:231], v[190:193], v[64:67]
	s_setprio 0
	s_mov_b32 m0, s78
	s_barrier
	ds_read_b128 v[144:147], v175 offset:49152
	ds_read_b128 v[148:151], v175 offset:50176
	ds_read_b128 v[164:167], v175 offset:51200
	ds_read_b128 v[168:171], v175 offset:52224
	ds_read_b128 v[178:181], v175 offset:53248
	ds_read_b128 v[182:185], v175 offset:54272
	ds_read_b128 v[186:189], v175 offset:55296
	ds_read_b128 v[190:193], v175 offset:56320
	s_add_u32 s98, s36, 0x80
	s_addc_u32 s99, s37, 0
	global_load_lds_dwordx4 v152, s[98:99]
	s_mov_b32 m0, s79
	s_add_u32 s100, s36, 0x80
	s_addc_u32 s101, s37, 0
	global_load_lds_dwordx4 v154, s[100:101]
	s_barrier
; __device__ __forceinline__ float bflo(unsigned w) { return __uint_as_float(w << 16); }
; __device__ __forceinline__ float bfhi(unsigned w) { return __uint_as_float(w & 0xffff0000u); }
; #define PG8_WAIT_V(n) asm volatile("s_waitcnt vmcnt(" #n ")" ::: "memory")
; #define PG8_BAR __builtin_amdgcn_s_barrier()
; template <class Epi>
; __device__ __forceinline__ void gemm_phase(LAS unsigned char* lds, const Gemm g, const Epi& E) {
;     ...
;             PG8_WAIT_V(6); PG8_BAR; PG8_MMA(1, 1, At, B1); PG8_BAR;
;             PG8_LDB(B0, 1, 0); PG8_SCHED; PG8_LDA(At, 1, 0); PG8_STAGE(PG8_SA(0, 1), a2 + hstep, voffA);
;             PG8_WAIT_L(8); PG8_BAR; PG8_WAIT_L(0); PG8_MMA(0, 0, At, B0); PG8_BAR; PG8_SCHED;
;             PG8_LDB(B1, 1, 1); PG8_STAGE(PG8_SB(1, 0), b3, voffB);
;             PG8_BAR; PG8_WAIT_L(0); PG8_MMA(0, 1, At, B1); PG8_BAR;
;             PG8_LDA(At, 1, 1); PG8_STAGE(PG8_SA(1, 0), a3, voffA);
;             PG8_BAR; PG8_WAIT_L(0); PG8_MMA(1, 0, At, B0); PG8_BAR; PG8_SCHED;
;             PG8_STAGE(PG8_SB(1, 1), b3 + hstep, voffB);
;             PG8_WAIT_V(6); PG8_BAR; PG8_MMA(1, 1, At, B1); PG8_BAR;
;     __device__ __forceinline__ void operator()(const AccT& acc, const Unit& u, int wr, int wc, int fr, int fq) const {
;         const int b = (u.pm * 256) / SEQ;
;         f32x4 gt[2][2];
; #pragma unroll
;         for (int bj = 0; bj < 2; ++bj)
; #pragma unroll
;             for (int n = 0; n < 2; ++n) gt[bj][n] = *(const f32x4*)(GT + (size_t)b * 6 * D + u.pn * 256 + bj * 128 + wc * 32 + fq * 8 + 4 * n);
; #pragma unroll
;         for (int ai = 0; ai < 2; ++ai)
; #pragma unroll
;             for (int m = 0; m < 4; ++m) {
;                 const int row = u.pm * 256 + ai * 128 + wr * 64 + m * 16 + fr;
; #pragma unroll
;                 for (int bj = 0; bj < 2; ++bj) {
;                     const size_t off = (size_t)row * D + u.pn * 256 + bj * 128 + wc * 32 + fq * 8;
;                     f32x4 x0, x1;
;                     if (XINF) { x0 = *(const f32x4*)(XINF + off); x1 = *(const f32x4*)(XINF + off + 4); }
;                     else { const u32x4 w = *(const u32x4*)(XIN16 + off); x0 = (f32x4){bflo(w[0]), bfhi(w[0]), bflo(w[1]), bfhi(w[1])}; x1 = (f32x4){bflo(w[2]), bfhi(w[2]), bflo(w[3]), bfhi(w[3])}; }
;                     *(u32x4*)(XOUT + off) = pack8u(x0 + gt[bj][0] * acc[ai][bj][m][0], x1 + gt[bj][1] * acc[ai][bj][m][1]);
	s_waitcnt lgkmcnt(0)
	s_setprio 1
	v_mfma_f32_16x16x32_bf16 v[60:63], v[72:75], v[144:147], v[60:63]
	v_mfma_f32_16x16x32_bf16 v[56:59], v[84:87], v[144:147], v[56:59]
	v_mfma_f32_16x16x32_bf16 v[44:47], v[72:75], v[164:167], v[44:47]
	v_mfma_f32_16x16x32_bf16 v[40:43], v[84:87], v[164:167], v[40:43]
	v_mfma_f32_16x16x32_bf16 v[28:31], v[72:75], v[178:181], v[28:31]
	v_mfma_f32_16x16x32_bf16 v[24:27], v[84:87], v[178:181], v[24:27]
	v_mfma_f32_16x16x32_bf16 v[12:15], v[72:75], v[186:189], v[12:15]
	v_mfma_f32_16x16x32_bf16 v[8:11], v[84:87], v[186:189], v[8:11]
	v_mfma_f32_16x16x32_bf16 v[60:63], v[76:79], v[148:151], v[60:63]
	v_mfma_f32_16x16x32_bf16 v[56:59], v[92:95], v[148:151], v[56:59]
	v_mfma_f32_16x16x32_bf16 v[44:47], v[76:79], v[168:171], v[44:47]
	v_mfma_f32_16x16x32_bf16 v[40:43], v[92:95], v[168:171], v[40:43]
	v_mfma_f32_16x16x32_bf16 v[28:31], v[76:79], v[182:185], v[28:31]
	v_mfma_f32_16x16x32_bf16 v[24:27], v[92:95], v[182:185], v[24:27]
	v_mfma_f32_16x16x32_bf16 v[12:15], v[76:79], v[190:193], v[12:15]
	v_mfma_f32_16x16x32_bf16 v[8:11], v[92:95], v[190:193], v[8:11]
	s_setprio 0
	s_barrier
	s_add_u32 s28, s28, 0x80080
	s_addc_u32 s29, s29, 0
	s_add_i32 s34, s34, s31
	s_mov_b32 m0, s34
	s_nop 0
	global_load_lds_dwordx4 v208, s[28:29]
	s_add_i32 m0, s34, 0x2000
	s_nop 0
	global_load_lds_dwordx4 v156, s[28:29]
	s_waitcnt vmcnt(6)
	s_barrier
	s_setprio 1
	v_mfma_f32_16x16x32_bf16 v[52:55], v[194:197], v[144:147], v[52:55]
	v_mfma_f32_16x16x32_bf16 v[48:51], v[202:205], v[144:147], v[48:51]
	v_mfma_f32_16x16x32_bf16 v[36:39], v[194:197], v[164:167], v[36:39]
	v_mfma_f32_16x16x32_bf16 v[32:35], v[202:205], v[164:167], v[32:35]
	v_mfma_f32_16x16x32_bf16 v[20:23], v[194:197], v[178:181], v[20:23]
	v_mfma_f32_16x16x32_bf16 v[16:19], v[202:205], v[178:181], v[16:19]
	v_mfma_f32_16x16x32_bf16 v[4:7], v[194:197], v[186:189], v[4:7]
	v_mfma_f32_16x16x32_bf16 v[0:3], v[202:205], v[186:189], v[0:3]
	v_mfma_f32_16x16x32_bf16 v[52:55], v[198:201], v[148:151], v[52:55]
	v_mfma_f32_16x16x32_bf16 v[48:51], v[228:231], v[148:151], v[48:51]
	v_mfma_f32_16x16x32_bf16 v[36:39], v[198:201], v[168:171], v[36:39]
	v_mfma_f32_16x16x32_bf16 v[32:35], v[228:231], v[168:171], v[32:35]
	v_mfma_f32_16x16x32_bf16 v[20:23], v[198:201], v[182:185], v[20:23]
	v_mfma_f32_16x16x32_bf16 v[16:19], v[228:231], v[182:185], v[16:19]
	v_mfma_f32_16x16x32_bf16 v[4:7], v[198:201], v[190:193], v[4:7]
	v_mfma_f32_16x16x32_bf16 v[0:3], v[228:231], v[190:193], v[0:3]
	s_setprio 0
	s_add_i32 vcc_lo, vcc_lo, 2
	s_add_u32 s26, s26, 0x100
	s_addc_u32 s27, s27, 0
	s_add_u32 s65, s65, 0x100
	s_addc_u32 s97, s97, 0
	s_cmp_gt_u32 vcc_lo, 29
	s_barrier
	s_cbranch_scc0 .LBB0_120
	s_ashr_i32 s26, s42, 31
	s_lshr_b32 s26, s26, 29
	s_add_i32 s26, s42, s26
	s_ashr_i32 s26, s26, 3
	s_mul_i32 s26, s26, 6
	s_ashr_i32 s27, s26, 31
	s_lshl_b64 s[26:27], s[26:27], 13
	s_add_u32 s34, s74, s26
	s_addc_u32 s35, s76, s27
	s_lshl_b32 s26, s96, 8
	s_ashr_i32 s27, s26, 31
	s_lshl_b64 s[28:29], s[26:27], 2
	s_add_u32 s28, s34, s28
	s_addc_u32 s29, s35, s29
	s_add_u32 s28, s28, s83
	s_addc_u32 s29, s29, 0
	global_load_dwordx4 v[84:87], v176, s[28:29] offset:16
	global_load_dwordx4 v[92:95], v176, s[28:29]
	global_load_dwordx4 v[72:75], v176, s[28:29] offset:528
	global_load_dwordx4 v[76:79], v176, s[28:29] offset:512
	v_readlane_b32 s34, v255, 22
	v_readlane_b32 s35, v255, 23
	v_lshl_add_u32 v166, s42, 8, v159
	v_or_b32_e32 v167, s26, v158
	v_lshlrev_b32_e32 v164, 2, v167
	v_lshl_add_u32 v164, v166, 13, v164
	v_lshlrev_b32_e32 v165, 1, v167
	v_lshl_add_u32 v165, v166, 12, v165
	s_and_b64 vcc, exec, s[44:45]
	s_cbranch_vccnz .Lepr1_f32
	v_add_u32_e32 v166, 0x0, v165
	global_load_dwordx4 v[168:171], v166, s[34:35] offset:0
	v_add_u32_e32 v166, 0x0, v165
	global_load_dwordx4 v[178:181], v166, s[34:35] offset:256
	v_add_u32_e32 v166, 0x10000, v165
	global_load_dwordx4 v[182:185], v166, s[34:35] offset:0
	v_add_u32_e32 v166, 0x10000, v165
	global_load_dwordx4 v[186:189], v166, s[34:35] offset:256
	v_add_u32_e32 v166, 0x20000, v165
	global_load_dwordx4 v[190:193], v166, s[34:35] offset:0
	v_add_u32_e32 v166, 0x20000, v165
	global_load_dwordx4 v[194:197], v166, s[34:35] offset:256
	v_add_u32_e32 v166, 0x30000, v165
	global_load_dwordx4 v[198:201], v166, s[34:35] offset:0
	v_add_u32_e32 v166, 0x30000, v165
	global_load_dwordx4 v[202:205], v166, s[34:35] offset:256
	v_add_u32_e32 v166, 0x80000, v165
	global_load_dwordx4 v[228:231], v166, s[34:35] offset:0
	s_waitcnt vmcnt(8)
	v_lshlrev_b32_e32 v144, 16, v168
	v_and_b32_e32 v145, 0xffff0000, v168
	v_lshlrev_b32_e32 v146, 16, v169
	v_and_b32_e32 v147, 0xffff0000, v169
	v_lshlrev_b32_e32 v148, 16, v170
	v_and_b32_e32 v149, 0xffff0000, v170
	v_lshlrev_b32_e32 v150, 16, v171
	v_and_b32_e32 v151, 0xffff0000, v171
	v_pk_fma_f32 v[140:141], v[140:141], v[92:93], v[144:145]
	v_pk_fma_f32 v[142:143], v[142:143], v[94:95], v[146:147]
	v_pk_fma_f32 v[136:137], v[136:137], v[84:85], v[148:149]
	v_pk_fma_f32 v[138:139], v[138:139], v[86:87], v[150:151]
	v_cvt_pk_bf16_f32 v140, v140, v141
	v_cvt_pk_bf16_f32 v141, v142, v143
	v_cvt_pk_bf16_f32 v142, v136, v137
	v_cvt_pk_bf16_f32 v143, v138, v139
	v_add_u32_e32 v167, 0x0, v165
	global_store_dwordx4 v167, v[140:143], s[34:35] offset:0
	v_add_u32_e32 v166, 0x80000, v165
	global_load_dwordx4 v[168:171], v166, s[34:35] offset:256
	v_add_u32_e32 v166, 0x90000, v165
	global_load_dwordx4 v[136:139], v166, s[34:35] offset:0
	s_waitcnt vmcnt(10)
; __device__ __forceinline__ float bflo(unsigned w) { return __uint_as_float(w << 16); }
; __device__ __forceinline__ float bfhi(unsigned w) { return __uint_as_float(w & 0xffff0000u); }
; __device__ __forceinline__ u32x4 pack8u(f32x4 a, f32x4 b) { u32x4 w = {cvt_pk_bf16(a[0], a[1]), cvt_pk_bf16(a[2], a[3]), cvt_pk_bf16(b[0], b[1]), cvt_pk_bf16(b[2], b[3])}; return w; }
;     __device__ __forceinline__ void operator()(const AccT& acc, const Unit& u, int wr, int wc, int fr, int fq) const {
;     ...
;                 for (int bj = 0; bj < 2; ++bj) {
;                     const size_t off = (size_t)row * D + u.pn * 256 + bj * 128 + wc * 32 + fq * 8;
;                     f32x4 x0, x1;
;                     if (XINF) { x0 = *(const f32x4*)(XINF + off); x1 = *(const f32x4*)(XINF + off + 4); }
;                     else { const u32x4 w = *(const u32x4*)(XIN16 + off); x0 = (f32x4){bflo(w[0]), bfhi(w[0]), bflo(w[1]), bfhi(w[1])}; x1 = (f32x4){bflo(w[2]), bfhi(w[2]), bflo(w[3]), bfhi(w[3])}; }
;                     *(u32x4*)(XOUT + off) = pack8u(x0 + gt[bj][0] * acc[ai][bj][m][0], x1 + gt[bj][1] * acc[ai][bj][m][1]);
	v_lshlrev_b32_e32 v144, 16, v178
	v_and_b32_e32 v145, 0xffff0000, v178
	v_lshlrev_b32_e32 v146, 16, v179
	v_and_b32_e32 v147, 0xffff0000, v179
	v_lshlrev_b32_e32 v148, 16, v180
	v_and_b32_e32 v149, 0xffff0000, v180
	v_lshlrev_b32_e32 v150, 16, v181
	v_and_b32_e32 v151, 0xffff0000, v181
	v_pk_fma_f32 v[132:133], v[132:133], v[76:77], v[144:145]
	v_pk_fma_f32 v[134:135], v[134:135], v[78:79], v[146:147]
	v_pk_fma_f32 v[128:129], v[128:129], v[72:73], v[148:149]
	v_pk_fma_f32 v[130:131], v[130:131], v[74:75], v[150:151]
	v_cvt_pk_bf16_f32 v132, v132, v133
	v_cvt_pk_bf16_f32 v133, v134, v135
	v_cvt_pk_bf16_f32 v134, v128, v129
	v_cvt_pk_bf16_f32 v135, v130, v131
	v_add_u32_e32 v167, 0x0, v165
	global_store_dwordx4 v167, v[132:135], s[34:35] offset:256
	v_add_u32_e32 v166, 0x90000, v165
	global_load_dwordx4 v[178:181], v166, s[34:35] offset:256
	v_add_u32_e32 v166, 0xa0000, v165
	global_load_dwordx4 v[128:131], v166, s[34:35] offset:0
	s_waitcnt vmcnt(12)
	v_lshlrev_b32_e32 v144, 16, v182
	v_and_b32_e32 v145, 0xffff0000, v182
	v_lshlrev_b32_e32 v146, 16, v183
	v_and_b32_e32 v147, 0xffff0000, v183
	v_lshlrev_b32_e32 v148, 16, v184
	v_and_b32_e32 v149, 0xffff0000, v184
	v_lshlrev_b32_e32 v150, 16, v185
	v_and_b32_e32 v151, 0xffff0000, v185
	v_pk_fma_f32 v[124:125], v[124:125], v[92:93], v[144:145]
	v_pk_fma_f32 v[126:127], v[126:127], v[94:95], v[146:147]
	v_pk_fma_f32 v[120:121], v[120:121], v[84:85], v[148:149]
	v_pk_fma_f32 v[122:123], v[122:123], v[86:87], v[150:151]
	v_cvt_pk_bf16_f32 v124, v124, v125
	v_cvt_pk_bf16_f32 v125, v126, v127
	v_cvt_pk_bf16_f32 v126, v120, v121
	v_cvt_pk_bf16_f32 v127, v122, v123
	v_add_u32_e32 v167, 0x10000, v165
	global_store_dwordx4 v167, v[124:127], s[34:35] offset:0
	v_add_u32_e32 v166, 0xa0000, v165
	global_load_dwordx4 v[182:185], v166, s[34:35] offset:256
	v_add_u32_e32 v166, 0xb0000, v165
	global_load_dwordx4 v[120:123], v166, s[34:35] offset:0
	s_waitcnt vmcnt(14)
	v_lshlrev_b32_e32 v144, 16, v186
	v_and_b32_e32 v145, 0xffff0000, v186
	v_lshlrev_b32_e32 v146, 16, v187
	v_and_b32_e32 v147, 0xffff0000, v187
	v_lshlrev_b32_e32 v148, 16, v188
	v_and_b32_e32 v149, 0xffff0000, v188
	v_lshlrev_b32_e32 v150, 16, v189
	v_and_b32_e32 v151, 0xffff0000, v189
	v_pk_fma_f32 v[116:117], v[116:117], v[76:77], v[144:145]
	v_pk_fma_f32 v[118:119], v[118:119], v[78:79], v[146:147]
	v_pk_fma_f32 v[112:113], v[112:113], v[72:73], v[148:149]
	v_pk_fma_f32 v[114:115], v[114:115], v[74:75], v[150:151]
	v_cvt_pk_bf16_f32 v116, v116, v117
	v_cvt_pk_bf16_f32 v117, v118, v119
	v_cvt_pk_bf16_f32 v118, v112, v113
	v_cvt_pk_bf16_f32 v119, v114, v115
	v_add_u32_e32 v167, 0x10000, v165
	global_store_dwordx4 v167, v[116:119], s[34:35] offset:256
	v_add_u32_e32 v166, 0xb0000, v165
	global_load_dwordx4 v[186:189], v166, s[34:35] offset:256
	s_waitcnt vmcnt(15)
	v_lshlrev_b32_e32 v144, 16, v190
	v_and_b32_e32 v145, 0xffff0000, v190
	v_lshlrev_b32_e32 v146, 16, v191
	v_and_b32_e32 v147, 0xffff0000, v191
	v_lshlrev_b32_e32 v148, 16, v192
	v_and_b32_e32 v149, 0xffff0000, v192
	v_lshlrev_b32_e32 v150, 16, v193
	v_and_b32_e32 v151, 0xffff0000, v193
	v_pk_fma_f32 v[108:109], v[108:109], v[92:93], v[144:145]
	v_pk_fma_f32 v[110:111], v[110:111], v[94:95], v[146:147]
	v_pk_fma_f32 v[104:105], v[104:105], v[84:85], v[148:149]
	v_pk_fma_f32 v[106:107], v[106:107], v[86:87], v[150:151]
	v_cvt_pk_bf16_f32 v108, v108, v109
	v_cvt_pk_bf16_f32 v109, v110, v111
	v_cvt_pk_bf16_f32 v110, v104, v105
	v_cvt_pk_bf16_f32 v111, v106, v107
	v_add_u32_e32 v167, 0x20000, v165
	global_store_dwordx4 v167, v[108:111], s[34:35] offset:0
	s_waitcnt vmcnt(15)
	v_lshlrev_b32_e32 v144, 16, v194
	v_and_b32_e32 v145, 0xffff0000, v194
	v_lshlrev_b32_e32 v146, 16, v195
	v_and_b32_e32 v147, 0xffff0000, v195
	v_lshlrev_b32_e32 v148, 16, v196
	v_and_b32_e32 v149, 0xffff0000, v196
	v_lshlrev_b32_e32 v150, 16, v197
	v_and_b32_e32 v151, 0xffff0000, v197
	v_pk_fma_f32 v[100:101], v[100:101], v[76:77], v[144:145]
	v_pk_fma_f32 v[102:103], v[102:103], v[78:79], v[146:147]
	v_pk_fma_f32 v[96:97], v[96:97], v[72:73], v[148:149]
	v_pk_fma_f32 v[98:99], v[98:99], v[74:75], v[150:151]
	v_cvt_pk_bf16_f32 v100, v100, v101
	v_cvt_pk_bf16_f32 v101, v102, v103
	v_cvt_pk_bf16_f32 v102, v96, v97
	v_cvt_pk_bf16_f32 v103, v98, v99
	v_add_u32_e32 v167, 0x20000, v165
	global_store_dwordx4 v167, v[100:103], s[34:35] offset:256
	s_waitcnt vmcnt(15)
	v_lshlrev_b32_e32 v144, 16, v198
	v_and_b32_e32 v145, 0xffff0000, v198
	v_lshlrev_b32_e32 v146, 16, v199
	v_and_b32_e32 v147, 0xffff0000, v199
	v_lshlrev_b32_e32 v148, 16, v200
	v_and_b32_e32 v149, 0xffff0000, v200
	v_lshlrev_b32_e32 v150, 16, v201
	v_and_b32_e32 v151, 0xffff0000, v201
	v_pk_fma_f32 v[88:89], v[88:89], v[92:93], v[144:145]
	v_pk_fma_f32 v[90:91], v[90:91], v[94:95], v[146:147]
	v_pk_fma_f32 v[80:81], v[80:81], v[84:85], v[148:149]
	v_pk_fma_f32 v[82:83], v[82:83], v[86:87], v[150:151]
	v_cvt_pk_bf16_f32 v88, v88, v89
	v_cvt_pk_bf16_f32 v89, v90, v91
	v_cvt_pk_bf16_f32 v90, v80, v81
	v_cvt_pk_bf16_f32 v91, v82, v83
	v_add_u32_e32 v167, 0x30000, v165
	global_store_dwordx4 v167, v[88:91], s[34:35] offset:0
	s_waitcnt vmcnt(15)
	v_lshlrev_b32_e32 v144, 16, v202
	v_and_b32_e32 v145, 0xffff0000, v202
	v_lshlrev_b32_e32 v146, 16, v203
	v_and_b32_e32 v147, 0xffff0000, v203
	v_lshlrev_b32_e32 v148, 16, v204
	v_and_b32_e32 v149, 0xffff0000, v204
	v_lshlrev_b32_e32 v150, 16, v205
	v_and_b32_e32 v151, 0xffff0000, v205
	v_pk_fma_f32 v[68:69], v[68:69], v[76:77], v[144:145]
	v_pk_fma_f32 v[70:71], v[70:71], v[78:79], v[146:147]
	v_pk_fma_f32 v[64:65], v[64:65], v[72:73], v[148:149]
	v_pk_fma_f32 v[66:67], v[66:67], v[74:75], v[150:151]
	v_cvt_pk_bf16_f32 v68, v68, v69
	v_cvt_pk_bf16_f32 v69, v70, v71
	v_cvt_pk_bf16_f32 v70, v64, v65
	v_cvt_pk_bf16_f32 v71, v66, v67
	v_add_u32_e32 v167, 0x30000, v165
	global_store_dwordx4 v167, v[68:71], s[34:35] offset:256
	s_waitcnt vmcnt(15)
; __device__ __forceinline__ float bflo(unsigned w) { return __uint_as_float(w << 16); }
; __device__ __forceinline__ float bfhi(unsigned w) { return __uint_as_float(w & 0xffff0000u); }
; __device__ __forceinline__ u32x4 pack8u(f32x4 a, f32x4 b) { u32x4 w = {cvt_pk_bf16(a[0], a[1]), cvt_pk_bf16(a[2], a[3]), cvt_pk_bf16(b[0], b[1]), cvt_pk_bf16(b[2], b[3])}; return w; }
;     __device__ __forceinline__ void operator()(const AccT& acc, const Unit& u, int wr, int wc, int fr, int fq) const {
;     ...
;                 for (int bj = 0; bj < 2; ++bj) {
;                     const size_t off = (size_t)row * D + u.pn * 256 + bj * 128 + wc * 32 + fq * 8;
;                     f32x4 x0, x1;
;                     if (XINF) { x0 = *(const f32x4*)(XINF + off); x1 = *(const f32x4*)(XINF + off + 4); }
;                     else { const u32x4 w = *(const u32x4*)(XIN16 + off); x0 = (f32x4){bflo(w[0]), bfhi(w[0]), bflo(w[1]), bfhi(w[1])}; x1 = (f32x4){bflo(w[2]), bfhi(w[2]), bflo(w[3]), bfhi(w[3])}; }
;                     *(u32x4*)(XOUT + off) = pack8u(x0 + gt[bj][0] * acc[ai][bj][m][0], x1 + gt[bj][1] * acc[ai][bj][m][1]);
	v_lshlrev_b32_e32 v144, 16, v228
	v_and_b32_e32 v145, 0xffff0000, v228
	v_lshlrev_b32_e32 v146, 16, v229
	v_and_b32_e32 v147, 0xffff0000, v229
	v_lshlrev_b32_e32 v148, 16, v230
	v_and_b32_e32 v149, 0xffff0000, v230
	v_lshlrev_b32_e32 v150, 16, v231
	v_and_b32_e32 v151, 0xffff0000, v231
	v_pk_fma_f32 v[60:61], v[60:61], v[92:93], v[144:145]
	v_pk_fma_f32 v[62:63], v[62:63], v[94:95], v[146:147]
	v_pk_fma_f32 v[56:57], v[56:57], v[84:85], v[148:149]
	v_pk_fma_f32 v[58:59], v[58:59], v[86:87], v[150:151]
	v_cvt_pk_bf16_f32 v60, v60, v61
	v_cvt_pk_bf16_f32 v61, v62, v63
	v_cvt_pk_bf16_f32 v62, v56, v57
	v_cvt_pk_bf16_f32 v63, v58, v59
	v_add_u32_e32 v167, 0x80000, v165
	global_store_dwordx4 v167, v[60:63], s[34:35] offset:0
	s_waitcnt vmcnt(14)
	v_lshlrev_b32_e32 v144, 16, v168
	v_and_b32_e32 v145, 0xffff0000, v168
	v_lshlrev_b32_e32 v146, 16, v169
	v_and_b32_e32 v147, 0xffff0000, v169
	v_lshlrev_b32_e32 v148, 16, v170
	v_and_b32_e32 v149, 0xffff0000, v170
	v_lshlrev_b32_e32 v150, 16, v171
	v_and_b32_e32 v151, 0xffff0000, v171
	v_pk_fma_f32 v[52:53], v[52:53], v[76:77], v[144:145]
	v_pk_fma_f32 v[54:55], v[54:55], v[78:79], v[146:147]
	v_pk_fma_f32 v[48:49], v[48:49], v[72:73], v[148:149]
	v_pk_fma_f32 v[50:51], v[50:51], v[74:75], v[150:151]
	v_cvt_pk_bf16_f32 v52, v52, v53
	v_cvt_pk_bf16_f32 v53, v54, v55
	v_cvt_pk_bf16_f32 v54, v48, v49
	v_cvt_pk_bf16_f32 v55, v50, v51
	v_add_u32_e32 v167, 0x80000, v165
	global_store_dwordx4 v167, v[52:55], s[34:35] offset:256
	s_waitcnt vmcnt(14)
	v_lshlrev_b32_e32 v144, 16, v136
	v_and_b32_e32 v145, 0xffff0000, v136
	v_lshlrev_b32_e32 v146, 16, v137
	v_and_b32_e32 v147, 0xffff0000, v137
	v_lshlrev_b32_e32 v148, 16, v138
	v_and_b32_e32 v149, 0xffff0000, v138
	v_lshlrev_b32_e32 v150, 16, v139
	v_and_b32_e32 v151, 0xffff0000, v139
	v_pk_fma_f32 v[44:45], v[44:45], v[92:93], v[144:145]
	v_pk_fma_f32 v[46:47], v[46:47], v[94:95], v[146:147]
	v_pk_fma_f32 v[40:41], v[40:41], v[84:85], v[148:149]
	v_pk_fma_f32 v[42:43], v[42:43], v[86:87], v[150:151]
	v_cvt_pk_bf16_f32 v44, v44, v45
	v_cvt_pk_bf16_f32 v45, v46, v47
	v_cvt_pk_bf16_f32 v46, v40, v41
	v_cvt_pk_bf16_f32 v47, v42, v43
	v_add_u32_e32 v167, 0x90000, v165
	global_store_dwordx4 v167, v[44:47], s[34:35] offset:0
	s_waitcnt vmcnt(13)
	v_lshlrev_b32_e32 v144, 16, v178
	v_and_b32_e32 v145, 0xffff0000, v178
	v_lshlrev_b32_e32 v146, 16, v179
	v_and_b32_e32 v147, 0xffff0000, v179
	v_lshlrev_b32_e32 v148, 16, v180
	v_and_b32_e32 v149, 0xffff0000, v180
	v_lshlrev_b32_e32 v150, 16, v181
	v_and_b32_e32 v151, 0xffff0000, v181
	v_pk_fma_f32 v[36:37], v[36:37], v[76:77], v[144:145]
	v_pk_fma_f32 v[38:39], v[38:39], v[78:79], v[146:147]
	v_pk_fma_f32 v[32:33], v[32:33], v[72:73], v[148:149]
	v_pk_fma_f32 v[34:35], v[34:35], v[74:75], v[150:151]
	v_cvt_pk_bf16_f32 v36, v36, v37
	v_cvt_pk_bf16_f32 v37, v38, v39
	v_cvt_pk_bf16_f32 v38, v32, v33
	v_cvt_pk_bf16_f32 v39, v34, v35
	v_add_u32_e32 v167, 0x90000, v165
	global_store_dwordx4 v167, v[36:39], s[34:35] offset:256
	s_waitcnt vmcnt(13)
	v_lshlrev_b32_e32 v144, 16, v128
	v_and_b32_e32 v145, 0xffff0000, v128
	v_lshlrev_b32_e32 v146, 16, v129
	v_and_b32_e32 v147, 0xffff0000, v129
	v_lshlrev_b32_e32 v148, 16, v130
	v_and_b32_e32 v149, 0xffff0000, v130
	v_lshlrev_b32_e32 v150, 16, v131
	v_and_b32_e32 v151, 0xffff0000, v131
	v_pk_fma_f32 v[28:29], v[28:29], v[92:93], v[144:145]
	v_pk_fma_f32 v[30:31], v[30:31], v[94:95], v[146:147]
	v_pk_fma_f32 v[24:25], v[24:25], v[84:85], v[148:149]
	v_pk_fma_f32 v[26:27], v[26:27], v[86:87], v[150:151]
	v_cvt_pk_bf16_f32 v28, v28, v29
	v_cvt_pk_bf16_f32 v29, v30, v31
	v_cvt_pk_bf16_f32 v30, v24, v25
	v_cvt_pk_bf16_f32 v31, v26, v27
	v_add_u32_e32 v167, 0xa0000, v165
	global_store_dwordx4 v167, v[28:31], s[34:35] offset:0
	s_waitcnt vmcnt(12)
	v_lshlrev_b32_e32 v144, 16, v182
	v_and_b32_e32 v145, 0xffff0000, v182
	v_lshlrev_b32_e32 v146, 16, v183
	v_and_b32_e32 v147, 0xffff0000, v183
	v_lshlrev_b32_e32 v148, 16, v184
	v_and_b32_e32 v149, 0xffff0000, v184
	v_lshlrev_b32_e32 v150, 16, v185
	v_and_b32_e32 v151, 0xffff0000, v185
	v_pk_fma_f32 v[20:21], v[20:21], v[76:77], v[144:145]
	v_pk_fma_f32 v[22:23], v[22:23], v[78:79], v[146:147]
	v_pk_fma_f32 v[16:17], v[16:17], v[72:73], v[148:149]
	v_pk_fma_f32 v[18:19], v[18:19], v[74:75], v[150:151]
	v_cvt_pk_bf16_f32 v20, v20, v21
	v_cvt_pk_bf16_f32 v21, v22, v23
	v_cvt_pk_bf16_f32 v22, v16, v17
	v_cvt_pk_bf16_f32 v23, v18, v19
	v_add_u32_e32 v167, 0xa0000, v165
	global_store_dwordx4 v167, v[20:23], s[34:35] offset:256
	s_waitcnt vmcnt(12)
	v_lshlrev_b32_e32 v144, 16, v120
	v_and_b32_e32 v145, 0xffff0000, v120
	v_lshlrev_b32_e32 v146, 16, v121
	v_and_b32_e32 v147, 0xffff0000, v121
	v_lshlrev_b32_e32 v148, 16, v122
	v_and_b32_e32 v149, 0xffff0000, v122
	v_lshlrev_b32_e32 v150, 16, v123
	v_and_b32_e32 v151, 0xffff0000, v123
	v_pk_fma_f32 v[12:13], v[12:13], v[92:93], v[144:145]
	v_pk_fma_f32 v[14:15], v[14:15], v[94:95], v[146:147]
	v_pk_fma_f32 v[8:9], v[8:9], v[84:85], v[148:149]
	v_pk_fma_f32 v[10:11], v[10:11], v[86:87], v[150:151]
	v_cvt_pk_bf16_f32 v12, v12, v13
	v_cvt_pk_bf16_f32 v13, v14, v15
	v_cvt_pk_bf16_f32 v14, v8, v9
	v_cvt_pk_bf16_f32 v15, v10, v11
	v_add_u32_e32 v167, 0xb0000, v165
	global_store_dwordx4 v167, v[12:15], s[34:35] offset:0
	s_waitcnt vmcnt(11)
	v_lshlrev_b32_e32 v144, 16, v186
	v_and_b32_e32 v145, 0xffff0000, v186
	v_lshlrev_b32_e32 v146, 16, v187
	v_and_b32_e32 v147, 0xffff0000, v187
	v_lshlrev_b32_e32 v148, 16, v188
	v_and_b32_e32 v149, 0xffff0000, v188
	v_lshlrev_b32_e32 v150, 16, v189
	v_and_b32_e32 v151, 0xffff0000, v189
	v_pk_fma_f32 v[4:5], v[4:5], v[76:77], v[144:145]
	v_pk_fma_f32 v[6:7], v[6:7], v[78:79], v[146:147]
	v_pk_fma_f32 v[0:1], v[0:1], v[72:73], v[148:149]
	v_pk_fma_f32 v[2:3], v[2:3], v[74:75], v[150:151]
	v_cvt_pk_bf16_f32 v4, v4, v5
	v_cvt_pk_bf16_f32 v5, v6, v7
	v_cvt_pk_bf16_f32 v6, v0, v1
	v_cvt_pk_bf16_f32 v7, v2, v3
	v_add_u32_e32 v167, 0xb0000, v165
	global_store_dwordx4 v167, v[4:7], s[34:35] offset:256
	s_mov_b64 s[42:43], exec
	s_branch .Lepr1_latch

; #define PG8_STAGE(bufoff, gbase, voff) do { _Pragma("unroll") for (int _i = 0; _i < 2; ++_i) \
;         __builtin_amdgcn_global_load_lds((const unsigned*)((const char*)(gbase) + (voff)[_i]), (LAS unsigned*)(lds + (bufoff) + ldsw + _i * 8192), 16, 0, 0); } while (0)
; #define PG8_LDA(dst, b, h) do { _Pragma("unroll") for (int m = 0; m < 4; ++m) _Pragma("unroll") for (int k = 0; k < 2; ++k) dst[m][k] = *(const LAS bf16x8*)(lds + PG8_SA(b, h) + aoff + m * 2048 + k * 1024); } while (0)
; #define PG8_LDB(dst, b, h) do { _Pragma("unroll") for (int n = 0; n < 2; ++n) _Pragma("unroll") for (int k = 0; k < 2; ++k) dst[n][k] = *(const LAS bf16x8*)(lds + PG8_SB(b, h) + boff + n * 2048 + k * 1024); } while (0)
; #define PG8_MMA(ai, bj, At, Bt) do { __builtin_amdgcn_s_setprio(1); _Pragma("unroll") for (int m = 0; m < 4; ++m) _Pragma("unroll") for (int n = 0; n < 2; ++n) _Pragma("unroll") for (int k = 0; k < 2; ++k) \
;         acc[ai][bj][m][n] = __builtin_amdgcn_mfma_f32_16x16x32_bf16(Bt[n][k], At[m][k], acc[ai][bj][m][n], 0, 0, 0); __builtin_amdgcn_s_setprio(0); } while (0)
; #define PG8_WAIT_V(n) asm volatile("s_waitcnt vmcnt(" #n ")" ::: "memory")
; #define PG8_WAIT_L(n) asm volatile("s_waitcnt lgkmcnt(" #n ")" ::: "memory")
; #define PG8_BAR __builtin_amdgcn_s_barrier()
; #define PG8_SCHED __builtin_amdgcn_sched_barrier(0)
; template <class Epi>
; __device__ __forceinline__ void gemm_phase(LAS unsigned char* lds, const Gemm g, const Epi& E) {
;     ...
;             PG8_LDB(B0, 0, 0); PG8_SCHED; PG8_LDA(At, 0, 0); PG8_STAGE(PG8_SA(1, 1), a1 + hstep, voffA);
;             PG8_WAIT_L(8); PG8_BAR; PG8_WAIT_L(0); PG8_MMA(0, 0, At, B0); PG8_BAR; PG8_SCHED;
;             PG8_LDB(B1, 0, 1); PG8_STAGE(PG8_SB(0, 0), b2, voffB);
;             PG8_BAR; PG8_WAIT_L(0); PG8_MMA(0, 1, At, B1); PG8_BAR;
;             PG8_LDA(At, 0, 1); PG8_STAGE(PG8_SA(0, 0), a2, voffA);
;             PG8_BAR; PG8_WAIT_L(0); PG8_MMA(1, 0, At, B0); PG8_BAR; PG8_SCHED;
;             PG8_STAGE(PG8_SB(0, 1), b2 + hstep, voffB);
;             PG8_WAIT_V(6); PG8_BAR; PG8_MMA(1, 1, At, B1); PG8_BAR;
.LBB0_211:
	s_add_u32 s28, s26, 0xfffc0080
	s_addc_u32 s29, s27, -1
	s_add_i32 s34, 0, 0x10000
	v_add_u32_e32 v150, s34, v159
	ds_read_b128 v[138:141], v150
	ds_read_b128 v[142:145], v150 offset:1024
	ds_read_b128 v[146:149], v150 offset:2048
	ds_read_b128 v[150:153], v150 offset:3072
	s_cmp_eq_u32 vcc_hi, 12
	s_cselect_b32 s37, s38, s29
	s_cselect_b32 s36, s39, s28
	s_cselect_b32 s29, s43, vcc_lo
	s_cselect_b32 s28, s49, s65
	s_add_i32 m0, s74, 0xc000
	ds_read_b128 v[154:157], v161
	ds_read_b128 v[162:165], v161 offset:1024
	ds_read_b128 v[166:169], v161 offset:2048
	ds_read_b128 v[170:173], v161 offset:3072
	ds_read_b128 v[174:177], v161 offset:4096
	ds_read_b128 v[178:181], v161 offset:5120
	ds_read_b128 v[182:185], v161 offset:6144
	ds_read_b128 v[186:189], v161 offset:7168
	global_load_lds_dwordx4 v134, s[26:27]
	s_add_i32 m0, s74, 0xe000
	s_nop 0
	global_load_lds_dwordx4 v136, s[26:27]
	s_waitcnt lgkmcnt(8)
	s_barrier
	s_waitcnt lgkmcnt(0)
	s_setprio 1
	v_mfma_f32_16x16x32_bf16 v[124:127], v[138:141], v[154:157], v[124:127]
	v_mfma_f32_16x16x32_bf16 v[120:123], v[146:149], v[154:157], v[120:123]
	v_mfma_f32_16x16x32_bf16 v[108:111], v[138:141], v[166:169], v[108:111]
	v_mfma_f32_16x16x32_bf16 v[104:107], v[146:149], v[166:169], v[104:107]
	v_mfma_f32_16x16x32_bf16 v[92:95], v[138:141], v[174:177], v[92:95]
	v_mfma_f32_16x16x32_bf16 v[88:91], v[146:149], v[174:177], v[88:91]
	v_mfma_f32_16x16x32_bf16 v[76:79], v[138:141], v[182:185], v[76:79]
	v_mfma_f32_16x16x32_bf16 v[72:75], v[146:149], v[182:185], v[72:75]
	v_mfma_f32_16x16x32_bf16 v[124:127], v[142:145], v[162:165], v[124:127]
	v_mfma_f32_16x16x32_bf16 v[120:123], v[150:153], v[162:165], v[120:123]
	v_mfma_f32_16x16x32_bf16 v[108:111], v[142:145], v[170:173], v[108:111]
	v_mfma_f32_16x16x32_bf16 v[104:107], v[150:153], v[170:173], v[104:107]
	v_mfma_f32_16x16x32_bf16 v[92:95], v[142:145], v[178:181], v[92:95]
	v_mfma_f32_16x16x32_bf16 v[88:91], v[150:153], v[178:181], v[88:91]
	v_mfma_f32_16x16x32_bf16 v[76:79], v[142:145], v[186:189], v[76:79]
	v_mfma_f32_16x16x32_bf16 v[72:75], v[150:153], v[186:189], v[72:75]
	s_setprio 0
	s_barrier
	s_add_i32 s46, 0, 0x14000
	s_add_i32 s34, s34, s71
	v_add_u32_e32 v202, s46, v159
	s_mov_b32 m0, s34
	ds_read_b128 v[190:193], v202
	ds_read_b128 v[194:197], v202 offset:1024
	ds_read_b128 v[198:201], v202 offset:2048
	ds_read_b128 v[202:205], v202 offset:3072
	global_load_lds_dwordx4 v208, s[28:29]
	s_add_i32 m0, s34, 0x2000
	s_nop 0
	global_load_lds_dwordx4 v132, s[28:29]
	s_barrier
	s_waitcnt lgkmcnt(0)
	s_setprio 1
	v_mfma_f32_16x16x32_bf16 v[116:119], v[190:193], v[154:157], v[116:119]
	v_mfma_f32_16x16x32_bf16 v[112:115], v[198:201], v[154:157], v[112:115]
	v_mfma_f32_16x16x32_bf16 v[100:103], v[190:193], v[166:169], v[100:103]
	v_mfma_f32_16x16x32_bf16 v[96:99], v[198:201], v[166:169], v[96:99]
	v_mfma_f32_16x16x32_bf16 v[84:87], v[190:193], v[174:177], v[84:87]
	v_mfma_f32_16x16x32_bf16 v[80:83], v[198:201], v[174:177], v[80:83]
	v_mfma_f32_16x16x32_bf16 v[68:71], v[190:193], v[182:185], v[68:71]
	v_mfma_f32_16x16x32_bf16 v[64:67], v[198:201], v[182:185], v[64:67]
	v_mfma_f32_16x16x32_bf16 v[116:119], v[194:197], v[162:165], v[116:119]
	v_mfma_f32_16x16x32_bf16 v[112:115], v[202:205], v[162:165], v[112:115]
	v_mfma_f32_16x16x32_bf16 v[100:103], v[194:197], v[170:173], v[100:103]
	v_mfma_f32_16x16x32_bf16 v[96:99], v[202:205], v[170:173], v[96:99]
	v_mfma_f32_16x16x32_bf16 v[84:87], v[194:197], v[178:181], v[84:87]
	v_mfma_f32_16x16x32_bf16 v[80:83], v[202:205], v[178:181], v[80:83]
	v_mfma_f32_16x16x32_bf16 v[68:71], v[194:197], v[186:189], v[68:71]
	v_mfma_f32_16x16x32_bf16 v[64:67], v[202:205], v[186:189], v[64:67]
	s_setprio 0
	s_mov_b32 m0, s74
	s_barrier
	ds_read_b128 v[154:157], v161 offset:16384
	ds_read_b128 v[162:165], v161 offset:17408
	ds_read_b128 v[166:169], v161 offset:18432
	ds_read_b128 v[170:173], v161 offset:19456
	ds_read_b128 v[174:177], v161 offset:20480
	ds_read_b128 v[178:181], v161 offset:21504
	ds_read_b128 v[182:185], v161 offset:22528
	ds_read_b128 v[186:189], v161 offset:23552
	global_load_lds_dwordx4 v128, s[36:37]
	s_mov_b32 m0, s76
	s_nop 0
	global_load_lds_dwordx4 v130, s[36:37]
	s_barrier
	s_waitcnt lgkmcnt(0)
	s_setprio 1
	v_mfma_f32_16x16x32_bf16 v[60:63], v[138:141], v[154:157], v[60:63]
	v_mfma_f32_16x16x32_bf16 v[56:59], v[146:149], v[154:157], v[56:59]
	v_mfma_f32_16x16x32_bf16 v[44:47], v[138:141], v[166:169], v[44:47]
	v_mfma_f32_16x16x32_bf16 v[40:43], v[146:149], v[166:169], v[40:43]
	v_mfma_f32_16x16x32_bf16 v[28:31], v[138:141], v[174:177], v[28:31]
	v_mfma_f32_16x16x32_bf16 v[24:27], v[146:149], v[174:177], v[24:27]
	v_mfma_f32_16x16x32_bf16 v[12:15], v[138:141], v[182:185], v[12:15]
	v_mfma_f32_16x16x32_bf16 v[8:11], v[146:149], v[182:185], v[8:11]
	v_mfma_f32_16x16x32_bf16 v[60:63], v[142:145], v[162:165], v[60:63]
	v_mfma_f32_16x16x32_bf16 v[56:59], v[150:153], v[162:165], v[56:59]
	v_mfma_f32_16x16x32_bf16 v[44:47], v[142:145], v[170:173], v[44:47]
	v_mfma_f32_16x16x32_bf16 v[40:43], v[150:153], v[170:173], v[40:43]
	v_mfma_f32_16x16x32_bf16 v[28:31], v[142:145], v[178:181], v[28:31]
	v_mfma_f32_16x16x32_bf16 v[24:27], v[150:153], v[178:181], v[24:27]
	v_mfma_f32_16x16x32_bf16 v[12:15], v[142:145], v[186:189], v[12:15]
	v_mfma_f32_16x16x32_bf16 v[8:11], v[150:153], v[186:189], v[8:11]
	s_setprio 0
	s_barrier
	s_add_u32 s34, s28, 0x40000
	s_addc_u32 s35, s29, 0
	s_add_i32 s46, s46, s71
	s_mov_b32 m0, s46
	s_nop 0
	global_load_lds_dwordx4 v208, s[34:35]
	s_add_i32 m0, s46, 0x2000
	s_nop 0
	global_load_lds_dwordx4 v132, s[34:35]
	s_waitcnt vmcnt(6)
	s_barrier
; #define PG8_STAGE(bufoff, gbase, voff) do { _Pragma("unroll") for (int _i = 0; _i < 2; ++_i) \
;         __builtin_amdgcn_global_load_lds((const unsigned*)((const char*)(gbase) + (voff)[_i]), (LAS unsigned*)(lds + (bufoff) + ldsw + _i * 8192), 16, 0, 0); } while (0)
; #define PG8_LDA(dst, b, h) do { _Pragma("unroll") for (int m = 0; m < 4; ++m) _Pragma("unroll") for (int k = 0; k < 2; ++k) dst[m][k] = *(const LAS bf16x8*)(lds + PG8_SA(b, h) + aoff + m * 2048 + k * 1024); } while (0)
; #define PG8_LDB(dst, b, h) do { _Pragma("unroll") for (int n = 0; n < 2; ++n) _Pragma("unroll") for (int k = 0; k < 2; ++k) dst[n][k] = *(const LAS bf16x8*)(lds + PG8_SB(b, h) + boff + n * 2048 + k * 1024); } while (0)
; #define PG8_MMA(ai, bj, At, Bt) do { __builtin_amdgcn_s_setprio(1); _Pragma("unroll") for (int m = 0; m < 4; ++m) _Pragma("unroll") for (int n = 0; n < 2; ++n) _Pragma("unroll") for (int k = 0; k < 2; ++k) \
;         acc[ai][bj][m][n] = __builtin_amdgcn_mfma_f32_16x16x32_bf16(Bt[n][k], At[m][k], acc[ai][bj][m][n], 0, 0, 0); __builtin_amdgcn_s_setprio(0); } while (0)
; #define PG8_WAIT_V(n) asm volatile("s_waitcnt vmcnt(" #n ")" ::: "memory")
; #define PG8_WAIT_L(n) asm volatile("s_waitcnt lgkmcnt(" #n ")" ::: "memory")
; #define PG8_BAR __builtin_amdgcn_s_barrier()
; #define PG8_SCHED __builtin_amdgcn_sched_barrier(0)
; template <class Epi>
; __device__ __forceinline__ void gemm_phase(LAS unsigned char* lds, const Gemm g, const Epi& E) {
;     ...
;             PG8_WAIT_V(6); PG8_BAR; PG8_MMA(1, 1, At, B1); PG8_BAR;
;             PG8_LDB(B0, 1, 0); PG8_SCHED; PG8_LDA(At, 1, 0); PG8_STAGE(PG8_SA(0, 1), a2 + hstep, voffA);
;             PG8_WAIT_L(8); PG8_BAR; PG8_WAIT_L(0); PG8_MMA(0, 0, At, B0); PG8_BAR; PG8_SCHED;
;             PG8_LDB(B1, 1, 1); PG8_STAGE(PG8_SB(1, 0), b3, voffB);
;             PG8_BAR; PG8_WAIT_L(0); PG8_MMA(0, 1, At, B1); PG8_BAR;
;             PG8_LDA(At, 1, 1); PG8_STAGE(PG8_SA(1, 0), a3, voffA);
;             PG8_BAR; PG8_WAIT_L(0); PG8_MMA(1, 0, At, B0); PG8_BAR; PG8_SCHED;
;             PG8_STAGE(PG8_SB(1, 1), b3 + hstep, voffB);
	s_setprio 1
	v_mfma_f32_16x16x32_bf16 v[52:55], v[190:193], v[154:157], v[52:55]
	v_mfma_f32_16x16x32_bf16 v[48:51], v[198:201], v[154:157], v[48:51]
	v_mfma_f32_16x16x32_bf16 v[36:39], v[190:193], v[166:169], v[36:39]
	v_mfma_f32_16x16x32_bf16 v[32:35], v[198:201], v[166:169], v[32:35]
	v_mfma_f32_16x16x32_bf16 v[20:23], v[190:193], v[174:177], v[20:23]
	v_mfma_f32_16x16x32_bf16 v[16:19], v[198:201], v[174:177], v[16:19]
	v_mfma_f32_16x16x32_bf16 v[4:7], v[190:193], v[182:185], v[4:7]
	v_mfma_f32_16x16x32_bf16 v[0:3], v[198:201], v[182:185], v[0:3]
	v_mfma_f32_16x16x32_bf16 v[52:55], v[194:197], v[162:165], v[52:55]
	v_mfma_f32_16x16x32_bf16 v[48:51], v[202:205], v[162:165], v[48:51]
	v_mfma_f32_16x16x32_bf16 v[36:39], v[194:197], v[170:173], v[36:39]
	v_mfma_f32_16x16x32_bf16 v[32:35], v[202:205], v[170:173], v[32:35]
	v_mfma_f32_16x16x32_bf16 v[20:23], v[194:197], v[178:181], v[20:23]
	v_mfma_f32_16x16x32_bf16 v[16:19], v[202:205], v[178:181], v[16:19]
	v_mfma_f32_16x16x32_bf16 v[4:7], v[194:197], v[186:189], v[4:7]
	v_mfma_f32_16x16x32_bf16 v[0:3], v[202:205], v[186:189], v[0:3]
	s_setprio 0
	s_add_i32 s46, 0, 0x18000
	v_add_u32_e32 v150, s46, v159
	s_barrier
	ds_read_b128 v[138:141], v150
	ds_read_b128 v[142:145], v150 offset:1024
	ds_read_b128 v[146:149], v150 offset:2048
	ds_read_b128 v[150:153], v150 offset:3072
	s_add_u32 s34, s36, 0x40000
	s_addc_u32 s35, s37, 0
	s_mov_b32 m0, s78
	ds_read_b128 v[154:157], v161 offset:32768
	ds_read_b128 v[162:165], v161 offset:33792
	ds_read_b128 v[166:169], v161 offset:34816
	ds_read_b128 v[170:173], v161 offset:35840
	ds_read_b128 v[174:177], v161 offset:36864
	ds_read_b128 v[178:181], v161 offset:37888
	ds_read_b128 v[182:185], v161 offset:38912
	ds_read_b128 v[186:189], v161 offset:39936
	global_load_lds_dwordx4 v128, s[34:35]
	s_mov_b32 m0, s79
	s_nop 0
	global_load_lds_dwordx4 v130, s[34:35]
	s_waitcnt lgkmcnt(8)
	s_barrier
	s_waitcnt lgkmcnt(0)
	s_setprio 1
	v_mfma_f32_16x16x32_bf16 v[124:127], v[138:141], v[154:157], v[124:127]
	v_mfma_f32_16x16x32_bf16 v[120:123], v[146:149], v[154:157], v[120:123]
	v_mfma_f32_16x16x32_bf16 v[108:111], v[138:141], v[166:169], v[108:111]
	v_mfma_f32_16x16x32_bf16 v[104:107], v[146:149], v[166:169], v[104:107]
	v_mfma_f32_16x16x32_bf16 v[92:95], v[138:141], v[174:177], v[92:95]
	v_mfma_f32_16x16x32_bf16 v[88:91], v[146:149], v[174:177], v[88:91]
	v_mfma_f32_16x16x32_bf16 v[76:79], v[138:141], v[182:185], v[76:79]
	v_mfma_f32_16x16x32_bf16 v[72:75], v[146:149], v[182:185], v[72:75]
	v_mfma_f32_16x16x32_bf16 v[124:127], v[142:145], v[162:165], v[124:127]
	v_mfma_f32_16x16x32_bf16 v[120:123], v[150:153], v[162:165], v[120:123]
	v_mfma_f32_16x16x32_bf16 v[108:111], v[142:145], v[170:173], v[108:111]
	v_mfma_f32_16x16x32_bf16 v[104:107], v[150:153], v[170:173], v[104:107]
	v_mfma_f32_16x16x32_bf16 v[92:95], v[142:145], v[178:181], v[92:95]
	v_mfma_f32_16x16x32_bf16 v[88:91], v[150:153], v[178:181], v[88:91]
	v_mfma_f32_16x16x32_bf16 v[76:79], v[142:145], v[186:189], v[76:79]
	v_mfma_f32_16x16x32_bf16 v[72:75], v[150:153], v[186:189], v[72:75]
	s_setprio 0
	s_barrier
	s_add_i32 s34, 0, 0x1c000
	s_add_i32 s35, s46, s71
	v_add_u32_e32 v202, s34, v159
	s_mov_b32 m0, s35
	ds_read_b128 v[190:193], v202
	ds_read_b128 v[194:197], v202 offset:1024
	ds_read_b128 v[198:201], v202 offset:2048
	ds_read_b128 v[202:205], v202 offset:3072
	s_add_u32 s98, s28, 0x80
	s_addc_u32 s99, s29, 0
	global_load_lds_dwordx4 v208, s[98:99]
	s_add_i32 m0, s35, 0x2000
	s_add_u32 s100, s28, 0x80
	s_addc_u32 s101, s29, 0
	global_load_lds_dwordx4 v132, s[100:101]
	s_barrier
	s_waitcnt lgkmcnt(0)
	s_setprio 1
	v_mfma_f32_16x16x32_bf16 v[116:119], v[190:193], v[154:157], v[116:119]
	v_mfma_f32_16x16x32_bf16 v[112:115], v[198:201], v[154:157], v[112:115]
	v_mfma_f32_16x16x32_bf16 v[100:103], v[190:193], v[166:169], v[100:103]
	v_mfma_f32_16x16x32_bf16 v[96:99], v[198:201], v[166:169], v[96:99]
	v_mfma_f32_16x16x32_bf16 v[84:87], v[190:193], v[174:177], v[84:87]
	v_mfma_f32_16x16x32_bf16 v[80:83], v[198:201], v[174:177], v[80:83]
	v_mfma_f32_16x16x32_bf16 v[68:71], v[190:193], v[182:185], v[68:71]
	v_mfma_f32_16x16x32_bf16 v[64:67], v[198:201], v[182:185], v[64:67]
	v_mfma_f32_16x16x32_bf16 v[116:119], v[194:197], v[162:165], v[116:119]
	v_mfma_f32_16x16x32_bf16 v[112:115], v[202:205], v[162:165], v[112:115]
	v_mfma_f32_16x16x32_bf16 v[100:103], v[194:197], v[170:173], v[100:103]
	v_mfma_f32_16x16x32_bf16 v[96:99], v[202:205], v[170:173], v[96:99]
	v_mfma_f32_16x16x32_bf16 v[84:87], v[194:197], v[178:181], v[84:87]
	v_mfma_f32_16x16x32_bf16 v[80:83], v[202:205], v[178:181], v[80:83]
	v_mfma_f32_16x16x32_bf16 v[68:71], v[194:197], v[186:189], v[68:71]
	v_mfma_f32_16x16x32_bf16 v[64:67], v[202:205], v[186:189], v[64:67]
	s_setprio 0
	s_mov_b32 m0, s82
	s_barrier
	ds_read_b128 v[154:157], v161 offset:49152
	ds_read_b128 v[162:165], v161 offset:50176
	ds_read_b128 v[166:169], v161 offset:51200
	ds_read_b128 v[170:173], v161 offset:52224
	ds_read_b128 v[174:177], v161 offset:53248
	ds_read_b128 v[178:181], v161 offset:54272
	ds_read_b128 v[182:185], v161 offset:55296
	ds_read_b128 v[186:189], v161 offset:56320
	s_add_u32 s98, s36, 0x80
	s_addc_u32 s99, s37, 0
	global_load_lds_dwordx4 v128, s[98:99]
	s_mov_b32 m0, s83
	s_add_u32 s100, s36, 0x80
	s_addc_u32 s101, s37, 0
	global_load_lds_dwordx4 v130, s[100:101]
	s_barrier
; __device__ __forceinline__ float bflo(unsigned w) { return __uint_as_float(w << 16); }
; __device__ __forceinline__ float bfhi(unsigned w) { return __uint_as_float(w & 0xffff0000u); }
; __device__ __forceinline__ u32x4 pack8u(f32x4 a, f32x4 b) { u32x4 w = {cvt_pk_bf16(a[0], a[1]), cvt_pk_bf16(a[2], a[3]), cvt_pk_bf16(b[0], b[1]), cvt_pk_bf16(b[2], b[3])}; return w; }
; #define PG8_STAGE(bufoff, gbase, voff) do { _Pragma("unroll") for (int _i = 0; _i < 2; ++_i) \
;         __builtin_amdgcn_global_load_lds((const unsigned*)((const char*)(gbase) + (voff)[_i]), (LAS unsigned*)(lds + (bufoff) + ldsw + _i * 8192), 16, 0, 0); } while (0)
; #define PG8_MMA(ai, bj, At, Bt) do { __builtin_amdgcn_s_setprio(1); _Pragma("unroll") for (int m = 0; m < 4; ++m) _Pragma("unroll") for (int n = 0; n < 2; ++n) _Pragma("unroll") for (int k = 0; k < 2; ++k) \
;         acc[ai][bj][m][n] = __builtin_amdgcn_mfma_f32_16x16x32_bf16(Bt[n][k], At[m][k], acc[ai][bj][m][n], 0, 0, 0); __builtin_amdgcn_s_setprio(0); } while (0)
; #define PG8_WAIT_V(n) asm volatile("s_waitcnt vmcnt(" #n ")" ::: "memory")
; #define PG8_BAR __builtin_amdgcn_s_barrier()
; template <class Epi>
; __device__ __forceinline__ void gemm_phase(LAS unsigned char* lds, const Gemm g, const Epi& E) {
;     ...
;             PG8_BAR; PG8_WAIT_L(0); PG8_MMA(1, 0, At, B0); PG8_BAR; PG8_SCHED;
;             PG8_STAGE(PG8_SB(1, 1), b3 + hstep, voffB);
;             PG8_WAIT_V(6); PG8_BAR; PG8_MMA(1, 1, At, B1); PG8_BAR;
;     __device__ __forceinline__ void operator()(const AccT& acc, const Unit& u, int wr, int wc, int fr, int fq) const {
; #pragma unroll
;         for (int ai = 0; ai < 2; ++ai)
; #pragma unroll
;             for (int m = 0; m < 4; ++m) {
;                 const int row = u.pm * 256 + ai * 128 + wr * 64 + m * 16 + fr;
; #pragma unroll
;                 for (int bj = 0; bj < 2; ++bj) {
;                     const int c8 = u.pn * 256 + bj * 128 + wc * 32 + fq * 8;
;                     const u32x4 gw = *(const u32x4*)(GATE + (size_t)row * 4096 + SECOND * 2048 + c8);
;                     const f32x4 g0 = {bflo(gw[0]), bfhi(gw[0]), bflo(gw[1]), bfhi(gw[1])}, g1 = {bflo(gw[2]), bfhi(gw[2]), bflo(gw[3]), bfhi(gw[3])};
;                     bf16_t* tp = (bf16_t*)TMP + (size_t)row * 2048 + c8;
;                     if (SECOND == 0) { *(u32x4*)tp = pack8u(g0 * acc[ai][bj][m][0], g1 * acc[ai][bj][m][1]); }
	s_waitcnt lgkmcnt(0)
	s_setprio 1
	v_mfma_f32_16x16x32_bf16 v[60:63], v[138:141], v[154:157], v[60:63]
	v_mfma_f32_16x16x32_bf16 v[56:59], v[146:149], v[154:157], v[56:59]
	v_mfma_f32_16x16x32_bf16 v[44:47], v[138:141], v[166:169], v[44:47]
	v_mfma_f32_16x16x32_bf16 v[40:43], v[146:149], v[166:169], v[40:43]
	v_mfma_f32_16x16x32_bf16 v[28:31], v[138:141], v[174:177], v[28:31]
	v_mfma_f32_16x16x32_bf16 v[24:27], v[146:149], v[174:177], v[24:27]
	v_mfma_f32_16x16x32_bf16 v[12:15], v[138:141], v[182:185], v[12:15]
	v_mfma_f32_16x16x32_bf16 v[8:11], v[146:149], v[182:185], v[8:11]
	v_mfma_f32_16x16x32_bf16 v[60:63], v[142:145], v[162:165], v[60:63]
	v_mfma_f32_16x16x32_bf16 v[56:59], v[150:153], v[162:165], v[56:59]
	v_mfma_f32_16x16x32_bf16 v[44:47], v[142:145], v[170:173], v[44:47]
	v_mfma_f32_16x16x32_bf16 v[40:43], v[150:153], v[170:173], v[40:43]
	v_mfma_f32_16x16x32_bf16 v[28:31], v[142:145], v[178:181], v[28:31]
	v_mfma_f32_16x16x32_bf16 v[24:27], v[150:153], v[178:181], v[24:27]
	v_mfma_f32_16x16x32_bf16 v[12:15], v[142:145], v[186:189], v[12:15]
	v_mfma_f32_16x16x32_bf16 v[8:11], v[150:153], v[186:189], v[8:11]
	s_setprio 0
	s_barrier
	s_add_u32 s28, s28, 0x40080
	s_addc_u32 s29, s29, 0
	s_add_i32 s34, s34, s71
	s_mov_b32 m0, s34
	s_nop 0
	global_load_lds_dwordx4 v208, s[28:29]
	s_add_i32 m0, s34, 0x2000
	s_nop 0
	global_load_lds_dwordx4 v132, s[28:29]
	s_waitcnt vmcnt(6)
	s_barrier
	s_setprio 1
	v_mfma_f32_16x16x32_bf16 v[52:55], v[190:193], v[154:157], v[52:55]
	v_mfma_f32_16x16x32_bf16 v[48:51], v[198:201], v[154:157], v[48:51]
	v_mfma_f32_16x16x32_bf16 v[36:39], v[190:193], v[166:169], v[36:39]
	v_mfma_f32_16x16x32_bf16 v[32:35], v[198:201], v[166:169], v[32:35]
	v_mfma_f32_16x16x32_bf16 v[20:23], v[190:193], v[174:177], v[20:23]
	v_mfma_f32_16x16x32_bf16 v[16:19], v[198:201], v[174:177], v[16:19]
	v_mfma_f32_16x16x32_bf16 v[4:7], v[190:193], v[182:185], v[4:7]
	v_mfma_f32_16x16x32_bf16 v[0:3], v[198:201], v[182:185], v[0:3]
	v_mfma_f32_16x16x32_bf16 v[52:55], v[194:197], v[162:165], v[52:55]
	v_mfma_f32_16x16x32_bf16 v[48:51], v[202:205], v[162:165], v[48:51]
	v_mfma_f32_16x16x32_bf16 v[36:39], v[194:197], v[170:173], v[36:39]
	v_mfma_f32_16x16x32_bf16 v[32:35], v[202:205], v[170:173], v[32:35]
	v_mfma_f32_16x16x32_bf16 v[20:23], v[194:197], v[178:181], v[20:23]
	v_mfma_f32_16x16x32_bf16 v[16:19], v[202:205], v[178:181], v[16:19]
	v_mfma_f32_16x16x32_bf16 v[4:7], v[194:197], v[186:189], v[4:7]
	v_mfma_f32_16x16x32_bf16 v[0:3], v[202:205], v[186:189], v[0:3]
	s_setprio 0
	s_add_i32 vcc_hi, vcc_hi, 2
	s_add_u32 s26, s26, 0x100
	s_addc_u32 s27, s27, 0
	s_add_u32 s65, s65, 0x100
	s_addc_u32 vcc_lo, vcc_lo, 0
	s_cmp_gt_u32 vcc_hi, 13
	s_barrier
	s_cbranch_scc0 .LBB0_211
	v_lshl_add_u32 v140, s42, 8, v158
	v_lshl_or_b32 v141, s96, 8, v160
	v_lshlrev_b32_e32 v141, 1, v141
	v_lshl_add_u32 v138, v140, 13, v141
	v_lshl_add_u32 v139, v140, 12, v141
	s_and_b64 vcc, exec, s[0:1]
	s_cbranch_vccnz .Lepo_second
	v_add_u32_e32 v140, 0x0, v138
	global_load_dwordx4 v[162:165], v140, s[44:45]
	v_add_u32_e32 v140, 0x0, v138
	global_load_dwordx4 v[166:169], v140, s[44:45] offset:256
	v_add_u32_e32 v140, 0x20000, v138
	global_load_dwordx4 v[170:173], v140, s[44:45]
	v_add_u32_e32 v140, 0x20000, v138
	global_load_dwordx4 v[174:177], v140, s[44:45] offset:256
	v_add_u32_e32 v140, 0x40000, v138
	global_load_dwordx4 v[178:181], v140, s[44:45]
	v_add_u32_e32 v140, 0x40000, v138
	global_load_dwordx4 v[182:185], v140, s[44:45] offset:256
	v_add_u32_e32 v140, 0x60000, v138
	global_load_dwordx4 v[186:189], v140, s[44:45]
	v_add_u32_e32 v140, 0x60000, v138
	global_load_dwordx4 v[190:193], v140, s[44:45] offset:256
	v_add_u32_e32 v140, 0x100000, v138
	global_load_dwordx4 v[194:197], v140, s[44:45]
	v_add_u32_e32 v140, 0x100000, v138
	global_load_dwordx4 v[198:201], v140, s[44:45] offset:256
	v_add_u32_e32 v140, 0x120000, v138
	global_load_dwordx4 v[202:205], v140, s[44:45]
	v_add_u32_e32 v140, 0x120000, v138
	global_load_dwordx4 v[228:231], v140, s[44:45] offset:256
	s_waitcnt vmcnt(11)
	v_lshlrev_b32_e32 v142, 16, v162
	v_and_b32_e32 v143, 0xffff0000, v162
	v_lshlrev_b32_e32 v144, 16, v163
	v_and_b32_e32 v145, 0xffff0000, v163
	v_lshlrev_b32_e32 v146, 16, v164
	v_and_b32_e32 v147, 0xffff0000, v164
	v_lshlrev_b32_e32 v148, 16, v165
	v_and_b32_e32 v149, 0xffff0000, v165
	v_pk_mul_f32 v[124:125], v[124:125], v[142:143]
	v_pk_mul_f32 v[126:127], v[126:127], v[144:145]
	v_pk_mul_f32 v[120:121], v[120:121], v[146:147]
	v_pk_mul_f32 v[122:123], v[122:123], v[148:149]
	v_cvt_pk_bf16_f32 v124, v124, v125
	v_cvt_pk_bf16_f32 v125, v126, v127
	v_cvt_pk_bf16_f32 v126, v120, v121
	v_cvt_pk_bf16_f32 v127, v122, v123
	v_add_u32_e32 v141, 0x0, v139
	global_store_dwordx4 v141, v[124:127], s[92:93]
	v_add_u32_e32 v140, 0x140000, v138
	global_load_dwordx4 v[162:165], v140, s[44:45]
	v_add_u32_e32 v140, 0x140000, v138
	global_load_dwordx4 v[120:123], v140, s[44:45] offset:256
	s_waitcnt vmcnt(13)
	v_lshlrev_b32_e32 v142, 16, v166
	v_and_b32_e32 v143, 0xffff0000, v166
	v_lshlrev_b32_e32 v144, 16, v167
	v_and_b32_e32 v145, 0xffff0000, v167
	v_lshlrev_b32_e32 v146, 16, v168
	v_and_b32_e32 v147, 0xffff0000, v168
	v_lshlrev_b32_e32 v148, 16, v169
	v_and_b32_e32 v149, 0xffff0000, v169
	v_pk_mul_f32 v[116:117], v[116:117], v[142:143]
	v_pk_mul_f32 v[118:119], v[118:119], v[144:145]
	v_pk_mul_f32 v[112:113], v[112:113], v[146:147]
	v_pk_mul_f32 v[114:115], v[114:115], v[148:149]
	v_cvt_pk_bf16_f32 v116, v116, v117
	v_cvt_pk_bf16_f32 v117, v118, v119
	v_cvt_pk_bf16_f32 v118, v112, v113
	v_cvt_pk_bf16_f32 v119, v114, v115
	v_add_u32_e32 v141, 0x0, v139
	global_store_dwordx4 v141, v[116:119], s[92:93] offset:256
	v_add_u32_e32 v140, 0x160000, v138
	global_load_dwordx4 v[166:169], v140, s[44:45]
	v_add_u32_e32 v140, 0x160000, v138
	global_load_dwordx4 v[112:115], v140, s[44:45] offset:256
	s_waitcnt vmcnt(15)
; __device__ __forceinline__ float bflo(unsigned w) { return __uint_as_float(w << 16); }
; __device__ __forceinline__ float bfhi(unsigned w) { return __uint_as_float(w & 0xffff0000u); }
; __device__ __forceinline__ u32x4 pack8u(f32x4 a, f32x4 b) { u32x4 w = {cvt_pk_bf16(a[0], a[1]), cvt_pk_bf16(a[2], a[3]), cvt_pk_bf16(b[0], b[1]), cvt_pk_bf16(b[2], b[3])}; return w; }
;     __device__ __forceinline__ void operator()(const AccT& acc, const Unit& u, int wr, int wc, int fr, int fq) const {
;     ...
; #pragma unroll
;                 for (int bj = 0; bj < 2; ++bj) {
;                     const int c8 = u.pn * 256 + bj * 128 + wc * 32 + fq * 8;
;                     const u32x4 gw = *(const u32x4*)(GATE + (size_t)row * 4096 + SECOND * 2048 + c8);
;                     const f32x4 g0 = {bflo(gw[0]), bfhi(gw[0]), bflo(gw[1]), bfhi(gw[1])}, g1 = {bflo(gw[2]), bfhi(gw[2]), bflo(gw[3]), bfhi(gw[3])};
;                     bf16_t* tp = (bf16_t*)TMP + (size_t)row * 2048 + c8;
;                     if (SECOND == 0) { *(u32x4*)tp = pack8u(g0 * acc[ai][bj][m][0], g1 * acc[ai][bj][m][1]); }
	v_lshlrev_b32_e32 v142, 16, v170
	v_and_b32_e32 v143, 0xffff0000, v170
	v_lshlrev_b32_e32 v144, 16, v171
	v_and_b32_e32 v145, 0xffff0000, v171
	v_lshlrev_b32_e32 v146, 16, v172
	v_and_b32_e32 v147, 0xffff0000, v172
	v_lshlrev_b32_e32 v148, 16, v173
	v_and_b32_e32 v149, 0xffff0000, v173
	v_pk_mul_f32 v[108:109], v[108:109], v[142:143]
	v_pk_mul_f32 v[110:111], v[110:111], v[144:145]
	v_pk_mul_f32 v[104:105], v[104:105], v[146:147]
	v_pk_mul_f32 v[106:107], v[106:107], v[148:149]
	v_cvt_pk_bf16_f32 v108, v108, v109
	v_cvt_pk_bf16_f32 v109, v110, v111
	v_cvt_pk_bf16_f32 v110, v104, v105
	v_cvt_pk_bf16_f32 v111, v106, v107
	v_add_u32_e32 v141, 0x10000, v139
	global_store_dwordx4 v141, v[108:111], s[92:93]
	s_waitcnt vmcnt(15)
	v_lshlrev_b32_e32 v142, 16, v174
	v_and_b32_e32 v143, 0xffff0000, v174
	v_lshlrev_b32_e32 v144, 16, v175
	v_and_b32_e32 v145, 0xffff0000, v175
	v_lshlrev_b32_e32 v146, 16, v176
	v_and_b32_e32 v147, 0xffff0000, v176
	v_lshlrev_b32_e32 v148, 16, v177
	v_and_b32_e32 v149, 0xffff0000, v177
	v_pk_mul_f32 v[100:101], v[100:101], v[142:143]
	v_pk_mul_f32 v[102:103], v[102:103], v[144:145]
	v_pk_mul_f32 v[96:97], v[96:97], v[146:147]
	v_pk_mul_f32 v[98:99], v[98:99], v[148:149]
	v_cvt_pk_bf16_f32 v100, v100, v101
	v_cvt_pk_bf16_f32 v101, v102, v103
	v_cvt_pk_bf16_f32 v102, v96, v97
	v_cvt_pk_bf16_f32 v103, v98, v99
	v_add_u32_e32 v141, 0x10000, v139
	global_store_dwordx4 v141, v[100:103], s[92:93] offset:256
	s_waitcnt vmcnt(15)
	v_lshlrev_b32_e32 v142, 16, v178
	v_and_b32_e32 v143, 0xffff0000, v178
	v_lshlrev_b32_e32 v144, 16, v179
	v_and_b32_e32 v145, 0xffff0000, v179
	v_lshlrev_b32_e32 v146, 16, v180
	v_and_b32_e32 v147, 0xffff0000, v180
	v_lshlrev_b32_e32 v148, 16, v181
	v_and_b32_e32 v149, 0xffff0000, v181
	v_pk_mul_f32 v[92:93], v[92:93], v[142:143]
	v_pk_mul_f32 v[94:95], v[94:95], v[144:145]
	v_pk_mul_f32 v[88:89], v[88:89], v[146:147]
	v_pk_mul_f32 v[90:91], v[90:91], v[148:149]
	v_cvt_pk_bf16_f32 v92, v92, v93
	v_cvt_pk_bf16_f32 v93, v94, v95
	v_cvt_pk_bf16_f32 v94, v88, v89
	v_cvt_pk_bf16_f32 v95, v90, v91
	v_add_u32_e32 v141, 0x20000, v139
	global_store_dwordx4 v141, v[92:95], s[92:93]
	s_waitcnt vmcnt(15)
	v_lshlrev_b32_e32 v142, 16, v182
	v_and_b32_e32 v143, 0xffff0000, v182
	v_lshlrev_b32_e32 v144, 16, v183
	v_and_b32_e32 v145, 0xffff0000, v183
	v_lshlrev_b32_e32 v146, 16, v184
	v_and_b32_e32 v147, 0xffff0000, v184
	v_lshlrev_b32_e32 v148, 16, v185
	v_and_b32_e32 v149, 0xffff0000, v185
	v_pk_mul_f32 v[84:85], v[84:85], v[142:143]
	v_pk_mul_f32 v[86:87], v[86:87], v[144:145]
	v_pk_mul_f32 v[80:81], v[80:81], v[146:147]
	v_pk_mul_f32 v[82:83], v[82:83], v[148:149]
	v_cvt_pk_bf16_f32 v84, v84, v85
	v_cvt_pk_bf16_f32 v85, v86, v87
	v_cvt_pk_bf16_f32 v86, v80, v81
	v_cvt_pk_bf16_f32 v87, v82, v83
	v_add_u32_e32 v141, 0x20000, v139
	global_store_dwordx4 v141, v[84:87], s[92:93] offset:256
	s_waitcnt vmcnt(15)
	v_lshlrev_b32_e32 v142, 16, v186
	v_and_b32_e32 v143, 0xffff0000, v186
	v_lshlrev_b32_e32 v144, 16, v187
	v_and_b32_e32 v145, 0xffff0000, v187
	v_lshlrev_b32_e32 v146, 16, v188
	v_and_b32_e32 v147, 0xffff0000, v188
	v_lshlrev_b32_e32 v148, 16, v189
	v_and_b32_e32 v149, 0xffff0000, v189
	v_pk_mul_f32 v[76:77], v[76:77], v[142:143]
	v_pk_mul_f32 v[78:79], v[78:79], v[144:145]
	v_pk_mul_f32 v[72:73], v[72:73], v[146:147]
	v_pk_mul_f32 v[74:75], v[74:75], v[148:149]
	v_cvt_pk_bf16_f32 v76, v76, v77
	v_cvt_pk_bf16_f32 v77, v78, v79
	v_cvt_pk_bf16_f32 v78, v72, v73
	v_cvt_pk_bf16_f32 v79, v74, v75
	v_add_u32_e32 v141, 0x30000, v139
	global_store_dwordx4 v141, v[76:79], s[92:93]
	s_waitcnt vmcnt(15)
	v_lshlrev_b32_e32 v142, 16, v190
	v_and_b32_e32 v143, 0xffff0000, v190
	v_lshlrev_b32_e32 v144, 16, v191
	v_and_b32_e32 v145, 0xffff0000, v191
	v_lshlrev_b32_e32 v146, 16, v192
	v_and_b32_e32 v147, 0xffff0000, v192
	v_lshlrev_b32_e32 v148, 16, v193
	v_and_b32_e32 v149, 0xffff0000, v193
	v_pk_mul_f32 v[68:69], v[68:69], v[142:143]
	v_pk_mul_f32 v[70:71], v[70:71], v[144:145]
	v_pk_mul_f32 v[64:65], v[64:65], v[146:147]
	v_pk_mul_f32 v[66:67], v[66:67], v[148:149]
	v_cvt_pk_bf16_f32 v68, v68, v69
	v_cvt_pk_bf16_f32 v69, v70, v71
	v_cvt_pk_bf16_f32 v70, v64, v65
	v_cvt_pk_bf16_f32 v71, v66, v67
	v_add_u32_e32 v141, 0x30000, v139
	global_store_dwordx4 v141, v[68:71], s[92:93] offset:256
	s_waitcnt vmcnt(15)
	v_lshlrev_b32_e32 v142, 16, v194
	v_and_b32_e32 v143, 0xffff0000, v194
	v_lshlrev_b32_e32 v144, 16, v195
	v_and_b32_e32 v145, 0xffff0000, v195
	v_lshlrev_b32_e32 v146, 16, v196
	v_and_b32_e32 v147, 0xffff0000, v196
	v_lshlrev_b32_e32 v148, 16, v197
	v_and_b32_e32 v149, 0xffff0000, v197
	v_pk_mul_f32 v[60:61], v[60:61], v[142:143]
	v_pk_mul_f32 v[62:63], v[62:63], v[144:145]
	v_pk_mul_f32 v[56:57], v[56:57], v[146:147]
	v_pk_mul_f32 v[58:59], v[58:59], v[148:149]
	v_cvt_pk_bf16_f32 v60, v60, v61
	v_cvt_pk_bf16_f32 v61, v62, v63
	v_cvt_pk_bf16_f32 v62, v56, v57
	v_cvt_pk_bf16_f32 v63, v58, v59
	v_add_u32_e32 v141, 0x80000, v139
	global_store_dwordx4 v141, v[60:63], s[92:93]
	s_waitcnt vmcnt(15)
; __device__ __forceinline__ float bflo(unsigned w) { return __uint_as_float(w << 16); }
; __device__ __forceinline__ float bfhi(unsigned w) { return __uint_as_float(w & 0xffff0000u); }
; __device__ __forceinline__ u32x4 pack8u(f32x4 a, f32x4 b) { u32x4 w = {cvt_pk_bf16(a[0], a[1]), cvt_pk_bf16(a[2], a[3]), cvt_pk_bf16(b[0], b[1]), cvt_pk_bf16(b[2], b[3])}; return w; }
;     __device__ __forceinline__ void operator()(const AccT& acc, const Unit& u, int wr, int wc, int fr, int fq) const {
;     ...
; #pragma unroll
;                 for (int bj = 0; bj < 2; ++bj) {
;                     const int c8 = u.pn * 256 + bj * 128 + wc * 32 + fq * 8;
;                     const u32x4 gw = *(const u32x4*)(GATE + (size_t)row * 4096 + SECOND * 2048 + c8);
;                     const f32x4 g0 = {bflo(gw[0]), bfhi(gw[0]), bflo(gw[1]), bfhi(gw[1])}, g1 = {bflo(gw[2]), bfhi(gw[2]), bflo(gw[3]), bfhi(gw[3])};
;                     bf16_t* tp = (bf16_t*)TMP + (size_t)row * 2048 + c8;
;                     if (SECOND == 0) { *(u32x4*)tp = pack8u(g0 * acc[ai][bj][m][0], g1 * acc[ai][bj][m][1]); }
	v_lshlrev_b32_e32 v142, 16, v198
	v_and_b32_e32 v143, 0xffff0000, v198
	v_lshlrev_b32_e32 v144, 16, v199
	v_and_b32_e32 v145, 0xffff0000, v199
	v_lshlrev_b32_e32 v146, 16, v200
	v_and_b32_e32 v147, 0xffff0000, v200
	v_lshlrev_b32_e32 v148, 16, v201
	v_and_b32_e32 v149, 0xffff0000, v201
	v_pk_mul_f32 v[52:53], v[52:53], v[142:143]
	v_pk_mul_f32 v[54:55], v[54:55], v[144:145]
	v_pk_mul_f32 v[48:49], v[48:49], v[146:147]
	v_pk_mul_f32 v[50:51], v[50:51], v[148:149]
	v_cvt_pk_bf16_f32 v52, v52, v53
	v_cvt_pk_bf16_f32 v53, v54, v55
	v_cvt_pk_bf16_f32 v54, v48, v49
	v_cvt_pk_bf16_f32 v55, v50, v51
	v_add_u32_e32 v141, 0x80000, v139
	global_store_dwordx4 v141, v[52:55], s[92:93] offset:256
	s_waitcnt vmcnt(15)
	v_lshlrev_b32_e32 v142, 16, v202
	v_and_b32_e32 v143, 0xffff0000, v202
	v_lshlrev_b32_e32 v144, 16, v203
	v_and_b32_e32 v145, 0xffff0000, v203
	v_lshlrev_b32_e32 v146, 16, v204
	v_and_b32_e32 v147, 0xffff0000, v204
	v_lshlrev_b32_e32 v148, 16, v205
	v_and_b32_e32 v149, 0xffff0000, v205
	v_pk_mul_f32 v[44:45], v[44:45], v[142:143]
	v_pk_mul_f32 v[46:47], v[46:47], v[144:145]
	v_pk_mul_f32 v[40:41], v[40:41], v[146:147]
	v_pk_mul_f32 v[42:43], v[42:43], v[148:149]
	v_cvt_pk_bf16_f32 v44, v44, v45
	v_cvt_pk_bf16_f32 v45, v46, v47
	v_cvt_pk_bf16_f32 v46, v40, v41
	v_cvt_pk_bf16_f32 v47, v42, v43
	v_add_u32_e32 v141, 0x90000, v139
	global_store_dwordx4 v141, v[44:47], s[92:93]
	s_waitcnt vmcnt(15)
	v_lshlrev_b32_e32 v142, 16, v228
	v_and_b32_e32 v143, 0xffff0000, v228
	v_lshlrev_b32_e32 v144, 16, v229
	v_and_b32_e32 v145, 0xffff0000, v229
	v_lshlrev_b32_e32 v146, 16, v230
	v_and_b32_e32 v147, 0xffff0000, v230
	v_lshlrev_b32_e32 v148, 16, v231
	v_and_b32_e32 v149, 0xffff0000, v231
	v_pk_mul_f32 v[36:37], v[36:37], v[142:143]
	v_pk_mul_f32 v[38:39], v[38:39], v[144:145]
	v_pk_mul_f32 v[32:33], v[32:33], v[146:147]
	v_pk_mul_f32 v[34:35], v[34:35], v[148:149]
	v_cvt_pk_bf16_f32 v36, v36, v37
	v_cvt_pk_bf16_f32 v37, v38, v39
	v_cvt_pk_bf16_f32 v38, v32, v33
	v_cvt_pk_bf16_f32 v39, v34, v35
	v_add_u32_e32 v141, 0x90000, v139
	global_store_dwordx4 v141, v[36:39], s[92:93] offset:256
	s_waitcnt vmcnt(14)
	v_lshlrev_b32_e32 v142, 16, v162
	v_and_b32_e32 v143, 0xffff0000, v162
	v_lshlrev_b32_e32 v144, 16, v163
	v_and_b32_e32 v145, 0xffff0000, v163
	v_lshlrev_b32_e32 v146, 16, v164
	v_and_b32_e32 v147, 0xffff0000, v164
	v_lshlrev_b32_e32 v148, 16, v165
	v_and_b32_e32 v149, 0xffff0000, v165
	v_pk_mul_f32 v[28:29], v[28:29], v[142:143]
	v_pk_mul_f32 v[30:31], v[30:31], v[144:145]
	v_pk_mul_f32 v[24:25], v[24:25], v[146:147]
	v_pk_mul_f32 v[26:27], v[26:27], v[148:149]
	v_cvt_pk_bf16_f32 v28, v28, v29
	v_cvt_pk_bf16_f32 v29, v30, v31
	v_cvt_pk_bf16_f32 v30, v24, v25
	v_cvt_pk_bf16_f32 v31, v26, v27
	v_add_u32_e32 v141, 0xa0000, v139
	global_store_dwordx4 v141, v[28:31], s[92:93]
	s_waitcnt vmcnt(14)
	v_lshlrev_b32_e32 v142, 16, v120
	v_and_b32_e32 v143, 0xffff0000, v120
	v_lshlrev_b32_e32 v144, 16, v121
	v_and_b32_e32 v145, 0xffff0000, v121
	v_lshlrev_b32_e32 v146, 16, v122
	v_and_b32_e32 v147, 0xffff0000, v122
	v_lshlrev_b32_e32 v148, 16, v123
	v_and_b32_e32 v149, 0xffff0000, v123
	v_pk_mul_f32 v[20:21], v[20:21], v[142:143]
	v_pk_mul_f32 v[22:23], v[22:23], v[144:145]
	v_pk_mul_f32 v[16:17], v[16:17], v[146:147]
	v_pk_mul_f32 v[18:19], v[18:19], v[148:149]
	v_cvt_pk_bf16_f32 v20, v20, v21
	v_cvt_pk_bf16_f32 v21, v22, v23
	v_cvt_pk_bf16_f32 v22, v16, v17
	v_cvt_pk_bf16_f32 v23, v18, v19
	v_add_u32_e32 v141, 0xa0000, v139
	global_store_dwordx4 v141, v[20:23], s[92:93] offset:256
	s_waitcnt vmcnt(13)
	v_lshlrev_b32_e32 v142, 16, v166
	v_and_b32_e32 v143, 0xffff0000, v166
	v_lshlrev_b32_e32 v144, 16, v167
	v_and_b32_e32 v145, 0xffff0000, v167
	v_lshlrev_b32_e32 v146, 16, v168
	v_and_b32_e32 v147, 0xffff0000, v168
	v_lshlrev_b32_e32 v148, 16, v169
	v_and_b32_e32 v149, 0xffff0000, v169
	v_pk_mul_f32 v[12:13], v[12:13], v[142:143]
	v_pk_mul_f32 v[14:15], v[14:15], v[144:145]
	v_pk_mul_f32 v[8:9], v[8:9], v[146:147]
	v_pk_mul_f32 v[10:11], v[10:11], v[148:149]
	v_cvt_pk_bf16_f32 v12, v12, v13
	v_cvt_pk_bf16_f32 v13, v14, v15
	v_cvt_pk_bf16_f32 v14, v8, v9
	v_cvt_pk_bf16_f32 v15, v10, v11
	v_add_u32_e32 v141, 0xb0000, v139
	global_store_dwordx4 v141, v[12:15], s[92:93]
	s_waitcnt vmcnt(13)
	v_lshlrev_b32_e32 v142, 16, v112
	v_and_b32_e32 v143, 0xffff0000, v112
	v_lshlrev_b32_e32 v144, 16, v113
	v_and_b32_e32 v145, 0xffff0000, v113
	v_lshlrev_b32_e32 v146, 16, v114
	v_and_b32_e32 v147, 0xffff0000, v114
	v_lshlrev_b32_e32 v148, 16, v115
	v_and_b32_e32 v149, 0xffff0000, v115
	v_pk_mul_f32 v[4:5], v[4:5], v[142:143]
	v_pk_mul_f32 v[6:7], v[6:7], v[144:145]
	v_pk_mul_f32 v[0:1], v[0:1], v[146:147]
	v_pk_mul_f32 v[2:3], v[2:3], v[148:149]
	v_cvt_pk_bf16_f32 v4, v4, v5
	v_cvt_pk_bf16_f32 v5, v6, v7
	v_cvt_pk_bf16_f32 v6, v0, v1
	v_cvt_pk_bf16_f32 v7, v2, v3
	v_add_u32_e32 v141, 0xb0000, v139
	global_store_dwordx4 v141, v[4:7], s[92:93] offset:256
	s_mov_b64 s[26:27], -1
	s_mov_b64 s[42:43], exec
	s_mov_b64 vcc, 0
	s_branch .LBB0_203

; #define PG8_STAGE(bufoff, gbase, voff) do { _Pragma("unroll") for (int _i = 0; _i < 2; ++_i) \
;         __builtin_amdgcn_global_load_lds((const unsigned*)((const char*)(gbase) + (voff)[_i]), (LAS unsigned*)(lds + (bufoff) + ldsw + _i * 8192), 16, 0, 0); } while (0)
; #define PG8_LDA(dst, b, h) do { _Pragma("unroll") for (int m = 0; m < 4; ++m) _Pragma("unroll") for (int k = 0; k < 2; ++k) dst[m][k] = *(const LAS bf16x8*)(lds + PG8_SA(b, h) + aoff + m * 2048 + k * 1024); } while (0)
; #define PG8_LDB(dst, b, h) do { _Pragma("unroll") for (int n = 0; n < 2; ++n) _Pragma("unroll") for (int k = 0; k < 2; ++k) dst[n][k] = *(const LAS bf16x8*)(lds + PG8_SB(b, h) + boff + n * 2048 + k * 1024); } while (0)
; #define PG8_MMA(ai, bj, At, Bt) do { __builtin_amdgcn_s_setprio(1); _Pragma("unroll") for (int m = 0; m < 4; ++m) _Pragma("unroll") for (int n = 0; n < 2; ++n) _Pragma("unroll") for (int k = 0; k < 2; ++k) \
;         acc[ai][bj][m][n] = __builtin_amdgcn_mfma_f32_16x16x32_bf16(Bt[n][k], At[m][k], acc[ai][bj][m][n], 0, 0, 0); __builtin_amdgcn_s_setprio(0); } while (0)
; #define PG8_WAIT_V(n) asm volatile("s_waitcnt vmcnt(" #n ")" ::: "memory")
; #define PG8_WAIT_L(n) asm volatile("s_waitcnt lgkmcnt(" #n ")" ::: "memory")
; #define PG8_BAR __builtin_amdgcn_s_barrier()
; #define PG8_SCHED __builtin_amdgcn_sched_barrier(0)
; template <class Epi>
; __device__ __forceinline__ void gemm_phase(LAS unsigned char* lds, const Gemm g, const Epi& E) {
;     ...
;             PG8_LDB(B0, 0, 0); PG8_SCHED; PG8_LDA(At, 0, 0); PG8_STAGE(PG8_SA(1, 1), a1 + hstep, voffA);
;             PG8_WAIT_L(8); PG8_BAR; PG8_WAIT_L(0); PG8_MMA(0, 0, At, B0); PG8_BAR; PG8_SCHED;
;             PG8_LDB(B1, 0, 1); PG8_STAGE(PG8_SB(0, 0), b2, voffB);
;             PG8_BAR; PG8_WAIT_L(0); PG8_MMA(0, 1, At, B1); PG8_BAR;
;             PG8_LDA(At, 0, 1); PG8_STAGE(PG8_SA(0, 0), a2, voffA);
;             PG8_BAR; PG8_WAIT_L(0); PG8_MMA(1, 0, At, B0); PG8_BAR; PG8_SCHED;
;             PG8_STAGE(PG8_SB(0, 1), b2 + hstep, voffB);
;             PG8_WAIT_V(6); PG8_BAR; PG8_MMA(1, 1, At, B1); PG8_BAR;
.LBB0_499:
	s_add_u32 s28, s26, 0xfffe0080
	s_addc_u32 s29, s27, -1
	s_add_i32 s34, 0, 0x10000
	v_add_u32_e32 v156, s34, v159
	ds_read_b128 v[144:147], v156
	ds_read_b128 v[148:151], v156 offset:1024
	ds_read_b128 v[152:155], v156 offset:2048
	ds_read_b128 v[162:165], v156 offset:3072
	s_cmp_eq_u32 vcc_lo, 4
	s_cselect_b32 s37, s1, s29
	s_cselect_b32 s36, s31, s28
	s_cselect_b32 s29, s42, s65
	s_cselect_b32 s28, s43, s45
	s_add_i32 m0, s95, 0xc000
	ds_read_b128 v[166:169], v161
	ds_read_b128 v[170:173], v161 offset:1024
	ds_read_b128 v[174:177], v161 offset:2048
	ds_read_b128 v[178:181], v161 offset:3072
	ds_read_b128 v[182:185], v161 offset:4096
	ds_read_b128 v[186:189], v161 offset:5120
	ds_read_b128 v[190:193], v161 offset:6144
	ds_read_b128 v[194:197], v161 offset:7168
	global_load_lds_dwordx4 v140, s[26:27]
	s_add_i32 m0, s95, 0xe000
	s_nop 0
	global_load_lds_dwordx4 v142, s[26:27]
	s_waitcnt lgkmcnt(8)
	s_barrier
	s_waitcnt lgkmcnt(0)
	s_setprio 1
	v_mfma_f32_16x16x32_bf16 v[124:127], v[144:147], v[166:169], v[124:127]
	v_mfma_f32_16x16x32_bf16 v[120:123], v[152:155], v[166:169], v[120:123]
	v_mfma_f32_16x16x32_bf16 v[108:111], v[144:147], v[174:177], v[108:111]
	v_mfma_f32_16x16x32_bf16 v[104:107], v[152:155], v[174:177], v[104:107]
	v_mfma_f32_16x16x32_bf16 v[92:95], v[144:147], v[182:185], v[92:95]
	v_mfma_f32_16x16x32_bf16 v[88:91], v[152:155], v[182:185], v[88:91]
	v_mfma_f32_16x16x32_bf16 v[76:79], v[144:147], v[190:193], v[76:79]
	v_mfma_f32_16x16x32_bf16 v[72:75], v[152:155], v[190:193], v[72:75]
	v_mfma_f32_16x16x32_bf16 v[124:127], v[148:151], v[170:173], v[124:127]
	v_mfma_f32_16x16x32_bf16 v[120:123], v[162:165], v[170:173], v[120:123]
	v_mfma_f32_16x16x32_bf16 v[108:111], v[148:151], v[178:181], v[108:111]
	v_mfma_f32_16x16x32_bf16 v[104:107], v[162:165], v[178:181], v[104:107]
	v_mfma_f32_16x16x32_bf16 v[92:95], v[148:151], v[186:189], v[92:95]
	v_mfma_f32_16x16x32_bf16 v[88:91], v[162:165], v[186:189], v[88:91]
	v_mfma_f32_16x16x32_bf16 v[76:79], v[148:151], v[194:197], v[76:79]
	v_mfma_f32_16x16x32_bf16 v[72:75], v[162:165], v[194:197], v[72:75]
	s_setprio 0
	s_barrier
	s_add_i32 vcc_hi, 0, 0x14000
	v_add_u32_e32 v156, vcc_hi, v159
	s_add_i32 s34, s34, s83
	ds_read_b128 v[198:201], v156
	ds_read_b128 v[202:205], v156 offset:1024
	ds_read_b128 v[238:241], v156 offset:2048
	ds_read_b128 v[242:245], v156 offset:3072
	s_mov_b32 m0, s34
	s_nop 0
	global_load_lds_dwordx4 v130, s[28:29]
	s_add_i32 m0, s34, 0x2000
	s_nop 0
	global_load_lds_dwordx4 v134, s[28:29]
	s_barrier
	s_waitcnt lgkmcnt(0)
	s_setprio 1
	v_mfma_f32_16x16x32_bf16 v[116:119], v[198:201], v[166:169], v[116:119]
	v_mfma_f32_16x16x32_bf16 v[112:115], v[238:241], v[166:169], v[112:115]
	v_mfma_f32_16x16x32_bf16 v[100:103], v[198:201], v[174:177], v[100:103]
	v_mfma_f32_16x16x32_bf16 v[96:99], v[238:241], v[174:177], v[96:99]
	v_mfma_f32_16x16x32_bf16 v[84:87], v[198:201], v[182:185], v[84:87]
	v_mfma_f32_16x16x32_bf16 v[80:83], v[238:241], v[182:185], v[80:83]
	v_mfma_f32_16x16x32_bf16 v[68:71], v[198:201], v[190:193], v[68:71]
	v_mfma_f32_16x16x32_bf16 v[64:67], v[238:241], v[190:193], v[64:67]
	v_mfma_f32_16x16x32_bf16 v[116:119], v[202:205], v[170:173], v[116:119]
	v_mfma_f32_16x16x32_bf16 v[112:115], v[242:245], v[170:173], v[112:115]
	v_mfma_f32_16x16x32_bf16 v[100:103], v[202:205], v[178:181], v[100:103]
	v_mfma_f32_16x16x32_bf16 v[96:99], v[242:245], v[178:181], v[96:99]
	v_mfma_f32_16x16x32_bf16 v[84:87], v[202:205], v[186:189], v[84:87]
	v_mfma_f32_16x16x32_bf16 v[80:83], v[242:245], v[186:189], v[80:83]
	v_mfma_f32_16x16x32_bf16 v[68:71], v[202:205], v[194:197], v[68:71]
	v_mfma_f32_16x16x32_bf16 v[64:67], v[242:245], v[194:197], v[64:67]
	s_setprio 0
	s_mov_b32 m0, s95
	s_barrier
	ds_read_b128 v[166:169], v161 offset:16384
	ds_read_b128 v[170:173], v161 offset:17408
	ds_read_b128 v[174:177], v161 offset:18432
	ds_read_b128 v[178:181], v161 offset:19456
	ds_read_b128 v[182:185], v161 offset:20480
	ds_read_b128 v[186:189], v161 offset:21504
	ds_read_b128 v[190:193], v161 offset:22528
	ds_read_b128 v[194:197], v161 offset:23552
	global_load_lds_dwordx4 v128, s[36:37]
	s_mov_b32 m0, s82
	s_nop 0
	global_load_lds_dwordx4 v132, s[36:37]
	s_barrier
	s_waitcnt lgkmcnt(0)
	s_setprio 1
	v_mfma_f32_16x16x32_bf16 v[60:63], v[144:147], v[166:169], v[60:63]
	v_mfma_f32_16x16x32_bf16 v[56:59], v[152:155], v[166:169], v[56:59]
	v_mfma_f32_16x16x32_bf16 v[44:47], v[144:147], v[174:177], v[44:47]
	v_mfma_f32_16x16x32_bf16 v[40:43], v[152:155], v[174:177], v[40:43]
	v_mfma_f32_16x16x32_bf16 v[28:31], v[144:147], v[182:185], v[28:31]
	v_mfma_f32_16x16x32_bf16 v[24:27], v[152:155], v[182:185], v[24:27]
	v_mfma_f32_16x16x32_bf16 v[12:15], v[144:147], v[190:193], v[12:15]
	v_mfma_f32_16x16x32_bf16 v[8:11], v[152:155], v[190:193], v[8:11]
	v_mfma_f32_16x16x32_bf16 v[60:63], v[148:151], v[170:173], v[60:63]
	v_mfma_f32_16x16x32_bf16 v[56:59], v[162:165], v[170:173], v[56:59]
	v_mfma_f32_16x16x32_bf16 v[44:47], v[148:151], v[178:181], v[44:47]
	v_mfma_f32_16x16x32_bf16 v[40:43], v[162:165], v[178:181], v[40:43]
	v_mfma_f32_16x16x32_bf16 v[28:31], v[148:151], v[186:189], v[28:31]
	v_mfma_f32_16x16x32_bf16 v[24:27], v[162:165], v[186:189], v[24:27]
	v_mfma_f32_16x16x32_bf16 v[12:15], v[148:151], v[194:197], v[12:15]
	v_mfma_f32_16x16x32_bf16 v[8:11], v[162:165], v[194:197], v[8:11]
	s_setprio 0
	s_barrier
	s_add_u32 s34, s28, 0x20000
	s_addc_u32 s35, s29, 0
	s_add_i32 vcc_hi, vcc_hi, s83
	s_mov_b32 m0, vcc_hi
	s_nop 0
	global_load_lds_dwordx4 v130, s[34:35]
	s_add_i32 m0, vcc_hi, 0x2000
	s_nop 0
	global_load_lds_dwordx4 v134, s[34:35]
	s_waitcnt vmcnt(6)
	s_barrier
; #define PG8_STAGE(bufoff, gbase, voff) do { _Pragma("unroll") for (int _i = 0; _i < 2; ++_i) \
;         __builtin_amdgcn_global_load_lds((const unsigned*)((const char*)(gbase) + (voff)[_i]), (LAS unsigned*)(lds + (bufoff) + ldsw + _i * 8192), 16, 0, 0); } while (0)
; #define PG8_LDA(dst, b, h) do { _Pragma("unroll") for (int m = 0; m < 4; ++m) _Pragma("unroll") for (int k = 0; k < 2; ++k) dst[m][k] = *(const LAS bf16x8*)(lds + PG8_SA(b, h) + aoff + m * 2048 + k * 1024); } while (0)
; #define PG8_LDB(dst, b, h) do { _Pragma("unroll") for (int n = 0; n < 2; ++n) _Pragma("unroll") for (int k = 0; k < 2; ++k) dst[n][k] = *(const LAS bf16x8*)(lds + PG8_SB(b, h) + boff + n * 2048 + k * 1024); } while (0)
; #define PG8_MMA(ai, bj, At, Bt) do { __builtin_amdgcn_s_setprio(1); _Pragma("unroll") for (int m = 0; m < 4; ++m) _Pragma("unroll") for (int n = 0; n < 2; ++n) _Pragma("unroll") for (int k = 0; k < 2; ++k) \
;         acc[ai][bj][m][n] = __builtin_amdgcn_mfma_f32_16x16x32_bf16(Bt[n][k], At[m][k], acc[ai][bj][m][n], 0, 0, 0); __builtin_amdgcn_s_setprio(0); } while (0)
; #define PG8_WAIT_V(n) asm volatile("s_waitcnt vmcnt(" #n ")" ::: "memory")
; #define PG8_WAIT_L(n) asm volatile("s_waitcnt lgkmcnt(" #n ")" ::: "memory")
; #define PG8_BAR __builtin_amdgcn_s_barrier()
; #define PG8_SCHED __builtin_amdgcn_sched_barrier(0)
; template <class Epi>
; __device__ __forceinline__ void gemm_phase(LAS unsigned char* lds, const Gemm g, const Epi& E) {
;     ...
;             PG8_WAIT_V(6); PG8_BAR; PG8_MMA(1, 1, At, B1); PG8_BAR;
;             PG8_LDB(B0, 1, 0); PG8_SCHED; PG8_LDA(At, 1, 0); PG8_STAGE(PG8_SA(0, 1), a2 + hstep, voffA);
;             PG8_WAIT_L(8); PG8_BAR; PG8_WAIT_L(0); PG8_MMA(0, 0, At, B0); PG8_BAR; PG8_SCHED;
;             PG8_LDB(B1, 1, 1); PG8_STAGE(PG8_SB(1, 0), b3, voffB);
;             PG8_BAR; PG8_WAIT_L(0); PG8_MMA(0, 1, At, B1); PG8_BAR;
;             PG8_LDA(At, 1, 1); PG8_STAGE(PG8_SA(1, 0), a3, voffA);
;             PG8_BAR; PG8_WAIT_L(0); PG8_MMA(1, 0, At, B0); PG8_BAR; PG8_SCHED;
;             PG8_STAGE(PG8_SB(1, 1), b3 + hstep, voffB);
	s_setprio 1
	v_mfma_f32_16x16x32_bf16 v[52:55], v[198:201], v[166:169], v[52:55]
	v_mfma_f32_16x16x32_bf16 v[48:51], v[238:241], v[166:169], v[48:51]
	v_mfma_f32_16x16x32_bf16 v[36:39], v[198:201], v[174:177], v[36:39]
	v_mfma_f32_16x16x32_bf16 v[32:35], v[238:241], v[174:177], v[32:35]
	v_mfma_f32_16x16x32_bf16 v[20:23], v[198:201], v[182:185], v[20:23]
	v_mfma_f32_16x16x32_bf16 v[16:19], v[238:241], v[182:185], v[16:19]
	v_mfma_f32_16x16x32_bf16 v[4:7], v[198:201], v[190:193], v[4:7]
	v_mfma_f32_16x16x32_bf16 v[0:3], v[238:241], v[190:193], v[0:3]
	v_mfma_f32_16x16x32_bf16 v[52:55], v[202:205], v[170:173], v[52:55]
	v_mfma_f32_16x16x32_bf16 v[48:51], v[242:245], v[170:173], v[48:51]
	v_mfma_f32_16x16x32_bf16 v[36:39], v[202:205], v[178:181], v[36:39]
	v_mfma_f32_16x16x32_bf16 v[32:35], v[242:245], v[178:181], v[32:35]
	v_mfma_f32_16x16x32_bf16 v[20:23], v[202:205], v[186:189], v[20:23]
	v_mfma_f32_16x16x32_bf16 v[16:19], v[242:245], v[186:189], v[16:19]
	v_mfma_f32_16x16x32_bf16 v[4:7], v[202:205], v[194:197], v[4:7]
	v_mfma_f32_16x16x32_bf16 v[0:3], v[242:245], v[194:197], v[0:3]
	s_setprio 0
	s_add_i32 vcc_hi, 0, 0x18000
	v_add_u32_e32 v162, vcc_hi, v159
	s_barrier
	ds_read_b128 v[144:147], v162
	ds_read_b128 v[148:151], v162 offset:1024
	ds_read_b128 v[152:155], v162 offset:2048
	ds_read_b128 v[162:165], v162 offset:3072
	s_add_u32 s34, s36, 0x20000
	s_addc_u32 s35, s37, 0
	s_mov_b32 m0, s78
	ds_read_b128 v[166:169], v161 offset:32768
	ds_read_b128 v[170:173], v161 offset:33792
	ds_read_b128 v[174:177], v161 offset:34816
	ds_read_b128 v[178:181], v161 offset:35840
	ds_read_b128 v[182:185], v161 offset:36864
	ds_read_b128 v[186:189], v161 offset:37888
	ds_read_b128 v[190:193], v161 offset:38912
	ds_read_b128 v[194:197], v161 offset:39936
	global_load_lds_dwordx4 v128, s[34:35]
	s_mov_b32 m0, s76
	s_nop 0
	global_load_lds_dwordx4 v132, s[34:35]
	s_waitcnt lgkmcnt(8)
	s_barrier
	s_waitcnt lgkmcnt(0)
	s_setprio 1
	v_mfma_f32_16x16x32_bf16 v[124:127], v[144:147], v[166:169], v[124:127]
	v_mfma_f32_16x16x32_bf16 v[120:123], v[152:155], v[166:169], v[120:123]
	v_mfma_f32_16x16x32_bf16 v[108:111], v[144:147], v[174:177], v[108:111]
	v_mfma_f32_16x16x32_bf16 v[104:107], v[152:155], v[174:177], v[104:107]
	v_mfma_f32_16x16x32_bf16 v[92:95], v[144:147], v[182:185], v[92:95]
	v_mfma_f32_16x16x32_bf16 v[88:91], v[152:155], v[182:185], v[88:91]
	v_mfma_f32_16x16x32_bf16 v[76:79], v[144:147], v[190:193], v[76:79]
	v_mfma_f32_16x16x32_bf16 v[72:75], v[152:155], v[190:193], v[72:75]
	v_mfma_f32_16x16x32_bf16 v[124:127], v[148:151], v[170:173], v[124:127]
	v_mfma_f32_16x16x32_bf16 v[120:123], v[162:165], v[170:173], v[120:123]
	v_mfma_f32_16x16x32_bf16 v[108:111], v[148:151], v[178:181], v[108:111]
	v_mfma_f32_16x16x32_bf16 v[104:107], v[162:165], v[178:181], v[104:107]
	v_mfma_f32_16x16x32_bf16 v[92:95], v[148:151], v[186:189], v[92:95]
	v_mfma_f32_16x16x32_bf16 v[88:91], v[162:165], v[186:189], v[88:91]
	v_mfma_f32_16x16x32_bf16 v[76:79], v[148:151], v[194:197], v[76:79]
	v_mfma_f32_16x16x32_bf16 v[72:75], v[162:165], v[194:197], v[72:75]
	s_setprio 0
	s_barrier
	s_add_i32 s34, 0, 0x1c000
	s_add_i32 s35, vcc_hi, s83
	v_add_u32_e32 v208, s34, v159
	s_mov_b32 m0, s35
	ds_read_b128 v[198:201], v208
	ds_read_b128 v[202:205], v208 offset:1024
	ds_read_b128 v[238:241], v208 offset:2048
	ds_read_b128 v[242:245], v208 offset:3072
	s_add_u32 s98, s28, 0x80
	s_addc_u32 s99, s29, 0
	global_load_lds_dwordx4 v130, s[98:99]
	s_add_i32 m0, s35, 0x2000
	s_add_u32 s100, s28, 0x80
	s_addc_u32 s101, s29, 0
	global_load_lds_dwordx4 v134, s[100:101]
	s_barrier
	s_waitcnt lgkmcnt(0)
	s_setprio 1
	v_mfma_f32_16x16x32_bf16 v[116:119], v[198:201], v[166:169], v[116:119]
	v_mfma_f32_16x16x32_bf16 v[112:115], v[238:241], v[166:169], v[112:115]
	v_mfma_f32_16x16x32_bf16 v[100:103], v[198:201], v[174:177], v[100:103]
	v_mfma_f32_16x16x32_bf16 v[96:99], v[238:241], v[174:177], v[96:99]
	v_mfma_f32_16x16x32_bf16 v[84:87], v[198:201], v[182:185], v[84:87]
	v_mfma_f32_16x16x32_bf16 v[80:83], v[238:241], v[182:185], v[80:83]
	v_mfma_f32_16x16x32_bf16 v[68:71], v[198:201], v[190:193], v[68:71]
	v_mfma_f32_16x16x32_bf16 v[64:67], v[238:241], v[190:193], v[64:67]
	v_mfma_f32_16x16x32_bf16 v[116:119], v[202:205], v[170:173], v[116:119]
	v_mfma_f32_16x16x32_bf16 v[112:115], v[242:245], v[170:173], v[112:115]
	v_mfma_f32_16x16x32_bf16 v[100:103], v[202:205], v[178:181], v[100:103]
	v_mfma_f32_16x16x32_bf16 v[96:99], v[242:245], v[178:181], v[96:99]
	v_mfma_f32_16x16x32_bf16 v[84:87], v[202:205], v[186:189], v[84:87]
	v_mfma_f32_16x16x32_bf16 v[80:83], v[242:245], v[186:189], v[80:83]
	v_mfma_f32_16x16x32_bf16 v[68:71], v[202:205], v[194:197], v[68:71]
	v_mfma_f32_16x16x32_bf16 v[64:67], v[242:245], v[194:197], v[64:67]
	s_setprio 0
	s_mov_b32 m0, s68
	s_barrier
	ds_read_b128 v[166:169], v161 offset:49152
	ds_read_b128 v[170:173], v161 offset:50176
	ds_read_b128 v[174:177], v161 offset:51200
	ds_read_b128 v[178:181], v161 offset:52224
	ds_read_b128 v[182:185], v161 offset:53248
	ds_read_b128 v[186:189], v161 offset:54272
	ds_read_b128 v[190:193], v161 offset:55296
	ds_read_b128 v[194:197], v161 offset:56320
	s_add_u32 s98, s36, 0x80
	s_addc_u32 s99, s37, 0
	global_load_lds_dwordx4 v128, s[98:99]
	s_mov_b32 m0, s74
	s_add_u32 s100, s36, 0x80
	s_addc_u32 s101, s37, 0
	global_load_lds_dwordx4 v132, s[100:101]
	s_barrier
; __device__ __forceinline__ u32x2 pack4u(f32x4 a) { u32x2 w = {cvt_pk_bf16(a[0], a[1]), cvt_pk_bf16(a[2], a[3])}; return w; }
; template <class Epi>
; __device__ __forceinline__ void gemm_phase(LAS unsigned char* lds, const Gemm g, const Epi& E) {
;     ...
;             PG8_BAR; PG8_WAIT_L(0); PG8_MMA(1, 0, At, B0); PG8_BAR; PG8_SCHED;
;             PG8_STAGE(PG8_SB(1, 1), b3 + hstep, voffB);
;             PG8_WAIT_V(6); PG8_BAR; PG8_MMA(1, 1, At, B1); PG8_BAR;
;     __device__ __forceinline__ void operator()(const AccT& acc, const Unit& u, int wr, int wc, int fr, int fq) const {
;     ...
;                 const int row = u.pm * 256 + ai * 128 + wr * 64 + m * 16 + fr; const int b = row / SEQ, t = row % SEQ;
;                 const f32x4 s0 = *(const f32x4*)(SSQ + (size_t)row * 16 + mode * 8), s1 = *(const f32x4*)(SSQ + (size_t)row * 16 + mode * 8 + 4);
;                 const float ssq = (s0[0] + s0[1]) + (s0[2] + s0[3]) + (s1[0] + s1[1]) + (s1[2] + s1[3]);
;                 float rs = rsqrtf(ssq * (1.0f / 512.0f) + EPS);
;                 if (mode == 0) {
;                     rs *= (0.07216878364870322f * 1.4426950408889634f);
; #pragma unroll
;                     for (int bj = 0; bj < 2; ++bj) {
;                         const int c8 = u.pn * 256 + bj * 128 + wc * 32 + fq * 8; const int head = c8 / DQK, d0 = c8 % DQK;
;                         bf16_t* qp = Q + ((size_t)(b * NH + head) * SEQ + t) * DQK;
;                         const f32x4 v0 = acc[ai][bj][m][0] * rs, v1 = acc[ai][bj][m][1] * rs;
;                         if (d0 < 128) { *(u32x4*)(qp + d0) = pack8u(v0, v1); }
;                         else { const int i0 = 4 * ((d0 - 128) >> 3);
;                             const f32x4 cs = *(const f32x4*)(COS + (size_t)row * 32 + i0), sn = *(const f32x4*)(SIN + (size_t)row * 32 + i0);
;                             const f32x4 o1 = v0 * cs - v1 * sn, o2 = v1 * cs + v0 * sn;
;                             *(u32x2*)(qp + 128 + i0) = pack4u(o1); *(u32x2*)(qp + 160 + i0) = pack4u(o2); }
;                     }
;                 } else {
;                     const size_t bh = (size_t)(b * NH + u.pn) * SEQ + t; const int d = wc * 32 + fq * 8;
;                     *(u32x4*)(Kb + bh * DQK + d) = pack8u(acc[ai][0][m][0] * rs, acc[ai][0][m][1] * rs);
;                     *(u32x4*)(Vb + bh * 128 + d) = pack8u(acc[ai][1][m][0] * rs, acc[ai][1][m][1] * rs);
	s_waitcnt lgkmcnt(0)
	s_setprio 1
	v_mfma_f32_16x16x32_bf16 v[60:63], v[144:147], v[166:169], v[60:63]
	v_mfma_f32_16x16x32_bf16 v[56:59], v[152:155], v[166:169], v[56:59]
	v_mfma_f32_16x16x32_bf16 v[44:47], v[144:147], v[174:177], v[44:47]
	v_mfma_f32_16x16x32_bf16 v[40:43], v[152:155], v[174:177], v[40:43]
	v_mfma_f32_16x16x32_bf16 v[28:31], v[144:147], v[182:185], v[28:31]
	v_mfma_f32_16x16x32_bf16 v[24:27], v[152:155], v[182:185], v[24:27]
	v_mfma_f32_16x16x32_bf16 v[12:15], v[144:147], v[190:193], v[12:15]
	v_mfma_f32_16x16x32_bf16 v[8:11], v[152:155], v[190:193], v[8:11]
	v_mfma_f32_16x16x32_bf16 v[60:63], v[148:151], v[170:173], v[60:63]
	v_mfma_f32_16x16x32_bf16 v[56:59], v[162:165], v[170:173], v[56:59]
	v_mfma_f32_16x16x32_bf16 v[44:47], v[148:151], v[178:181], v[44:47]
	v_mfma_f32_16x16x32_bf16 v[40:43], v[162:165], v[178:181], v[40:43]
	v_mfma_f32_16x16x32_bf16 v[28:31], v[148:151], v[186:189], v[28:31]
	v_mfma_f32_16x16x32_bf16 v[24:27], v[162:165], v[186:189], v[24:27]
	v_mfma_f32_16x16x32_bf16 v[12:15], v[148:151], v[194:197], v[12:15]
	v_mfma_f32_16x16x32_bf16 v[8:11], v[162:165], v[194:197], v[8:11]
	s_setprio 0
	s_barrier
	s_add_u32 s28, s28, 0x20080
	s_addc_u32 s29, s29, 0
	s_add_i32 s34, s34, s83
	s_mov_b32 m0, s34
	s_nop 0
	global_load_lds_dwordx4 v130, s[28:29]
	s_add_i32 m0, s34, 0x2000
	s_nop 0
	global_load_lds_dwordx4 v134, s[28:29]
	s_waitcnt vmcnt(6)
	s_barrier
	s_setprio 1
	v_mfma_f32_16x16x32_bf16 v[52:55], v[198:201], v[166:169], v[52:55]
	v_mfma_f32_16x16x32_bf16 v[48:51], v[238:241], v[166:169], v[48:51]
	v_mfma_f32_16x16x32_bf16 v[36:39], v[198:201], v[174:177], v[36:39]
	v_mfma_f32_16x16x32_bf16 v[32:35], v[238:241], v[174:177], v[32:35]
	v_mfma_f32_16x16x32_bf16 v[20:23], v[198:201], v[182:185], v[20:23]
	v_mfma_f32_16x16x32_bf16 v[16:19], v[238:241], v[182:185], v[16:19]
	v_mfma_f32_16x16x32_bf16 v[4:7], v[198:201], v[190:193], v[4:7]
	v_mfma_f32_16x16x32_bf16 v[0:3], v[238:241], v[190:193], v[0:3]
	v_mfma_f32_16x16x32_bf16 v[52:55], v[202:205], v[170:173], v[52:55]
	v_mfma_f32_16x16x32_bf16 v[48:51], v[242:245], v[170:173], v[48:51]
	v_mfma_f32_16x16x32_bf16 v[36:39], v[202:205], v[178:181], v[36:39]
	v_mfma_f32_16x16x32_bf16 v[32:35], v[242:245], v[178:181], v[32:35]
	v_mfma_f32_16x16x32_bf16 v[20:23], v[202:205], v[186:189], v[20:23]
	v_mfma_f32_16x16x32_bf16 v[16:19], v[242:245], v[186:189], v[16:19]
	v_mfma_f32_16x16x32_bf16 v[4:7], v[202:205], v[194:197], v[4:7]
	v_mfma_f32_16x16x32_bf16 v[0:3], v[242:245], v[194:197], v[0:3]
	s_setprio 0
	s_add_i32 vcc_lo, vcc_lo, 2
	s_add_u32 s26, s26, 0x100
	s_addc_u32 s27, s27, 0
	s_add_u32 s45, s45, 0x100
	s_addc_u32 s65, s65, 0
	s_cmp_gt_u32 vcc_lo, 5
	s_barrier
	s_cbranch_scc0 .LBB0_499
	v_lshl_add_u32 v144, s0, 8, v158
	v_lshlrev_b32_e32 v220, 6, v144
	v_add_u32_e32 v221, 0x2000, v220
	global_load_dwordx4 v[176:179], v220, s[48:49] offset:16
	global_load_dwordx4 v[180:183], v220, s[48:49]
	global_load_dwordx4 v[184:187], v220, s[48:49] offset:1040
	global_load_dwordx4 v[188:191], v220, s[48:49] offset:1024
	global_load_dwordx4 v[192:195], v220, s[48:49] offset:2064
	global_load_dwordx4 v[196:199], v220, s[48:49] offset:2048
	global_load_dwordx4 v[200:203], v220, s[48:49] offset:3088
	global_load_dwordx4 v[204:207], v220, s[48:49] offset:3072
	v_ashrrev_i32_e32 v145, 31, v144
	v_lshlrev_b64 v[150:151], 6, v[144:145]
	v_lshl_add_u64 v[154:155], s[48:49], 0, v[150:151]
	s_waitcnt vmcnt(6)
	v_mov_b32_e32 v150, v176
	v_mov_b32_e32 v151, v177
	v_mov_b32_e32 v152, v178
	v_mov_b32_e32 v153, v179
	s_nop 0
	v_mov_b32_e32 v154, v180
	v_mov_b32_e32 v155, v181
	v_mov_b32_e32 v156, v182
	v_mov_b32_e32 v157, v183
	global_load_dwordx4 v[176:179], v221, s[48:49] offset:16
	global_load_dwordx4 v[180:183], v221, s[48:49]
	v_lshrrev_b32_e32 v146, 21, v145
	v_add_u32_e32 v146, v144, v146
	v_ashrrev_i32_e32 v149, 11, v146
	v_mul_i32_i24_e32 v146, 0x800, v149
	v_sub_u32_e32 v146, v144, v146
	s_mov_b64 s[0:1], -1
	s_nop 0
	v_mov_b32_e32 v162, v155
	v_mov_b32_e32 v163, v156
	v_mov_b32_e32 v155, v157
	v_pk_add_f32 v[154:155], v[162:163], v[154:155]
	v_mov_b32_e32 v156, v152
	v_mov_b32_e32 v157, v150
	v_mov_b32_e32 v150, v153
	v_pk_add_f32 v[150:151], v[156:157], v[150:151]
	v_add_f32_e32 v147, v154, v155
	v_add_f32_e32 v147, v147, v151
	v_add_f32_e32 v147, v150, v147
	v_fmamk_f32 v147, v147, 0x3b000000, v223
	v_cmp_gt_f32_e32 vcc, s60, v147
	v_mul_f32_e32 v148, 0x4b800000, v147
	s_nop 0
	v_cndmask_b32_e32 v147, v147, v148, vcc
	v_rsq_f32_e32 v147, v147
	s_nop 0
	v_mul_f32_e32 v148, 0x45800000, v147
	v_cndmask_b32_e32 v148, v147, v148, vcc
	s_and_b64 vcc, exec, s[46:47]
	v_ashrrev_i32_e32 v147, 31, v146
	s_cbranch_vccz .LBB0_502
	v_lshl_add_u32 v150, v149, 3, s94
	v_ashrrev_i32_e32 v151, 31, v150
	v_lshlrev_b64 v[150:151], 11, v[150:151]
	v_lshl_add_u64 v[154:155], v[150:151], 0, v[146:147]
	v_pk_mul_f32 v[152:153], v[126:127], v[148:149] op_sel_hi:[1,0]
	v_pk_mul_f32 v[150:151], v[124:125], v[148:149] op_sel_hi:[1,0]
	v_pk_mul_f32 v[156:157], v[122:123], v[148:149] op_sel_hi:[1,0]
	v_pk_mul_f32 v[162:163], v[120:121], v[148:149] op_sel_hi:[1,0]
	v_cvt_pk_bf16_f32 v150, v150, v151
	v_cvt_pk_bf16_f32 v151, v152, v153
	v_cvt_pk_bf16_f32 v153, v156, v157
	v_mad_u64_u32 v[156:157], s[0:1], v154, s33, v[136:137]
	v_cvt_pk_bf16_f32 v152, v162, v163
	v_mad_i32_i24 v157, v155, s33, v157
	global_store_dwordx4 v[156:157], v[150:153], off
	v_pk_mul_f32 v[156:157], v[114:115], v[148:149] op_sel_hi:[1,0]
	v_pk_mul_f32 v[162:163], v[112:113], v[148:149] op_sel_hi:[1,0]
	v_pk_mul_f32 v[152:153], v[118:119], v[148:149] op_sel_hi:[1,0]
	v_pk_mul_f32 v[150:151], v[116:117], v[148:149] op_sel_hi:[1,0]
	v_lshlrev_b64 v[154:155], 8, v[154:155]
	v_cvt_pk_bf16_f32 v150, v150, v151
	v_cvt_pk_bf16_f32 v151, v152, v153
	v_cvt_pk_bf16_f32 v152, v162, v163
	v_cvt_pk_bf16_f32 v153, v156, v157
	v_lshl_add_u64 v[154:155], v[138:139], 0, v[154:155]
	global_store_dwordx4 v[154:155], v[150:153], off
	s_mov_b64 s[0:1], 0

; #define PG8_STAGE(bufoff, gbase, voff) do { _Pragma("unroll") for (int _i = 0; _i < 2; ++_i) \
;         __builtin_amdgcn_global_load_lds((const unsigned*)((const char*)(gbase) + (voff)[_i]), (LAS unsigned*)(lds + (bufoff) + ldsw + _i * 8192), 16, 0, 0); } while (0)
; #define PG8_LDA(dst, b, h) do { _Pragma("unroll") for (int m = 0; m < 4; ++m) _Pragma("unroll") for (int k = 0; k < 2; ++k) dst[m][k] = *(const LAS bf16x8*)(lds + PG8_SA(b, h) + aoff + m * 2048 + k * 1024); } while (0)
; #define PG8_LDB(dst, b, h) do { _Pragma("unroll") for (int n = 0; n < 2; ++n) _Pragma("unroll") for (int k = 0; k < 2; ++k) dst[n][k] = *(const LAS bf16x8*)(lds + PG8_SB(b, h) + boff + n * 2048 + k * 1024); } while (0)
; #define PG8_MMA(ai, bj, At, Bt) do { __builtin_amdgcn_s_setprio(1); _Pragma("unroll") for (int m = 0; m < 4; ++m) _Pragma("unroll") for (int n = 0; n < 2; ++n) _Pragma("unroll") for (int k = 0; k < 2; ++k) \
;         acc[ai][bj][m][n] = __builtin_amdgcn_mfma_f32_16x16x32_bf16(Bt[n][k], At[m][k], acc[ai][bj][m][n], 0, 0, 0); __builtin_amdgcn_s_setprio(0); } while (0)
; #define PG8_WAIT_V(n) asm volatile("s_waitcnt vmcnt(" #n ")" ::: "memory")
; #define PG8_WAIT_L(n) asm volatile("s_waitcnt lgkmcnt(" #n ")" ::: "memory")
; #define PG8_BAR __builtin_amdgcn_s_barrier()
; #define PG8_SCHED __builtin_amdgcn_sched_barrier(0)
; template <class Epi>
; __device__ __forceinline__ void gemm_phase(LAS unsigned char* lds, const Gemm g, const Epi& E) {
;     ...
;             PG8_LDB(B0, 0, 0); PG8_SCHED; PG8_LDA(At, 0, 0); PG8_STAGE(PG8_SA(1, 1), a1 + hstep, voffA);
;             PG8_WAIT_L(8); PG8_BAR; PG8_WAIT_L(0); PG8_MMA(0, 0, At, B0); PG8_BAR; PG8_SCHED;
;             PG8_LDB(B1, 0, 1); PG8_STAGE(PG8_SB(0, 0), b2, voffB);
;             PG8_BAR; PG8_WAIT_L(0); PG8_MMA(0, 1, At, B1); PG8_BAR;
;             PG8_LDA(At, 0, 1); PG8_STAGE(PG8_SA(0, 0), a2, voffA);
;             PG8_BAR; PG8_WAIT_L(0); PG8_MMA(1, 0, At, B0); PG8_BAR; PG8_SCHED;
;             PG8_STAGE(PG8_SB(0, 1), b2 + hstep, voffB);
;             PG8_WAIT_V(6); PG8_BAR; PG8_MMA(1, 1, At, B1); PG8_BAR;
.LBB0_672:
	s_add_u32 s28, s26, 0xfff80080
	s_addc_u32 s29, s27, -1
	s_add_i32 s34, 0, 0x10000
	v_add_u32_e32 v160, s34, v163
	ds_read_b128 v[128:131], v160
	ds_read_b128 v[132:135], v160 offset:1024
	ds_read_b128 v[156:159], v160 offset:2048
	ds_read_b128 v[166:169], v160 offset:3072
	s_cmp_eq_u32 s39, 28
	s_cselect_b32 s37, s1, s29
	s_cselect_b32 s36, s2, s28
	s_cselect_b32 s29, s3, s38
	s_cselect_b32 s28, s30, s31
	s_add_i32 m0, s96, 0xc000
	ds_read_b128 v[170:173], v164
	ds_read_b128 v[174:177], v164 offset:1024
	ds_read_b128 v[178:181], v164 offset:2048
	ds_read_b128 v[182:185], v164 offset:3072
	ds_read_b128 v[186:189], v164 offset:4096
	ds_read_b128 v[190:193], v164 offset:5120
	ds_read_b128 v[194:197], v164 offset:6144
	ds_read_b128 v[198:201], v164 offset:7168
	global_load_lds_dwordx4 v152, s[26:27]
	s_add_i32 m0, s96, 0xe000
	s_nop 0
	global_load_lds_dwordx4 v154, s[26:27]
	s_waitcnt lgkmcnt(8)
	s_barrier
	s_waitcnt lgkmcnt(0)
	s_setprio 1
	v_mfma_f32_16x16x32_bf16 v[124:127], v[128:131], v[170:173], v[124:127]
	v_mfma_f32_16x16x32_bf16 v[120:123], v[156:159], v[170:173], v[120:123]
	v_mfma_f32_16x16x32_bf16 v[108:111], v[128:131], v[178:181], v[108:111]
	v_mfma_f32_16x16x32_bf16 v[104:107], v[156:159], v[178:181], v[104:107]
	v_mfma_f32_16x16x32_bf16 v[92:95], v[128:131], v[186:189], v[92:95]
	v_mfma_f32_16x16x32_bf16 v[88:91], v[156:159], v[186:189], v[88:91]
	v_mfma_f32_16x16x32_bf16 v[76:79], v[128:131], v[194:197], v[76:79]
	v_mfma_f32_16x16x32_bf16 v[72:75], v[156:159], v[194:197], v[72:75]
	v_mfma_f32_16x16x32_bf16 v[124:127], v[132:135], v[174:177], v[124:127]
	v_mfma_f32_16x16x32_bf16 v[120:123], v[166:169], v[174:177], v[120:123]
	v_mfma_f32_16x16x32_bf16 v[108:111], v[132:135], v[182:185], v[108:111]
	v_mfma_f32_16x16x32_bf16 v[104:107], v[166:169], v[182:185], v[104:107]
	v_mfma_f32_16x16x32_bf16 v[92:95], v[132:135], v[190:193], v[92:95]
	v_mfma_f32_16x16x32_bf16 v[88:91], v[166:169], v[190:193], v[88:91]
	v_mfma_f32_16x16x32_bf16 v[76:79], v[132:135], v[198:201], v[76:79]
	v_mfma_f32_16x16x32_bf16 v[72:75], v[166:169], v[198:201], v[72:75]
	s_setprio 0
	s_barrier
	s_add_i32 s35, 0, 0x14000
	v_add_u32_e32 v160, s35, v163
	s_add_i32 s34, s34, s71
	ds_read_b128 v[202:205], v160
	ds_read_b128 v[238:241], v160 offset:1024
	ds_read_b128 v[242:245], v160 offset:2048
	ds_read_b128 v[246:249], v160 offset:3072
	s_mov_b32 m0, s34
	s_nop 0
	global_load_lds_dwordx4 v138, s[28:29]
	s_add_i32 m0, s34, 0x2000
	s_nop 0
	global_load_lds_dwordx4 v142, s[28:29]
	s_barrier
	s_waitcnt lgkmcnt(0)
	s_setprio 1
	v_mfma_f32_16x16x32_bf16 v[116:119], v[202:205], v[170:173], v[116:119]
	v_mfma_f32_16x16x32_bf16 v[112:115], v[242:245], v[170:173], v[112:115]
	v_mfma_f32_16x16x32_bf16 v[100:103], v[202:205], v[178:181], v[100:103]
	v_mfma_f32_16x16x32_bf16 v[96:99], v[242:245], v[178:181], v[96:99]
	v_mfma_f32_16x16x32_bf16 v[84:87], v[202:205], v[186:189], v[84:87]
	v_mfma_f32_16x16x32_bf16 v[80:83], v[242:245], v[186:189], v[80:83]
	v_mfma_f32_16x16x32_bf16 v[68:71], v[202:205], v[194:197], v[68:71]
	v_mfma_f32_16x16x32_bf16 v[64:67], v[242:245], v[194:197], v[64:67]
	v_mfma_f32_16x16x32_bf16 v[116:119], v[238:241], v[174:177], v[116:119]
	v_mfma_f32_16x16x32_bf16 v[112:115], v[246:249], v[174:177], v[112:115]
	v_mfma_f32_16x16x32_bf16 v[100:103], v[238:241], v[182:185], v[100:103]
	v_mfma_f32_16x16x32_bf16 v[96:99], v[246:249], v[182:185], v[96:99]
	v_mfma_f32_16x16x32_bf16 v[84:87], v[238:241], v[190:193], v[84:87]
	v_mfma_f32_16x16x32_bf16 v[80:83], v[246:249], v[190:193], v[80:83]
	v_mfma_f32_16x16x32_bf16 v[68:71], v[238:241], v[198:201], v[68:71]
	v_mfma_f32_16x16x32_bf16 v[64:67], v[246:249], v[198:201], v[64:67]
	s_setprio 0
	s_mov_b32 m0, s96
	s_barrier
	ds_read_b128 v[170:173], v164 offset:16384
	ds_read_b128 v[174:177], v164 offset:17408
	ds_read_b128 v[178:181], v164 offset:18432
	ds_read_b128 v[182:185], v164 offset:19456
	ds_read_b128 v[186:189], v164 offset:20480
	ds_read_b128 v[190:193], v164 offset:21504
	ds_read_b128 v[194:197], v164 offset:22528
	ds_read_b128 v[198:201], v164 offset:23552
	global_load_lds_dwordx4 v136, s[36:37]
	s_mov_b32 m0, s97
	s_nop 0
	global_load_lds_dwordx4 v140, s[36:37]
	s_barrier
	s_waitcnt lgkmcnt(0)
	s_setprio 1
	v_mfma_f32_16x16x32_bf16 v[60:63], v[128:131], v[170:173], v[60:63]
	v_mfma_f32_16x16x32_bf16 v[56:59], v[156:159], v[170:173], v[56:59]
	v_mfma_f32_16x16x32_bf16 v[44:47], v[128:131], v[178:181], v[44:47]
	v_mfma_f32_16x16x32_bf16 v[40:43], v[156:159], v[178:181], v[40:43]
	v_mfma_f32_16x16x32_bf16 v[28:31], v[128:131], v[186:189], v[28:31]
	v_mfma_f32_16x16x32_bf16 v[24:27], v[156:159], v[186:189], v[24:27]
	v_mfma_f32_16x16x32_bf16 v[12:15], v[128:131], v[194:197], v[12:15]
	v_mfma_f32_16x16x32_bf16 v[8:11], v[156:159], v[194:197], v[8:11]
	v_mfma_f32_16x16x32_bf16 v[60:63], v[132:135], v[174:177], v[60:63]
	v_mfma_f32_16x16x32_bf16 v[56:59], v[166:169], v[174:177], v[56:59]
	v_mfma_f32_16x16x32_bf16 v[44:47], v[132:135], v[182:185], v[44:47]
	v_mfma_f32_16x16x32_bf16 v[40:43], v[166:169], v[182:185], v[40:43]
	v_mfma_f32_16x16x32_bf16 v[28:31], v[132:135], v[190:193], v[28:31]
	v_mfma_f32_16x16x32_bf16 v[24:27], v[166:169], v[190:193], v[24:27]
	v_mfma_f32_16x16x32_bf16 v[12:15], v[132:135], v[198:201], v[12:15]
	v_mfma_f32_16x16x32_bf16 v[8:11], v[166:169], v[198:201], v[8:11]
	s_setprio 0
	s_barrier
	s_add_u32 s48, s28, 0x80000
	s_addc_u32 s49, s29, 0
	s_add_i32 s34, s35, s71
	s_mov_b32 m0, s34
	s_nop 0
	global_load_lds_dwordx4 v138, s[48:49]
	s_add_i32 m0, s34, 0x2000
	s_nop 0
	global_load_lds_dwordx4 v142, s[48:49]
	s_waitcnt vmcnt(6)
	s_barrier
; #define PG8_STAGE(bufoff, gbase, voff) do { _Pragma("unroll") for (int _i = 0; _i < 2; ++_i) \
;         __builtin_amdgcn_global_load_lds((const unsigned*)((const char*)(gbase) + (voff)[_i]), (LAS unsigned*)(lds + (bufoff) + ldsw + _i * 8192), 16, 0, 0); } while (0)
; #define PG8_LDA(dst, b, h) do { _Pragma("unroll") for (int m = 0; m < 4; ++m) _Pragma("unroll") for (int k = 0; k < 2; ++k) dst[m][k] = *(const LAS bf16x8*)(lds + PG8_SA(b, h) + aoff + m * 2048 + k * 1024); } while (0)
; #define PG8_LDB(dst, b, h) do { _Pragma("unroll") for (int n = 0; n < 2; ++n) _Pragma("unroll") for (int k = 0; k < 2; ++k) dst[n][k] = *(const LAS bf16x8*)(lds + PG8_SB(b, h) + boff + n * 2048 + k * 1024); } while (0)
; #define PG8_MMA(ai, bj, At, Bt) do { __builtin_amdgcn_s_setprio(1); _Pragma("unroll") for (int m = 0; m < 4; ++m) _Pragma("unroll") for (int n = 0; n < 2; ++n) _Pragma("unroll") for (int k = 0; k < 2; ++k) \
;         acc[ai][bj][m][n] = __builtin_amdgcn_mfma_f32_16x16x32_bf16(Bt[n][k], At[m][k], acc[ai][bj][m][n], 0, 0, 0); __builtin_amdgcn_s_setprio(0); } while (0)
; #define PG8_WAIT_V(n) asm volatile("s_waitcnt vmcnt(" #n ")" ::: "memory")
; #define PG8_WAIT_L(n) asm volatile("s_waitcnt lgkmcnt(" #n ")" ::: "memory")
; #define PG8_BAR __builtin_amdgcn_s_barrier()
; #define PG8_SCHED __builtin_amdgcn_sched_barrier(0)
; template <class Epi>
; __device__ __forceinline__ void gemm_phase(LAS unsigned char* lds, const Gemm g, const Epi& E) {
;     ...
;             PG8_WAIT_V(6); PG8_BAR; PG8_MMA(1, 1, At, B1); PG8_BAR;
;             PG8_LDB(B0, 1, 0); PG8_SCHED; PG8_LDA(At, 1, 0); PG8_STAGE(PG8_SA(0, 1), a2 + hstep, voffA);
;             PG8_WAIT_L(8); PG8_BAR; PG8_WAIT_L(0); PG8_MMA(0, 0, At, B0); PG8_BAR; PG8_SCHED;
;             PG8_LDB(B1, 1, 1); PG8_STAGE(PG8_SB(1, 0), b3, voffB);
;             PG8_BAR; PG8_WAIT_L(0); PG8_MMA(0, 1, At, B1); PG8_BAR;
;             PG8_LDA(At, 1, 1); PG8_STAGE(PG8_SA(1, 0), a3, voffA);
;             PG8_BAR; PG8_WAIT_L(0); PG8_MMA(1, 0, At, B0); PG8_BAR; PG8_SCHED;
	s_setprio 1
	v_mfma_f32_16x16x32_bf16 v[52:55], v[202:205], v[170:173], v[52:55]
	v_mfma_f32_16x16x32_bf16 v[48:51], v[242:245], v[170:173], v[48:51]
	v_mfma_f32_16x16x32_bf16 v[36:39], v[202:205], v[178:181], v[36:39]
	v_mfma_f32_16x16x32_bf16 v[32:35], v[242:245], v[178:181], v[32:35]
	v_mfma_f32_16x16x32_bf16 v[20:23], v[202:205], v[186:189], v[20:23]
	v_mfma_f32_16x16x32_bf16 v[16:19], v[242:245], v[186:189], v[16:19]
	v_mfma_f32_16x16x32_bf16 v[4:7], v[202:205], v[194:197], v[4:7]
	v_mfma_f32_16x16x32_bf16 v[0:3], v[242:245], v[194:197], v[0:3]
	v_mfma_f32_16x16x32_bf16 v[52:55], v[238:241], v[174:177], v[52:55]
	v_mfma_f32_16x16x32_bf16 v[48:51], v[246:249], v[174:177], v[48:51]
	v_mfma_f32_16x16x32_bf16 v[36:39], v[238:241], v[182:185], v[36:39]
	v_mfma_f32_16x16x32_bf16 v[32:35], v[246:249], v[182:185], v[32:35]
	v_mfma_f32_16x16x32_bf16 v[20:23], v[238:241], v[190:193], v[20:23]
	v_mfma_f32_16x16x32_bf16 v[16:19], v[246:249], v[190:193], v[16:19]
	v_mfma_f32_16x16x32_bf16 v[4:7], v[238:241], v[198:201], v[4:7]
	v_mfma_f32_16x16x32_bf16 v[0:3], v[246:249], v[198:201], v[0:3]
	s_setprio 0
	s_add_i32 s34, 0, 0x18000
	v_add_u32_e32 v165, s34, v163
	s_barrier
	ds_read_b128 v[128:131], v165
	ds_read_b128 v[132:135], v165 offset:1024
	ds_read_b128 v[156:159], v165 offset:2048
	ds_read_b128 v[166:169], v165 offset:3072
	s_add_u32 s36, s36, 0x80000
	s_addc_u32 s37, s37, 0
	s_mov_b32 m0, s70
	ds_read_b128 v[170:173], v164 offset:32768
	ds_read_b128 v[174:177], v164 offset:33792
	ds_read_b128 v[178:181], v164 offset:34816
	ds_read_b128 v[182:185], v164 offset:35840
	ds_read_b128 v[186:189], v164 offset:36864
	ds_read_b128 v[190:193], v164 offset:37888
	ds_read_b128 v[194:197], v164 offset:38912
	ds_read_b128 v[198:201], v164 offset:39936
	global_load_lds_dwordx4 v136, s[36:37]
	s_mov_b32 m0, s69
	s_nop 0
	global_load_lds_dwordx4 v140, s[36:37]
	s_waitcnt lgkmcnt(8)
	s_barrier
	s_waitcnt lgkmcnt(0)
	s_setprio 1
	v_mfma_f32_16x16x32_bf16 v[124:127], v[128:131], v[170:173], v[124:127]
	v_mfma_f32_16x16x32_bf16 v[120:123], v[156:159], v[170:173], v[120:123]
	v_mfma_f32_16x16x32_bf16 v[108:111], v[128:131], v[178:181], v[108:111]
	v_mfma_f32_16x16x32_bf16 v[104:107], v[156:159], v[178:181], v[104:107]
	v_mfma_f32_16x16x32_bf16 v[92:95], v[128:131], v[186:189], v[92:95]
	v_mfma_f32_16x16x32_bf16 v[88:91], v[156:159], v[186:189], v[88:91]
	v_mfma_f32_16x16x32_bf16 v[76:79], v[128:131], v[194:197], v[76:79]
	v_mfma_f32_16x16x32_bf16 v[72:75], v[156:159], v[194:197], v[72:75]
	v_mfma_f32_16x16x32_bf16 v[124:127], v[132:135], v[174:177], v[124:127]
	v_mfma_f32_16x16x32_bf16 v[120:123], v[166:169], v[174:177], v[120:123]
	v_mfma_f32_16x16x32_bf16 v[108:111], v[132:135], v[182:185], v[108:111]
	v_mfma_f32_16x16x32_bf16 v[104:107], v[166:169], v[182:185], v[104:107]
	v_mfma_f32_16x16x32_bf16 v[92:95], v[132:135], v[190:193], v[92:95]
	v_mfma_f32_16x16x32_bf16 v[88:91], v[166:169], v[190:193], v[88:91]
	v_mfma_f32_16x16x32_bf16 v[76:79], v[132:135], v[198:201], v[76:79]
	v_mfma_f32_16x16x32_bf16 v[72:75], v[166:169], v[198:201], v[72:75]
	s_setprio 0
	s_barrier
	s_add_i32 s35, 0, 0x1c000
	s_add_i32 s34, s34, s71
	v_add_u32_e32 v165, s35, v163
	s_mov_b32 m0, s34
	ds_read_b128 v[202:205], v165
	ds_read_b128 v[238:241], v165 offset:1024
	ds_read_b128 v[242:245], v165 offset:2048
	ds_read_b128 v[246:249], v165 offset:3072
	s_add_u32 s98, s28, 0x80
	s_addc_u32 s99, s29, 0
	global_load_lds_dwordx4 v138, s[98:99]
	s_add_i32 m0, s34, 0x2000
	s_add_u32 s100, s28, 0x80
	s_addc_u32 s101, s29, 0
	global_load_lds_dwordx4 v142, s[100:101]
	s_barrier
	s_waitcnt lgkmcnt(0)
	s_setprio 1
	v_mfma_f32_16x16x32_bf16 v[116:119], v[202:205], v[170:173], v[116:119]
	v_mfma_f32_16x16x32_bf16 v[112:115], v[242:245], v[170:173], v[112:115]
	v_mfma_f32_16x16x32_bf16 v[100:103], v[202:205], v[178:181], v[100:103]
	v_mfma_f32_16x16x32_bf16 v[96:99], v[242:245], v[178:181], v[96:99]
	v_mfma_f32_16x16x32_bf16 v[84:87], v[202:205], v[186:189], v[84:87]
	v_mfma_f32_16x16x32_bf16 v[80:83], v[242:245], v[186:189], v[80:83]
	v_mfma_f32_16x16x32_bf16 v[68:71], v[202:205], v[194:197], v[68:71]
	v_mfma_f32_16x16x32_bf16 v[64:67], v[242:245], v[194:197], v[64:67]
	v_mfma_f32_16x16x32_bf16 v[116:119], v[238:241], v[174:177], v[116:119]
	v_mfma_f32_16x16x32_bf16 v[112:115], v[246:249], v[174:177], v[112:115]
	v_mfma_f32_16x16x32_bf16 v[100:103], v[238:241], v[182:185], v[100:103]
	v_mfma_f32_16x16x32_bf16 v[96:99], v[246:249], v[182:185], v[96:99]
	v_mfma_f32_16x16x32_bf16 v[84:87], v[238:241], v[190:193], v[84:87]
	v_mfma_f32_16x16x32_bf16 v[80:83], v[246:249], v[190:193], v[80:83]
	v_mfma_f32_16x16x32_bf16 v[68:71], v[238:241], v[198:201], v[68:71]
	v_mfma_f32_16x16x32_bf16 v[64:67], v[246:249], v[198:201], v[64:67]
	s_setprio 0
	s_mov_b32 m0, s68
	s_barrier
; #define PG8_WAIT_V(n) asm volatile("s_waitcnt vmcnt(" #n ")" ::: "memory")
; template <class Epi>
; __device__ __forceinline__ void gemm_phase(LAS unsigned char* lds, const Gemm g, const Epi& E) {
;     ...
;             PG8_BAR; PG8_WAIT_L(0); PG8_MMA(1, 0, At, B0); PG8_BAR; PG8_SCHED;
;             PG8_STAGE(PG8_SB(1, 1), b3 + hstep, voffB);
;             PG8_WAIT_V(6); PG8_BAR; PG8_MMA(1, 1, At, B1); PG8_BAR;
;     __device__ __forceinline__ void operator()(const AccT& acc, const Unit& u, int wr, int wc, int fr, int fq) const {
;         const int pn = u.pn;
;         if (pn < 36) {
;             bf16_t* base; int ld;
;             if (pn < 4) { base = (pn < 2 ? CQ : CKV) + (pn & 1) * 256; ld = 512; }
;             else if (pn < 16) { base = QKVG + (pn - 4) * 256; ld = 3072; }
;             else if (pn < 20) { base = Z + (pn - 16) * 256; ld = 1024; }
;             else { base = GATE + (pn - 20) * 256; ld = 4096; }
;             base += wc * 32 + fq * 8;
; #pragma unroll
;             for (int ai = 0; ai < 2; ++ai)
; #pragma unroll
;                 for (int m = 0; m < 4; ++m) {
;                     const int row = u.pm * 256 + ai * 128 + wr * 64 + m * 16 + fr;
;                     bf16_t* dst = base + (size_t)row * ld; float s = 0.f;
; #pragma unroll
;                     for (int bj = 0; bj < 2; ++bj) { f32x4 v0 = acc[ai][bj][m][0], v1 = acc[ai][bj][m][1];
;                         if (pn < 4) s += (v0[0] * v0[0] + v0[1] * v0[1]) + (v0[2] * v0[2] + v0[3] * v0[3]) + (v1[0] * v1[0] + v1[1] * v1[1]) + (v1[2] * v1[2] + v1[3] * v1[3]);
;                         if (pn >= 20) {
; #pragma unroll
;                             for (int j = 0; j < 4; ++j) { v0[j] = sigmoidf_(v0[j]); v1[j] = sigmoidf_(v1[j]); } }
;                         *(u32x4*)(dst + bj * 128) = pack8u(v0, v1); }
;                     if (pn < 4) { s += swz<16>(s); s = halfsum(s); if (fq == 0) SSQ[(size_t)row * 16 + pn * 4 + wc] = s; }
;                 }
;         } else {
;             const int g8 = wc * 4 + fq;
; #pragma unroll
;             for (int ai = 0; ai < 2; ++ai)
; #pragma unroll
;                 for (int m = 0; m < 4; ++m) {
;                     const int row = u.pm * 256 + ai * 128 + wr * 64 + m * 16 + fr;
;                     const f32x4 v0 = acc[ai][0][m][0], v1 = acc[ai][0][m][1];
;                     if (g8 < 8) {
;                         const int i0 = 4 * g8;
	ds_read_b128 v[170:173], v164 offset:49152
	ds_read_b128 v[174:177], v164 offset:50176
	ds_read_b128 v[178:181], v164 offset:51200
	ds_read_b128 v[182:185], v164 offset:52224
	ds_read_b128 v[186:189], v164 offset:53248
	ds_read_b128 v[190:193], v164 offset:54272
	ds_read_b128 v[194:197], v164 offset:55296
	ds_read_b128 v[198:201], v164 offset:56320
	s_add_u32 s98, s36, 0xfff80080
	s_addc_u32 s99, s37, -1
	global_load_lds_dwordx4 v136, s[98:99]
	s_mov_b32 m0, s83
	s_add_u32 s100, s36, 0xfff80080
	s_addc_u32 s101, s37, -1
	global_load_lds_dwordx4 v140, s[100:101]
	s_barrier
	s_waitcnt lgkmcnt(0)
	s_setprio 1
	v_mfma_f32_16x16x32_bf16 v[60:63], v[128:131], v[170:173], v[60:63]
	v_mfma_f32_16x16x32_bf16 v[56:59], v[156:159], v[170:173], v[56:59]
	v_mfma_f32_16x16x32_bf16 v[44:47], v[128:131], v[178:181], v[44:47]
	v_mfma_f32_16x16x32_bf16 v[40:43], v[156:159], v[178:181], v[40:43]
	v_mfma_f32_16x16x32_bf16 v[28:31], v[128:131], v[186:189], v[28:31]
	v_mfma_f32_16x16x32_bf16 v[24:27], v[156:159], v[186:189], v[24:27]
	v_mfma_f32_16x16x32_bf16 v[12:15], v[128:131], v[194:197], v[12:15]
	v_mfma_f32_16x16x32_bf16 v[8:11], v[156:159], v[194:197], v[8:11]
	v_mfma_f32_16x16x32_bf16 v[60:63], v[132:135], v[174:177], v[60:63]
	v_mfma_f32_16x16x32_bf16 v[56:59], v[166:169], v[174:177], v[56:59]
	v_mfma_f32_16x16x32_bf16 v[44:47], v[132:135], v[182:185], v[44:47]
	v_mfma_f32_16x16x32_bf16 v[40:43], v[166:169], v[182:185], v[40:43]
	v_mfma_f32_16x16x32_bf16 v[28:31], v[132:135], v[190:193], v[28:31]
	v_mfma_f32_16x16x32_bf16 v[24:27], v[166:169], v[190:193], v[24:27]
	v_mfma_f32_16x16x32_bf16 v[12:15], v[132:135], v[198:201], v[12:15]
	v_mfma_f32_16x16x32_bf16 v[8:11], v[166:169], v[198:201], v[8:11]
	s_setprio 0
	s_barrier
	s_add_u32 s28, s28, 0x80080
	s_addc_u32 s29, s29, 0
	s_add_i32 s34, s35, s71
	s_mov_b32 m0, s34
	s_nop 0
	global_load_lds_dwordx4 v138, s[28:29]
	s_add_i32 m0, s34, 0x2000
	s_nop 0
	global_load_lds_dwordx4 v142, s[28:29]
	s_waitcnt vmcnt(6)
	s_barrier
	s_setprio 1
	v_mfma_f32_16x16x32_bf16 v[52:55], v[202:205], v[170:173], v[52:55]
	v_mfma_f32_16x16x32_bf16 v[48:51], v[242:245], v[170:173], v[48:51]
	v_mfma_f32_16x16x32_bf16 v[36:39], v[202:205], v[178:181], v[36:39]
	v_mfma_f32_16x16x32_bf16 v[32:35], v[242:245], v[178:181], v[32:35]
	v_mfma_f32_16x16x32_bf16 v[20:23], v[202:205], v[186:189], v[20:23]
	v_mfma_f32_16x16x32_bf16 v[16:19], v[242:245], v[186:189], v[16:19]
	v_mfma_f32_16x16x32_bf16 v[4:7], v[202:205], v[194:197], v[4:7]
	v_mfma_f32_16x16x32_bf16 v[0:3], v[242:245], v[194:197], v[0:3]
	v_mfma_f32_16x16x32_bf16 v[52:55], v[238:241], v[174:177], v[52:55]
	v_mfma_f32_16x16x32_bf16 v[48:51], v[246:249], v[174:177], v[48:51]
	v_mfma_f32_16x16x32_bf16 v[36:39], v[238:241], v[182:185], v[36:39]
	v_mfma_f32_16x16x32_bf16 v[32:35], v[246:249], v[182:185], v[32:35]
	v_mfma_f32_16x16x32_bf16 v[20:23], v[238:241], v[190:193], v[20:23]
	v_mfma_f32_16x16x32_bf16 v[16:19], v[246:249], v[190:193], v[16:19]
	v_mfma_f32_16x16x32_bf16 v[4:7], v[238:241], v[198:201], v[4:7]
	v_mfma_f32_16x16x32_bf16 v[0:3], v[246:249], v[198:201], v[0:3]
	s_setprio 0
	s_add_i32 s39, s39, 2
	s_add_u32 s26, s26, 0x100
	s_addc_u32 s27, s27, 0
	s_add_u32 s31, s31, 0x100
	s_addc_u32 s38, s38, 0
	s_cmp_gt_u32 s39, 29
	s_barrier
	s_cbranch_scc0 .LBB0_672
	s_mov_b64 s[26:27], -1
	s_cmp_gt_i32 s64, 35
	v_lshl_add_u32 v156, s46, 8, v162
	s_movk_i32 s95, 0x1ff
	s_cbranch_scc0 .LBB0_723
	s_and_b64 vcc, exec, s[52:53]
	s_cbranch_vccz .LBB0_678
	s_and_saveexec_b64 s[26:27], s[54:55]
	s_cbranch_execz .LBB0_677
	v_ashrrev_i32_e32 v157, 31, v156
	v_lshlrev_b64 v[128:129], 6, v[156:157]
	v_lshl_add_u64 v[128:129], v[144:145], 0, v[128:129]
	global_store_dwordx4 v[128:129], v[124:127], off offset:-256
	global_store_dwordx4 v[128:129], v[120:123], off offset:-240

; #define PG8_STAGE(bufoff, gbase, voff) do { _Pragma("unroll") for (int _i = 0; _i < 2; ++_i) \
;         __builtin_amdgcn_global_load_lds((const unsigned*)((const char*)(gbase) + (voff)[_i]), (LAS unsigned*)(lds + (bufoff) + ldsw + _i * 8192), 16, 0, 0); } while (0)
; #define PG8_LDA(dst, b, h) do { _Pragma("unroll") for (int m = 0; m < 4; ++m) _Pragma("unroll") for (int k = 0; k < 2; ++k) dst[m][k] = *(const LAS bf16x8*)(lds + PG8_SA(b, h) + aoff + m * 2048 + k * 1024); } while (0)
; #define PG8_LDB(dst, b, h) do { _Pragma("unroll") for (int n = 0; n < 2; ++n) _Pragma("unroll") for (int k = 0; k < 2; ++k) dst[n][k] = *(const LAS bf16x8*)(lds + PG8_SB(b, h) + boff + n * 2048 + k * 1024); } while (0)
; #define PG8_MMA(ai, bj, At, Bt) do { __builtin_amdgcn_s_setprio(1); _Pragma("unroll") for (int m = 0; m < 4; ++m) _Pragma("unroll") for (int n = 0; n < 2; ++n) _Pragma("unroll") for (int k = 0; k < 2; ++k) \
;         acc[ai][bj][m][n] = __builtin_amdgcn_mfma_f32_16x16x32_bf16(Bt[n][k], At[m][k], acc[ai][bj][m][n], 0, 0, 0); __builtin_amdgcn_s_setprio(0); } while (0)
; #define PG8_WAIT_V(n) asm volatile("s_waitcnt vmcnt(" #n ")" ::: "memory")
; #define PG8_WAIT_L(n) asm volatile("s_waitcnt lgkmcnt(" #n ")" ::: "memory")
; #define PG8_BAR __builtin_amdgcn_s_barrier()
; #define PG8_SCHED __builtin_amdgcn_sched_barrier(0)
; template <class Epi>
; __device__ __forceinline__ void gemm_phase(LAS unsigned char* lds, const Gemm g, const Epi& E) {
;     ...
;             PG8_LDB(B0, 0, 0); PG8_SCHED; PG8_LDA(At, 0, 0); PG8_STAGE(PG8_SA(1, 1), a1 + hstep, voffA);
;             PG8_WAIT_L(8); PG8_BAR; PG8_WAIT_L(0); PG8_MMA(0, 0, At, B0); PG8_BAR; PG8_SCHED;
;             PG8_LDB(B1, 0, 1); PG8_STAGE(PG8_SB(0, 0), b2, voffB);
;             PG8_BAR; PG8_WAIT_L(0); PG8_MMA(0, 1, At, B1); PG8_BAR;
;             PG8_LDA(At, 0, 1); PG8_STAGE(PG8_SA(0, 0), a2, voffA);
;             PG8_BAR; PG8_WAIT_L(0); PG8_MMA(1, 0, At, B0); PG8_BAR; PG8_SCHED;
;             PG8_STAGE(PG8_SB(0, 1), b2 + hstep, voffB);
;             PG8_WAIT_V(6); PG8_BAR; PG8_MMA(1, 1, At, B1); PG8_BAR;
.LBB0_873:
	s_add_u32 s28, s26, 0x100
	s_addc_u32 s29, s27, 0
	s_add_i32 s34, 0, 0x10000
	v_add_u32_e32 v140, s34, v160
	ds_read_b128 v[128:131], v140
	ds_read_b128 v[132:135], v140 offset:1024
	ds_read_b128 v[136:139], v140 offset:2048
	ds_read_b128 v[140:143], v140 offset:3072
	s_cmpk_eq_i32 s82, 0x54
	s_cselect_b32 s39, s1, s29
	s_cselect_b32 s38, s0, s28
	s_cselect_b32 s37, s43, s79
	s_cselect_b32 s36, s42, s78
	s_add_i32 m0, s44, 0xc000
	ds_read_b128 v[156:159], v161
	ds_read_b128 v[164:167], v161 offset:1024
	ds_read_b128 v[168:171], v161 offset:2048
	ds_read_b128 v[172:175], v161 offset:3072
	ds_read_b128 v[176:179], v161 offset:4096
	ds_read_b128 v[180:183], v161 offset:5120
	ds_read_b128 v[184:187], v161 offset:6144
	ds_read_b128 v[188:191], v161 offset:7168
	global_load_lds_dwordx4 v152, s[26:27]
	s_add_i32 m0, s44, 0xe000
	s_nop 0
	global_load_lds_dwordx4 v154, s[26:27]
	s_waitcnt lgkmcnt(8)
	s_barrier
	s_waitcnt lgkmcnt(0)
	s_setprio 1
	v_mfma_f32_16x16x32_bf16 v[124:127], v[128:131], v[156:159], v[124:127]
	v_mfma_f32_16x16x32_bf16 v[120:123], v[136:139], v[156:159], v[120:123]
	v_mfma_f32_16x16x32_bf16 v[108:111], v[128:131], v[168:171], v[108:111]
	v_mfma_f32_16x16x32_bf16 v[104:107], v[136:139], v[168:171], v[104:107]
	v_mfma_f32_16x16x32_bf16 v[92:95], v[128:131], v[176:179], v[92:95]
	v_mfma_f32_16x16x32_bf16 v[88:91], v[136:139], v[176:179], v[88:91]
	v_mfma_f32_16x16x32_bf16 v[76:79], v[128:131], v[184:187], v[76:79]
	v_mfma_f32_16x16x32_bf16 v[72:75], v[136:139], v[184:187], v[72:75]
	v_mfma_f32_16x16x32_bf16 v[124:127], v[132:135], v[164:167], v[124:127]
	v_mfma_f32_16x16x32_bf16 v[120:123], v[140:143], v[164:167], v[120:123]
	v_mfma_f32_16x16x32_bf16 v[108:111], v[132:135], v[172:175], v[108:111]
	v_mfma_f32_16x16x32_bf16 v[104:107], v[140:143], v[172:175], v[104:107]
	v_mfma_f32_16x16x32_bf16 v[92:95], v[132:135], v[180:183], v[92:95]
	v_mfma_f32_16x16x32_bf16 v[88:91], v[140:143], v[180:183], v[88:91]
	v_mfma_f32_16x16x32_bf16 v[76:79], v[132:135], v[188:191], v[76:79]
	v_mfma_f32_16x16x32_bf16 v[72:75], v[140:143], v[188:191], v[72:75]
	s_setprio 0
	s_barrier
	s_add_i32 s35, 0, 0x14000
	s_add_i32 s26, s34, s31
	v_add_u32_e32 v163, s35, v160
	s_mov_b32 m0, s26
	ds_read_b128 v[192:195], v163
	ds_read_b128 v[196:199], v163 offset:1024
	ds_read_b128 v[200:203], v163 offset:2048
	ds_read_b128 v[204:207], v163 offset:3072
	global_load_lds_dwordx4 v208, s[36:37]
	s_add_i32 m0, s26, 0x2000
	s_nop 0
	global_load_lds_dwordx4 v148, s[36:37]
	s_barrier
	s_waitcnt lgkmcnt(0)
	s_setprio 1
	v_mfma_f32_16x16x32_bf16 v[116:119], v[192:195], v[156:159], v[116:119]
	v_mfma_f32_16x16x32_bf16 v[112:115], v[200:203], v[156:159], v[112:115]
	v_mfma_f32_16x16x32_bf16 v[100:103], v[192:195], v[168:171], v[100:103]
	v_mfma_f32_16x16x32_bf16 v[96:99], v[200:203], v[168:171], v[96:99]
	v_mfma_f32_16x16x32_bf16 v[84:87], v[192:195], v[176:179], v[84:87]
	v_mfma_f32_16x16x32_bf16 v[80:83], v[200:203], v[176:179], v[80:83]
	v_mfma_f32_16x16x32_bf16 v[68:71], v[192:195], v[184:187], v[68:71]
	v_mfma_f32_16x16x32_bf16 v[64:67], v[200:203], v[184:187], v[64:67]
	v_mfma_f32_16x16x32_bf16 v[116:119], v[196:199], v[164:167], v[116:119]
	v_mfma_f32_16x16x32_bf16 v[112:115], v[204:207], v[164:167], v[112:115]
	v_mfma_f32_16x16x32_bf16 v[100:103], v[196:199], v[172:175], v[100:103]
	v_mfma_f32_16x16x32_bf16 v[96:99], v[204:207], v[172:175], v[96:99]
	v_mfma_f32_16x16x32_bf16 v[84:87], v[196:199], v[180:183], v[84:87]
	v_mfma_f32_16x16x32_bf16 v[80:83], v[204:207], v[180:183], v[80:83]
	v_mfma_f32_16x16x32_bf16 v[68:71], v[196:199], v[188:191], v[68:71]
	v_mfma_f32_16x16x32_bf16 v[64:67], v[204:207], v[188:191], v[64:67]
	s_setprio 0
	s_mov_b32 m0, s44
	s_barrier
	ds_read_b128 v[156:159], v161 offset:16384
	ds_read_b128 v[164:167], v161 offset:17408
	ds_read_b128 v[168:171], v161 offset:18432
	ds_read_b128 v[172:175], v161 offset:19456
	ds_read_b128 v[176:179], v161 offset:20480
	ds_read_b128 v[180:183], v161 offset:21504
	ds_read_b128 v[184:187], v161 offset:22528
	ds_read_b128 v[188:191], v161 offset:23552
	global_load_lds_dwordx4 v144, s[38:39]
	s_mov_b32 m0, s45
	s_nop 0
	global_load_lds_dwordx4 v146, s[38:39]
	s_barrier
	s_waitcnt lgkmcnt(0)
	s_setprio 1
	v_mfma_f32_16x16x32_bf16 v[60:63], v[128:131], v[156:159], v[60:63]
	v_mfma_f32_16x16x32_bf16 v[56:59], v[136:139], v[156:159], v[56:59]
	v_mfma_f32_16x16x32_bf16 v[44:47], v[128:131], v[168:171], v[44:47]
	v_mfma_f32_16x16x32_bf16 v[40:43], v[136:139], v[168:171], v[40:43]
	v_mfma_f32_16x16x32_bf16 v[28:31], v[128:131], v[176:179], v[28:31]
	v_mfma_f32_16x16x32_bf16 v[24:27], v[136:139], v[176:179], v[24:27]
	v_mfma_f32_16x16x32_bf16 v[12:15], v[128:131], v[184:187], v[12:15]
	v_mfma_f32_16x16x32_bf16 v[8:11], v[136:139], v[184:187], v[8:11]
	v_mfma_f32_16x16x32_bf16 v[60:63], v[132:135], v[164:167], v[60:63]
	v_mfma_f32_16x16x32_bf16 v[56:59], v[140:143], v[164:167], v[56:59]
	v_mfma_f32_16x16x32_bf16 v[44:47], v[132:135], v[172:175], v[44:47]
	v_mfma_f32_16x16x32_bf16 v[40:43], v[140:143], v[172:175], v[40:43]
	v_mfma_f32_16x16x32_bf16 v[28:31], v[132:135], v[180:183], v[28:31]
	v_mfma_f32_16x16x32_bf16 v[24:27], v[140:143], v[180:183], v[24:27]
	v_mfma_f32_16x16x32_bf16 v[12:15], v[132:135], v[188:191], v[12:15]
	v_mfma_f32_16x16x32_bf16 v[8:11], v[140:143], v[188:191], v[8:11]
	s_setprio 0
	s_barrier
	s_add_u32 s26, s36, 0x160000
	s_addc_u32 s27, s37, 0
	s_add_i32 s34, s35, s31
	s_mov_b32 m0, s34
	s_nop 0
	global_load_lds_dwordx4 v208, s[26:27]
	s_add_i32 m0, s34, 0x2000
	s_nop 0
	global_load_lds_dwordx4 v148, s[26:27]
	s_waitcnt vmcnt(6)
	s_barrier
; #define PG8_STAGE(bufoff, gbase, voff) do { _Pragma("unroll") for (int _i = 0; _i < 2; ++_i) \
;         __builtin_amdgcn_global_load_lds((const unsigned*)((const char*)(gbase) + (voff)[_i]), (LAS unsigned*)(lds + (bufoff) + ldsw + _i * 8192), 16, 0, 0); } while (0)
; #define PG8_LDA(dst, b, h) do { _Pragma("unroll") for (int m = 0; m < 4; ++m) _Pragma("unroll") for (int k = 0; k < 2; ++k) dst[m][k] = *(const LAS bf16x8*)(lds + PG8_SA(b, h) + aoff + m * 2048 + k * 1024); } while (0)
; #define PG8_LDB(dst, b, h) do { _Pragma("unroll") for (int n = 0; n < 2; ++n) _Pragma("unroll") for (int k = 0; k < 2; ++k) dst[n][k] = *(const LAS bf16x8*)(lds + PG8_SB(b, h) + boff + n * 2048 + k * 1024); } while (0)
; #define PG8_MMA(ai, bj, At, Bt) do { __builtin_amdgcn_s_setprio(1); _Pragma("unroll") for (int m = 0; m < 4; ++m) _Pragma("unroll") for (int n = 0; n < 2; ++n) _Pragma("unroll") for (int k = 0; k < 2; ++k) \
;         acc[ai][bj][m][n] = __builtin_amdgcn_mfma_f32_16x16x32_bf16(Bt[n][k], At[m][k], acc[ai][bj][m][n], 0, 0, 0); __builtin_amdgcn_s_setprio(0); } while (0)
; #define PG8_WAIT_V(n) asm volatile("s_waitcnt vmcnt(" #n ")" ::: "memory")
; #define PG8_WAIT_L(n) asm volatile("s_waitcnt lgkmcnt(" #n ")" ::: "memory")
; #define PG8_BAR __builtin_amdgcn_s_barrier()
; #define PG8_SCHED __builtin_amdgcn_sched_barrier(0)
; template <class Epi>
; __device__ __forceinline__ void gemm_phase(LAS unsigned char* lds, const Gemm g, const Epi& E) {
;     ...
;             PG8_WAIT_V(6); PG8_BAR; PG8_MMA(1, 1, At, B1); PG8_BAR;
;             PG8_LDB(B0, 1, 0); PG8_SCHED; PG8_LDA(At, 1, 0); PG8_STAGE(PG8_SA(0, 1), a2 + hstep, voffA);
;             PG8_WAIT_L(8); PG8_BAR; PG8_WAIT_L(0); PG8_MMA(0, 0, At, B0); PG8_BAR; PG8_SCHED;
;             PG8_LDB(B1, 1, 1); PG8_STAGE(PG8_SB(1, 0), b3, voffB);
;             PG8_BAR; PG8_WAIT_L(0); PG8_MMA(0, 1, At, B1); PG8_BAR;
;             PG8_LDA(At, 1, 1); PG8_STAGE(PG8_SA(1, 0), a3, voffA);
;             PG8_BAR; PG8_WAIT_L(0); PG8_MMA(1, 0, At, B0); PG8_BAR; PG8_SCHED;
;             PG8_STAGE(PG8_SB(1, 1), b3 + hstep, voffB);
	s_setprio 1
	v_mfma_f32_16x16x32_bf16 v[52:55], v[192:195], v[156:159], v[52:55]
	v_mfma_f32_16x16x32_bf16 v[48:51], v[200:203], v[156:159], v[48:51]
	v_mfma_f32_16x16x32_bf16 v[36:39], v[192:195], v[168:171], v[36:39]
	v_mfma_f32_16x16x32_bf16 v[32:35], v[200:203], v[168:171], v[32:35]
	v_mfma_f32_16x16x32_bf16 v[20:23], v[192:195], v[176:179], v[20:23]
	v_mfma_f32_16x16x32_bf16 v[16:19], v[200:203], v[176:179], v[16:19]
	v_mfma_f32_16x16x32_bf16 v[4:7], v[192:195], v[184:187], v[4:7]
	v_mfma_f32_16x16x32_bf16 v[0:3], v[200:203], v[184:187], v[0:3]
	v_mfma_f32_16x16x32_bf16 v[52:55], v[196:199], v[164:167], v[52:55]
	v_mfma_f32_16x16x32_bf16 v[48:51], v[204:207], v[164:167], v[48:51]
	v_mfma_f32_16x16x32_bf16 v[36:39], v[196:199], v[172:175], v[36:39]
	v_mfma_f32_16x16x32_bf16 v[32:35], v[204:207], v[172:175], v[32:35]
	v_mfma_f32_16x16x32_bf16 v[20:23], v[196:199], v[180:183], v[20:23]
	v_mfma_f32_16x16x32_bf16 v[16:19], v[204:207], v[180:183], v[16:19]
	v_mfma_f32_16x16x32_bf16 v[4:7], v[196:199], v[188:191], v[4:7]
	v_mfma_f32_16x16x32_bf16 v[0:3], v[204:207], v[188:191], v[0:3]
	s_setprio 0
	s_add_i32 s34, 0, 0x18000
	v_add_u32_e32 v140, s34, v160
	s_barrier
	ds_read_b128 v[128:131], v140
	ds_read_b128 v[132:135], v140 offset:1024
	ds_read_b128 v[136:139], v140 offset:2048
	ds_read_b128 v[140:143], v140 offset:3072
	s_add_u32 s26, s38, 0x160000
	s_addc_u32 s27, s39, 0
	s_mov_b32 m0, s46
	ds_read_b128 v[156:159], v161 offset:32768
	ds_read_b128 v[164:167], v161 offset:33792
	ds_read_b128 v[168:171], v161 offset:34816
	ds_read_b128 v[172:175], v161 offset:35840
	ds_read_b128 v[176:179], v161 offset:36864
	ds_read_b128 v[180:183], v161 offset:37888
	ds_read_b128 v[184:187], v161 offset:38912
	ds_read_b128 v[188:191], v161 offset:39936
	global_load_lds_dwordx4 v144, s[26:27]
	s_mov_b32 m0, s47
	s_nop 0
	global_load_lds_dwordx4 v146, s[26:27]
	s_waitcnt lgkmcnt(8)
	s_barrier
	s_waitcnt lgkmcnt(0)
	s_setprio 1
	v_mfma_f32_16x16x32_bf16 v[124:127], v[128:131], v[156:159], v[124:127]
	v_mfma_f32_16x16x32_bf16 v[120:123], v[136:139], v[156:159], v[120:123]
	v_mfma_f32_16x16x32_bf16 v[108:111], v[128:131], v[168:171], v[108:111]
	v_mfma_f32_16x16x32_bf16 v[104:107], v[136:139], v[168:171], v[104:107]
	v_mfma_f32_16x16x32_bf16 v[92:95], v[128:131], v[176:179], v[92:95]
	v_mfma_f32_16x16x32_bf16 v[88:91], v[136:139], v[176:179], v[88:91]
	v_mfma_f32_16x16x32_bf16 v[76:79], v[128:131], v[184:187], v[76:79]
	v_mfma_f32_16x16x32_bf16 v[72:75], v[136:139], v[184:187], v[72:75]
	v_mfma_f32_16x16x32_bf16 v[124:127], v[132:135], v[164:167], v[124:127]
	v_mfma_f32_16x16x32_bf16 v[120:123], v[140:143], v[164:167], v[120:123]
	v_mfma_f32_16x16x32_bf16 v[108:111], v[132:135], v[172:175], v[108:111]
	v_mfma_f32_16x16x32_bf16 v[104:107], v[140:143], v[172:175], v[104:107]
	v_mfma_f32_16x16x32_bf16 v[92:95], v[132:135], v[180:183], v[92:95]
	v_mfma_f32_16x16x32_bf16 v[88:91], v[140:143], v[180:183], v[88:91]
	v_mfma_f32_16x16x32_bf16 v[76:79], v[132:135], v[188:191], v[76:79]
	v_mfma_f32_16x16x32_bf16 v[72:75], v[140:143], v[188:191], v[72:75]
	s_setprio 0
	s_barrier
	s_add_i32 s35, 0, 0x1c000
	s_add_i32 s26, s34, s31
	v_add_u32_e32 v163, s35, v160
	s_mov_b32 m0, s26
	ds_read_b128 v[192:195], v163
	ds_read_b128 v[196:199], v163 offset:1024
	ds_read_b128 v[200:203], v163 offset:2048
	ds_read_b128 v[204:207], v163 offset:3072
	s_add_u32 s98, s36, 0x80
	s_addc_u32 s99, s37, 0
	global_load_lds_dwordx4 v208, s[98:99]
	s_add_i32 m0, s26, 0x2000
	s_add_u32 s100, s36, 0x80
	s_addc_u32 s101, s37, 0
	global_load_lds_dwordx4 v148, s[100:101]
	s_barrier
	s_waitcnt lgkmcnt(0)
	s_setprio 1
	v_mfma_f32_16x16x32_bf16 v[116:119], v[192:195], v[156:159], v[116:119]
	v_mfma_f32_16x16x32_bf16 v[112:115], v[200:203], v[156:159], v[112:115]
	v_mfma_f32_16x16x32_bf16 v[100:103], v[192:195], v[168:171], v[100:103]
	v_mfma_f32_16x16x32_bf16 v[96:99], v[200:203], v[168:171], v[96:99]
	v_mfma_f32_16x16x32_bf16 v[84:87], v[192:195], v[176:179], v[84:87]
	v_mfma_f32_16x16x32_bf16 v[80:83], v[200:203], v[176:179], v[80:83]
	v_mfma_f32_16x16x32_bf16 v[68:71], v[192:195], v[184:187], v[68:71]
	v_mfma_f32_16x16x32_bf16 v[64:67], v[200:203], v[184:187], v[64:67]
	v_mfma_f32_16x16x32_bf16 v[116:119], v[196:199], v[164:167], v[116:119]
	v_mfma_f32_16x16x32_bf16 v[112:115], v[204:207], v[164:167], v[112:115]
	v_mfma_f32_16x16x32_bf16 v[100:103], v[196:199], v[172:175], v[100:103]
	v_mfma_f32_16x16x32_bf16 v[96:99], v[204:207], v[172:175], v[96:99]
	v_mfma_f32_16x16x32_bf16 v[84:87], v[196:199], v[180:183], v[84:87]
	v_mfma_f32_16x16x32_bf16 v[80:83], v[204:207], v[180:183], v[80:83]
	v_mfma_f32_16x16x32_bf16 v[68:71], v[196:199], v[188:191], v[68:71]
	v_mfma_f32_16x16x32_bf16 v[64:67], v[204:207], v[188:191], v[64:67]
	s_setprio 0
	s_mov_b32 m0, s64
	s_barrier
	ds_read_b128 v[156:159], v161 offset:49152
	ds_read_b128 v[164:167], v161 offset:50176
	ds_read_b128 v[168:171], v161 offset:51200
	ds_read_b128 v[172:175], v161 offset:52224
	ds_read_b128 v[176:179], v161 offset:53248
	ds_read_b128 v[180:183], v161 offset:54272
	ds_read_b128 v[184:187], v161 offset:55296
	ds_read_b128 v[188:191], v161 offset:56320
	s_add_u32 s98, s38, 0x80
	s_addc_u32 s99, s39, 0
	global_load_lds_dwordx4 v144, s[98:99]
	s_mov_b32 m0, s65
	s_add_u32 s100, s38, 0x80
	s_addc_u32 s101, s39, 0
	global_load_lds_dwordx4 v146, s[100:101]
	s_barrier
; __device__ __forceinline__ float bflo(unsigned w) { return __uint_as_float(w << 16); }
; __device__ __forceinline__ float bfhi(unsigned w) { return __uint_as_float(w & 0xffff0000u); }
; __device__ __forceinline__ u32x4 pack8u(f32x4 a, f32x4 b) { u32x4 w = {cvt_pk_bf16(a[0], a[1]), cvt_pk_bf16(a[2], a[3]), cvt_pk_bf16(b[0], b[1]), cvt_pk_bf16(b[2], b[3])}; return w; }
; #define PG8_STAGE(bufoff, gbase, voff) do { _Pragma("unroll") for (int _i = 0; _i < 2; ++_i) \
;         __builtin_amdgcn_global_load_lds((const unsigned*)((const char*)(gbase) + (voff)[_i]), (LAS unsigned*)(lds + (bufoff) + ldsw + _i * 8192), 16, 0, 0); } while (0)
; #define PG8_WAIT_V(n) asm volatile("s_waitcnt vmcnt(" #n ")" ::: "memory")
; #define PG8_WAIT_L(n) asm volatile("s_waitcnt lgkmcnt(" #n ")" ::: "memory")
; template <class Epi>
; __device__ __forceinline__ void gemm_phase(LAS unsigned char* lds, const Gemm g, const Epi& E) {
;     ...
;             PG8_BAR; PG8_WAIT_L(0); PG8_MMA(1, 0, At, B0); PG8_BAR; PG8_SCHED;
;             PG8_STAGE(PG8_SB(1, 1), b3 + hstep, voffB);
;             PG8_WAIT_V(6); PG8_BAR; PG8_MMA(1, 1, At, B1); PG8_BAR;
;     __device__ __forceinline__ void operator()(const AccT& acc, const Unit& u, int wr, int wc, int fr, int fq) const {
;         const int b = (u.pm * 256) / SEQ;
;         f32x4 gt[2][2];
; #pragma unroll
;         for (int bj = 0; bj < 2; ++bj)
; #pragma unroll
;             for (int n = 0; n < 2; ++n) gt[bj][n] = *(const f32x4*)(GT + (size_t)b * 6 * D + u.pn * 256 + bj * 128 + wc * 32 + fq * 8 + 4 * n);
; #pragma unroll
;         for (int ai = 0; ai < 2; ++ai)
; #pragma unroll
;             for (int m = 0; m < 4; ++m) {
;                 const int row = u.pm * 256 + ai * 128 + wr * 64 + m * 16 + fr;
; #pragma unroll
;                 for (int bj = 0; bj < 2; ++bj) {
;                     const size_t off = (size_t)row * D + u.pn * 256 + bj * 128 + wc * 32 + fq * 8;
;                     f32x4 x0, x1;
;                     if (XINF) { x0 = *(const f32x4*)(XINF + off); x1 = *(const f32x4*)(XINF + off + 4); }
;                     else { const u32x4 w = *(const u32x4*)(XIN16 + off); x0 = (f32x4){bflo(w[0]), bfhi(w[0]), bflo(w[1]), bfhi(w[1])}; x1 = (f32x4){bflo(w[2]), bfhi(w[2]), bflo(w[3]), bfhi(w[3])}; }
;                     *(u32x4*)(XOUT + off) = pack8u(x0 + gt[bj][0] * acc[ai][bj][m][0], x1 + gt[bj][1] * acc[ai][bj][m][1]);
	s_waitcnt lgkmcnt(0)
	s_setprio 1
	v_mfma_f32_16x16x32_bf16 v[60:63], v[128:131], v[156:159], v[60:63]
	v_mfma_f32_16x16x32_bf16 v[56:59], v[136:139], v[156:159], v[56:59]
	v_mfma_f32_16x16x32_bf16 v[44:47], v[128:131], v[168:171], v[44:47]
	v_mfma_f32_16x16x32_bf16 v[40:43], v[136:139], v[168:171], v[40:43]
	v_mfma_f32_16x16x32_bf16 v[28:31], v[128:131], v[176:179], v[28:31]
	v_mfma_f32_16x16x32_bf16 v[24:27], v[136:139], v[176:179], v[24:27]
	v_mfma_f32_16x16x32_bf16 v[12:15], v[128:131], v[184:187], v[12:15]
	v_mfma_f32_16x16x32_bf16 v[8:11], v[136:139], v[184:187], v[8:11]
	v_mfma_f32_16x16x32_bf16 v[60:63], v[132:135], v[164:167], v[60:63]
	v_mfma_f32_16x16x32_bf16 v[56:59], v[140:143], v[164:167], v[56:59]
	v_mfma_f32_16x16x32_bf16 v[44:47], v[132:135], v[172:175], v[44:47]
	v_mfma_f32_16x16x32_bf16 v[40:43], v[140:143], v[172:175], v[40:43]
	v_mfma_f32_16x16x32_bf16 v[28:31], v[132:135], v[180:183], v[28:31]
	v_mfma_f32_16x16x32_bf16 v[24:27], v[140:143], v[180:183], v[24:27]
	v_mfma_f32_16x16x32_bf16 v[12:15], v[132:135], v[188:191], v[12:15]
	v_mfma_f32_16x16x32_bf16 v[8:11], v[140:143], v[188:191], v[8:11]
	s_setprio 0
	s_barrier
	s_add_u32 s26, s36, 0x160080
	s_addc_u32 s27, s37, 0
	s_add_i32 s34, s35, s31
	s_mov_b32 m0, s34
	s_nop 0
	global_load_lds_dwordx4 v208, s[26:27]
	s_add_i32 m0, s34, 0x2000
	s_nop 0
	global_load_lds_dwordx4 v148, s[26:27]
	s_waitcnt vmcnt(6)
	s_barrier
	s_setprio 1
	v_mfma_f32_16x16x32_bf16 v[52:55], v[192:195], v[156:159], v[52:55]
	v_mfma_f32_16x16x32_bf16 v[48:51], v[200:203], v[156:159], v[48:51]
	v_mfma_f32_16x16x32_bf16 v[36:39], v[192:195], v[168:171], v[36:39]
	v_mfma_f32_16x16x32_bf16 v[32:35], v[200:203], v[168:171], v[32:35]
	v_mfma_f32_16x16x32_bf16 v[20:23], v[192:195], v[176:179], v[20:23]
	v_mfma_f32_16x16x32_bf16 v[16:19], v[200:203], v[176:179], v[16:19]
	v_mfma_f32_16x16x32_bf16 v[4:7], v[192:195], v[184:187], v[4:7]
	v_mfma_f32_16x16x32_bf16 v[0:3], v[200:203], v[184:187], v[0:3]
	v_mfma_f32_16x16x32_bf16 v[52:55], v[196:199], v[164:167], v[52:55]
	v_mfma_f32_16x16x32_bf16 v[48:51], v[204:207], v[164:167], v[48:51]
	v_mfma_f32_16x16x32_bf16 v[36:39], v[196:199], v[172:175], v[36:39]
	v_mfma_f32_16x16x32_bf16 v[32:35], v[204:207], v[172:175], v[32:35]
	v_mfma_f32_16x16x32_bf16 v[20:23], v[196:199], v[180:183], v[20:23]
	v_mfma_f32_16x16x32_bf16 v[16:19], v[204:207], v[180:183], v[16:19]
	v_mfma_f32_16x16x32_bf16 v[4:7], v[196:199], v[188:191], v[4:7]
	v_mfma_f32_16x16x32_bf16 v[0:3], v[204:207], v[188:191], v[0:3]
	s_setprio 0
	s_add_i32 s82, s82, 2
	s_add_u32 s78, s78, 0x100
	s_addc_u32 s79, s79, 0
	s_cmpk_gt_u32 s82, 0x55
	s_mov_b64 s[26:27], s[28:29]
	s_barrier
	s_cbranch_scc0 .LBB0_873
	s_ashr_i32 s26, s74, 31
	s_lshr_b32 s26, s26, 29
	s_add_i32 s26, s74, s26
	s_ashr_i32 s26, s26, 3
	s_mul_i32 s26, s26, 6
	s_ashr_i32 s27, s26, 31
	s_lshl_b64 s[26:27], s[26:27], 13
	s_add_u32 s28, s48, s26
	s_addc_u32 s29, s49, s27
	s_lshl_b32 s26, s76, 8
	s_ashr_i32 s27, s26, 31
	v_lshl_add_u32 v157, s74, 8, v151
	v_or_b32_e32 v158, s26, v150
	s_lshl_b64 s[26:27], s[26:27], 2
	s_add_u32 s26, s28, s26
	s_addc_u32 s27, s29, s27
	s_add_u32 s26, s26, s69
	s_addc_u32 s27, s27, 0
	global_load_dwordx4 v[140:143], v162, s[26:27]
	global_load_dwordx4 v[136:139], v162, s[26:27] offset:16
	global_load_dwordx4 v[132:135], v162, s[26:27] offset:512
	global_load_dwordx4 v[128:131], v162, s[26:27] offset:528
	v_lshlrev_b32_e32 v156, 1, v158
	v_lshl_add_u32 v156, v157, 12, v156
	v_add_u32_e32 v157, 0x0, v156
	global_load_dwordx4 v[164:167], v157, s[96:97] offset:0
	v_add_u32_e32 v157, 0x0, v156
	global_load_dwordx4 v[168:171], v157, s[96:97] offset:256
	v_add_u32_e32 v157, 0x10000, v156
	global_load_dwordx4 v[172:175], v157, s[96:97] offset:0
	v_add_u32_e32 v157, 0x10000, v156
	global_load_dwordx4 v[184:187], v157, s[96:97] offset:256
	v_add_u32_e32 v157, 0x20000, v156
	global_load_dwordx4 v[188:191], v157, s[96:97] offset:0
	v_add_u32_e32 v157, 0x20000, v156
	global_load_dwordx4 v[192:195], v157, s[96:97] offset:256
	v_add_u32_e32 v157, 0x30000, v156
	global_load_dwordx4 v[196:199], v157, s[96:97] offset:0
	v_add_u32_e32 v157, 0x30000, v156
	global_load_dwordx4 v[200:203], v157, s[96:97] offset:256
	v_add_u32_e32 v157, 0x80000, v156
	global_load_dwordx4 v[204:207], v157, s[96:97] offset:0
	v_add_u32_e32 v157, 0x80000, v156
	global_load_dwordx4 v[228:231], v157, s[96:97] offset:256
	s_waitcnt vmcnt(9)
	v_lshlrev_b32_e32 v176, 16, v164
	v_and_b32_e32 v177, 0xffff0000, v164
	v_lshlrev_b32_e32 v178, 16, v165
	v_and_b32_e32 v179, 0xffff0000, v165
	v_lshlrev_b32_e32 v180, 16, v166
	v_and_b32_e32 v181, 0xffff0000, v166
	v_lshlrev_b32_e32 v182, 16, v167
	v_and_b32_e32 v183, 0xffff0000, v167
	v_pk_fma_f32 v[124:125], v[124:125], v[140:141], v[176:177]
	v_pk_fma_f32 v[126:127], v[126:127], v[142:143], v[178:179]
	v_pk_fma_f32 v[120:121], v[120:121], v[136:137], v[180:181]
	v_pk_fma_f32 v[122:123], v[122:123], v[138:139], v[182:183]
	v_cvt_pk_bf16_f32 v124, v124, v125
	v_cvt_pk_bf16_f32 v125, v126, v127
	v_cvt_pk_bf16_f32 v126, v120, v121
	v_cvt_pk_bf16_f32 v127, v122, v123
	v_add_u32_e32 v158, 0x0, v156
	global_store_dwordx4 v158, v[124:127], s[96:97] offset:0
	v_add_u32_e32 v157, 0x90000, v156
	global_load_dwordx4 v[164:167], v157, s[96:97] offset:0
	v_add_u32_e32 v157, 0x90000, v156
	global_load_dwordx4 v[120:123], v157, s[96:97] offset:256
	s_waitcnt vmcnt(11)
; __device__ __forceinline__ float bflo(unsigned w) { return __uint_as_float(w << 16); }
; __device__ __forceinline__ float bfhi(unsigned w) { return __uint_as_float(w & 0xffff0000u); }
; __device__ __forceinline__ u32x4 pack8u(f32x4 a, f32x4 b) { u32x4 w = {cvt_pk_bf16(a[0], a[1]), cvt_pk_bf16(a[2], a[3]), cvt_pk_bf16(b[0], b[1]), cvt_pk_bf16(b[2], b[3])}; return w; }
;     __device__ __forceinline__ void operator()(const AccT& acc, const Unit& u, int wr, int wc, int fr, int fq) const {
;     ...
;                 for (int bj = 0; bj < 2; ++bj) {
;                     const size_t off = (size_t)row * D + u.pn * 256 + bj * 128 + wc * 32 + fq * 8;
;                     f32x4 x0, x1;
;                     if (XINF) { x0 = *(const f32x4*)(XINF + off); x1 = *(const f32x4*)(XINF + off + 4); }
;                     else { const u32x4 w = *(const u32x4*)(XIN16 + off); x0 = (f32x4){bflo(w[0]), bfhi(w[0]), bflo(w[1]), bfhi(w[1])}; x1 = (f32x4){bflo(w[2]), bfhi(w[2]), bflo(w[3]), bfhi(w[3])}; }
;                     *(u32x4*)(XOUT + off) = pack8u(x0 + gt[bj][0] * acc[ai][bj][m][0], x1 + gt[bj][1] * acc[ai][bj][m][1]);
	v_lshlrev_b32_e32 v176, 16, v168
	v_and_b32_e32 v177, 0xffff0000, v168
	v_lshlrev_b32_e32 v178, 16, v169
	v_and_b32_e32 v179, 0xffff0000, v169
	v_lshlrev_b32_e32 v180, 16, v170
	v_and_b32_e32 v181, 0xffff0000, v170
	v_lshlrev_b32_e32 v182, 16, v171
	v_and_b32_e32 v183, 0xffff0000, v171
	v_pk_fma_f32 v[116:117], v[116:117], v[132:133], v[176:177]
	v_pk_fma_f32 v[118:119], v[118:119], v[134:135], v[178:179]
	v_pk_fma_f32 v[112:113], v[112:113], v[128:129], v[180:181]
	v_pk_fma_f32 v[114:115], v[114:115], v[130:131], v[182:183]
	v_cvt_pk_bf16_f32 v116, v116, v117
	v_cvt_pk_bf16_f32 v117, v118, v119
	v_cvt_pk_bf16_f32 v118, v112, v113
	v_cvt_pk_bf16_f32 v119, v114, v115
	v_add_u32_e32 v158, 0x0, v156
	global_store_dwordx4 v158, v[116:119], s[96:97] offset:256
	v_add_u32_e32 v157, 0xa0000, v156
	global_load_dwordx4 v[168:171], v157, s[96:97] offset:0
	v_add_u32_e32 v157, 0xa0000, v156
	global_load_dwordx4 v[112:115], v157, s[96:97] offset:256
	s_waitcnt vmcnt(13)
	v_lshlrev_b32_e32 v176, 16, v172
	v_and_b32_e32 v177, 0xffff0000, v172
	v_lshlrev_b32_e32 v178, 16, v173
	v_and_b32_e32 v179, 0xffff0000, v173
	v_lshlrev_b32_e32 v180, 16, v174
	v_and_b32_e32 v181, 0xffff0000, v174
	v_lshlrev_b32_e32 v182, 16, v175
	v_and_b32_e32 v183, 0xffff0000, v175
	v_pk_fma_f32 v[108:109], v[108:109], v[140:141], v[176:177]
	v_pk_fma_f32 v[110:111], v[110:111], v[142:143], v[178:179]
	v_pk_fma_f32 v[104:105], v[104:105], v[136:137], v[180:181]
	v_pk_fma_f32 v[106:107], v[106:107], v[138:139], v[182:183]
	v_cvt_pk_bf16_f32 v108, v108, v109
	v_cvt_pk_bf16_f32 v109, v110, v111
	v_cvt_pk_bf16_f32 v110, v104, v105
	v_cvt_pk_bf16_f32 v111, v106, v107
	v_add_u32_e32 v158, 0x10000, v156
	global_store_dwordx4 v158, v[108:111], s[96:97] offset:0
	v_add_u32_e32 v157, 0xb0000, v156
	global_load_dwordx4 v[172:175], v157, s[96:97] offset:0
	v_add_u32_e32 v157, 0xb0000, v156
	global_load_dwordx4 v[104:107], v157, s[96:97] offset:256
	s_waitcnt vmcnt(15)
	v_lshlrev_b32_e32 v176, 16, v184
	v_and_b32_e32 v177, 0xffff0000, v184
	v_lshlrev_b32_e32 v178, 16, v185
	v_and_b32_e32 v179, 0xffff0000, v185
	v_lshlrev_b32_e32 v180, 16, v186
	v_and_b32_e32 v181, 0xffff0000, v186
	v_lshlrev_b32_e32 v182, 16, v187
	v_and_b32_e32 v183, 0xffff0000, v187
	v_pk_fma_f32 v[100:101], v[100:101], v[132:133], v[176:177]
	v_pk_fma_f32 v[102:103], v[102:103], v[134:135], v[178:179]
	v_pk_fma_f32 v[96:97], v[96:97], v[128:129], v[180:181]
	v_pk_fma_f32 v[98:99], v[98:99], v[130:131], v[182:183]
	v_cvt_pk_bf16_f32 v100, v100, v101
	v_cvt_pk_bf16_f32 v101, v102, v103
	v_cvt_pk_bf16_f32 v102, v96, v97
	v_cvt_pk_bf16_f32 v103, v98, v99
	v_add_u32_e32 v158, 0x10000, v156
	global_store_dwordx4 v158, v[100:103], s[96:97] offset:256
	s_waitcnt vmcnt(15)
	v_lshlrev_b32_e32 v176, 16, v188
	v_and_b32_e32 v177, 0xffff0000, v188
	v_lshlrev_b32_e32 v178, 16, v189
	v_and_b32_e32 v179, 0xffff0000, v189
	v_lshlrev_b32_e32 v180, 16, v190
	v_and_b32_e32 v181, 0xffff0000, v190
	v_lshlrev_b32_e32 v182, 16, v191
	v_and_b32_e32 v183, 0xffff0000, v191
	v_pk_fma_f32 v[92:93], v[92:93], v[140:141], v[176:177]
	v_pk_fma_f32 v[94:95], v[94:95], v[142:143], v[178:179]
	v_pk_fma_f32 v[88:89], v[88:89], v[136:137], v[180:181]
	v_pk_fma_f32 v[90:91], v[90:91], v[138:139], v[182:183]
	v_cvt_pk_bf16_f32 v92, v92, v93
	v_cvt_pk_bf16_f32 v93, v94, v95
	v_cvt_pk_bf16_f32 v94, v88, v89
	v_cvt_pk_bf16_f32 v95, v90, v91
	v_add_u32_e32 v158, 0x20000, v156
	global_store_dwordx4 v158, v[92:95], s[96:97] offset:0
	s_waitcnt vmcnt(15)
	v_lshlrev_b32_e32 v176, 16, v192
	v_and_b32_e32 v177, 0xffff0000, v192
	v_lshlrev_b32_e32 v178, 16, v193
	v_and_b32_e32 v179, 0xffff0000, v193
	v_lshlrev_b32_e32 v180, 16, v194
	v_and_b32_e32 v181, 0xffff0000, v194
	v_lshlrev_b32_e32 v182, 16, v195
	v_and_b32_e32 v183, 0xffff0000, v195
	v_pk_fma_f32 v[84:85], v[84:85], v[132:133], v[176:177]
	v_pk_fma_f32 v[86:87], v[86:87], v[134:135], v[178:179]
	v_pk_fma_f32 v[80:81], v[80:81], v[128:129], v[180:181]
	v_pk_fma_f32 v[82:83], v[82:83], v[130:131], v[182:183]
	v_cvt_pk_bf16_f32 v84, v84, v85
	v_cvt_pk_bf16_f32 v85, v86, v87
	v_cvt_pk_bf16_f32 v86, v80, v81
	v_cvt_pk_bf16_f32 v87, v82, v83
	v_add_u32_e32 v158, 0x20000, v156
	global_store_dwordx4 v158, v[84:87], s[96:97] offset:256
	s_waitcnt vmcnt(15)
	v_lshlrev_b32_e32 v176, 16, v196
	v_and_b32_e32 v177, 0xffff0000, v196
	v_lshlrev_b32_e32 v178, 16, v197
	v_and_b32_e32 v179, 0xffff0000, v197
	v_lshlrev_b32_e32 v180, 16, v198
	v_and_b32_e32 v181, 0xffff0000, v198
	v_lshlrev_b32_e32 v182, 16, v199
	v_and_b32_e32 v183, 0xffff0000, v199
	v_pk_fma_f32 v[76:77], v[76:77], v[140:141], v[176:177]
	v_pk_fma_f32 v[78:79], v[78:79], v[142:143], v[178:179]
	v_pk_fma_f32 v[72:73], v[72:73], v[136:137], v[180:181]
	v_pk_fma_f32 v[74:75], v[74:75], v[138:139], v[182:183]
	v_cvt_pk_bf16_f32 v76, v76, v77
	v_cvt_pk_bf16_f32 v77, v78, v79
	v_cvt_pk_bf16_f32 v78, v72, v73
	v_cvt_pk_bf16_f32 v79, v74, v75
	v_add_u32_e32 v158, 0x30000, v156
	global_store_dwordx4 v158, v[76:79], s[96:97] offset:0
	s_waitcnt vmcnt(15)
	v_lshlrev_b32_e32 v176, 16, v200
	v_and_b32_e32 v177, 0xffff0000, v200
	v_lshlrev_b32_e32 v178, 16, v201
	v_and_b32_e32 v179, 0xffff0000, v201
	v_lshlrev_b32_e32 v180, 16, v202
	v_and_b32_e32 v181, 0xffff0000, v202
	v_lshlrev_b32_e32 v182, 16, v203
	v_and_b32_e32 v183, 0xffff0000, v203
	v_pk_fma_f32 v[68:69], v[68:69], v[132:133], v[176:177]
	v_pk_fma_f32 v[70:71], v[70:71], v[134:135], v[178:179]
	v_pk_fma_f32 v[64:65], v[64:65], v[128:129], v[180:181]
	v_pk_fma_f32 v[66:67], v[66:67], v[130:131], v[182:183]
	v_cvt_pk_bf16_f32 v68, v68, v69
	v_cvt_pk_bf16_f32 v69, v70, v71
	v_cvt_pk_bf16_f32 v70, v64, v65
	v_cvt_pk_bf16_f32 v71, v66, v67
	v_add_u32_e32 v158, 0x30000, v156
	global_store_dwordx4 v158, v[68:71], s[96:97] offset:256
	s_waitcnt vmcnt(15)
; __device__ __forceinline__ float bflo(unsigned w) { return __uint_as_float(w << 16); }
; __device__ __forceinline__ float bfhi(unsigned w) { return __uint_as_float(w & 0xffff0000u); }
; __device__ __forceinline__ u32x4 pack8u(f32x4 a, f32x4 b) { u32x4 w = {cvt_pk_bf16(a[0], a[1]), cvt_pk_bf16(a[2], a[3]), cvt_pk_bf16(b[0], b[1]), cvt_pk_bf16(b[2], b[3])}; return w; }
; #define PG8_WAIT_V(n) asm volatile("s_waitcnt vmcnt(" #n ")" ::: "memory")
; #define PG8_BAR __builtin_amdgcn_s_barrier()
; template <class Epi>
; __device__ __forceinline__ void gemm_phase(LAS unsigned char* lds, const Gemm g, const Epi& E) {
;     ...
;         if (!has_next) break;
; #pragma unroll
;         for (int a = 0; a < 2; ++a)
; #pragma unroll
;             for (int b = 0; b < 2; ++b)
; #pragma unroll
;                 for (int m = 0; m < 4; ++m)
; #pragma unroll
;                     for (int n = 0; n < 2; ++n) acc[a][b][m][n] = (f32x4){0.f, 0.f, 0.f, 0.f};
;         cur = nxt; cA = nA; cB = nB; ++ui;
;     }
;     PG8_WAIT_V(0);
;     if (wr == 0) PG8_BAR;
;     PG8_BAR;
;     __device__ __forceinline__ void operator()(const AccT& acc, const Unit& u, int wr, int wc, int fr, int fq) const {
;     ...
;                 for (int bj = 0; bj < 2; ++bj) {
;                     const size_t off = (size_t)row * D + u.pn * 256 + bj * 128 + wc * 32 + fq * 8;
;                     f32x4 x0, x1;
;                     if (XINF) { x0 = *(const f32x4*)(XINF + off); x1 = *(const f32x4*)(XINF + off + 4); }
;                     else { const u32x4 w = *(const u32x4*)(XIN16 + off); x0 = (f32x4){bflo(w[0]), bfhi(w[0]), bflo(w[1]), bfhi(w[1])}; x1 = (f32x4){bflo(w[2]), bfhi(w[2]), bflo(w[3]), bfhi(w[3])}; }
;                     *(u32x4*)(XOUT + off) = pack8u(x0 + gt[bj][0] * acc[ai][bj][m][0], x1 + gt[bj][1] * acc[ai][bj][m][1]);
	v_lshlrev_b32_e32 v176, 16, v204
	v_and_b32_e32 v177, 0xffff0000, v204
	v_lshlrev_b32_e32 v178, 16, v205
	v_and_b32_e32 v179, 0xffff0000, v205
	v_lshlrev_b32_e32 v180, 16, v206
	v_and_b32_e32 v181, 0xffff0000, v206
	v_lshlrev_b32_e32 v182, 16, v207
	v_and_b32_e32 v183, 0xffff0000, v207
	v_pk_fma_f32 v[60:61], v[60:61], v[140:141], v[176:177]
	v_pk_fma_f32 v[62:63], v[62:63], v[142:143], v[178:179]
	v_pk_fma_f32 v[56:57], v[56:57], v[136:137], v[180:181]
	v_pk_fma_f32 v[58:59], v[58:59], v[138:139], v[182:183]
	v_cvt_pk_bf16_f32 v60, v60, v61
	v_cvt_pk_bf16_f32 v61, v62, v63
	v_cvt_pk_bf16_f32 v62, v56, v57
	v_cvt_pk_bf16_f32 v63, v58, v59
	v_add_u32_e32 v158, 0x80000, v156
	global_store_dwordx4 v158, v[60:63], s[96:97] offset:0
	s_waitcnt vmcnt(15)
	v_lshlrev_b32_e32 v176, 16, v228
	v_and_b32_e32 v177, 0xffff0000, v228
	v_lshlrev_b32_e32 v178, 16, v229
	v_and_b32_e32 v179, 0xffff0000, v229
	v_lshlrev_b32_e32 v180, 16, v230
	v_and_b32_e32 v181, 0xffff0000, v230
	v_lshlrev_b32_e32 v182, 16, v231
	v_and_b32_e32 v183, 0xffff0000, v231
	v_pk_fma_f32 v[52:53], v[52:53], v[132:133], v[176:177]
	v_pk_fma_f32 v[54:55], v[54:55], v[134:135], v[178:179]
	v_pk_fma_f32 v[48:49], v[48:49], v[128:129], v[180:181]
	v_pk_fma_f32 v[50:51], v[50:51], v[130:131], v[182:183]
	v_cvt_pk_bf16_f32 v52, v52, v53
	v_cvt_pk_bf16_f32 v53, v54, v55
	v_cvt_pk_bf16_f32 v54, v48, v49
	v_cvt_pk_bf16_f32 v55, v50, v51
	v_add_u32_e32 v158, 0x80000, v156
	global_store_dwordx4 v158, v[52:55], s[96:97] offset:256
	s_waitcnt vmcnt(14)
	v_lshlrev_b32_e32 v176, 16, v164
	v_and_b32_e32 v177, 0xffff0000, v164
	v_lshlrev_b32_e32 v178, 16, v165
	v_and_b32_e32 v179, 0xffff0000, v165
	v_lshlrev_b32_e32 v180, 16, v166
	v_and_b32_e32 v181, 0xffff0000, v166
	v_lshlrev_b32_e32 v182, 16, v167
	v_and_b32_e32 v183, 0xffff0000, v167
	v_pk_fma_f32 v[44:45], v[44:45], v[140:141], v[176:177]
	v_pk_fma_f32 v[46:47], v[46:47], v[142:143], v[178:179]
	v_pk_fma_f32 v[40:41], v[40:41], v[136:137], v[180:181]
	v_pk_fma_f32 v[42:43], v[42:43], v[138:139], v[182:183]
	v_cvt_pk_bf16_f32 v44, v44, v45
	v_cvt_pk_bf16_f32 v45, v46, v47
	v_cvt_pk_bf16_f32 v46, v40, v41
	v_cvt_pk_bf16_f32 v47, v42, v43
	v_add_u32_e32 v158, 0x90000, v156
	global_store_dwordx4 v158, v[44:47], s[96:97] offset:0
	s_waitcnt vmcnt(14)
	v_lshlrev_b32_e32 v176, 16, v120
	v_and_b32_e32 v177, 0xffff0000, v120
	v_lshlrev_b32_e32 v178, 16, v121
	v_and_b32_e32 v179, 0xffff0000, v121
	v_lshlrev_b32_e32 v180, 16, v122
	v_and_b32_e32 v181, 0xffff0000, v122
	v_lshlrev_b32_e32 v182, 16, v123
	v_and_b32_e32 v183, 0xffff0000, v123
	v_pk_fma_f32 v[36:37], v[36:37], v[132:133], v[176:177]
	v_pk_fma_f32 v[38:39], v[38:39], v[134:135], v[178:179]
	v_pk_fma_f32 v[32:33], v[32:33], v[128:129], v[180:181]
	v_pk_fma_f32 v[34:35], v[34:35], v[130:131], v[182:183]
	v_cvt_pk_bf16_f32 v36, v36, v37
	v_cvt_pk_bf16_f32 v37, v38, v39
	v_cvt_pk_bf16_f32 v38, v32, v33
	v_cvt_pk_bf16_f32 v39, v34, v35
	v_add_u32_e32 v158, 0x90000, v156
	global_store_dwordx4 v158, v[36:39], s[96:97] offset:256
	s_waitcnt vmcnt(13)
	v_lshlrev_b32_e32 v176, 16, v168
	v_and_b32_e32 v177, 0xffff0000, v168
	v_lshlrev_b32_e32 v178, 16, v169
	v_and_b32_e32 v179, 0xffff0000, v169
	v_lshlrev_b32_e32 v180, 16, v170
	v_and_b32_e32 v181, 0xffff0000, v170
	v_lshlrev_b32_e32 v182, 16, v171
	v_and_b32_e32 v183, 0xffff0000, v171
	v_pk_fma_f32 v[28:29], v[28:29], v[140:141], v[176:177]
	v_pk_fma_f32 v[30:31], v[30:31], v[142:143], v[178:179]
	v_pk_fma_f32 v[24:25], v[24:25], v[136:137], v[180:181]
	v_pk_fma_f32 v[26:27], v[26:27], v[138:139], v[182:183]
	v_cvt_pk_bf16_f32 v28, v28, v29
	v_cvt_pk_bf16_f32 v29, v30, v31
	v_cvt_pk_bf16_f32 v30, v24, v25
	v_cvt_pk_bf16_f32 v31, v26, v27
	v_add_u32_e32 v158, 0xa0000, v156
	global_store_dwordx4 v158, v[28:31], s[96:97] offset:0
	s_waitcnt vmcnt(13)
	v_lshlrev_b32_e32 v176, 16, v112
	v_and_b32_e32 v177, 0xffff0000, v112
	v_lshlrev_b32_e32 v178, 16, v113
	v_and_b32_e32 v179, 0xffff0000, v113
	v_lshlrev_b32_e32 v180, 16, v114
	v_and_b32_e32 v181, 0xffff0000, v114
	v_lshlrev_b32_e32 v182, 16, v115
	v_and_b32_e32 v183, 0xffff0000, v115
	v_pk_fma_f32 v[20:21], v[20:21], v[132:133], v[176:177]
	v_pk_fma_f32 v[22:23], v[22:23], v[134:135], v[178:179]
	v_pk_fma_f32 v[16:17], v[16:17], v[128:129], v[180:181]
	v_pk_fma_f32 v[18:19], v[18:19], v[130:131], v[182:183]
	v_cvt_pk_bf16_f32 v20, v20, v21
	v_cvt_pk_bf16_f32 v21, v22, v23
	v_cvt_pk_bf16_f32 v22, v16, v17
	v_cvt_pk_bf16_f32 v23, v18, v19
	v_add_u32_e32 v158, 0xa0000, v156
	global_store_dwordx4 v158, v[20:23], s[96:97] offset:256
	s_waitcnt vmcnt(12)
	v_lshlrev_b32_e32 v176, 16, v172
	v_and_b32_e32 v177, 0xffff0000, v172
	v_lshlrev_b32_e32 v178, 16, v173
	v_and_b32_e32 v179, 0xffff0000, v173
	v_lshlrev_b32_e32 v180, 16, v174
	v_and_b32_e32 v181, 0xffff0000, v174
	v_lshlrev_b32_e32 v182, 16, v175
	v_and_b32_e32 v183, 0xffff0000, v175
	v_pk_fma_f32 v[12:13], v[12:13], v[140:141], v[176:177]
	v_pk_fma_f32 v[14:15], v[14:15], v[142:143], v[178:179]
	v_pk_fma_f32 v[8:9], v[8:9], v[136:137], v[180:181]
	v_pk_fma_f32 v[10:11], v[10:11], v[138:139], v[182:183]
	v_cvt_pk_bf16_f32 v12, v12, v13
	v_cvt_pk_bf16_f32 v13, v14, v15
	v_cvt_pk_bf16_f32 v14, v8, v9
	v_cvt_pk_bf16_f32 v15, v10, v11
	v_add_u32_e32 v158, 0xb0000, v156
	global_store_dwordx4 v158, v[12:15], s[96:97] offset:0
	s_waitcnt vmcnt(12)
	v_lshlrev_b32_e32 v176, 16, v104
	v_and_b32_e32 v177, 0xffff0000, v104
	v_lshlrev_b32_e32 v178, 16, v105
	v_and_b32_e32 v179, 0xffff0000, v105
	v_lshlrev_b32_e32 v180, 16, v106
	v_and_b32_e32 v181, 0xffff0000, v106
	v_lshlrev_b32_e32 v182, 16, v107
	v_and_b32_e32 v183, 0xffff0000, v107
	v_pk_fma_f32 v[4:5], v[4:5], v[132:133], v[176:177]
	v_pk_fma_f32 v[6:7], v[6:7], v[134:135], v[178:179]
	v_pk_fma_f32 v[0:1], v[0:1], v[128:129], v[180:181]
	v_pk_fma_f32 v[2:3], v[2:3], v[130:131], v[182:183]
	v_cvt_pk_bf16_f32 v4, v4, v5
	v_cvt_pk_bf16_f32 v5, v6, v7
	v_cvt_pk_bf16_f32 v6, v0, v1
	v_cvt_pk_bf16_f32 v7, v2, v3
	v_add_u32_e32 v158, 0xb0000, v156
	global_store_dwordx4 v158, v[4:7], s[96:97] offset:256
	s_mov_b64 s[28:29], s[42:43]
	s_mov_b64 s[26:27], s[0:1]
	s_mov_b32 s74, s71
	s_mov_b32 s76, s70
	s_and_b64 vcc, exec, s[40:41]
	v_readlane_b32 s82, v255, 24
	v_readlane_b32 s83, v255, 25
	s_cbranch_vccz .LBB0_862
	s_waitcnt vmcnt(0)
	s_cmpk_gt_u32 s3, 0xff
	s_cbranch_scc1 .LBB0_877
	s_barrier

; #define LAS __attribute__((address_space(3)))
; __global__ void __launch_bounds__(NTHR) mega(Params p) {
;     extern __shared__ __attribute__((aligned(16))) unsigned char smem[];
;     LAS unsigned char* lds = (LAS unsigned char*)smem;
;     cg::grid_group grid = cg::this_grid();
;     unsigned char* ws = p.ws;
;     float* MOD = (float*)(ws + WS_MOD); bf16_t* XA = (bf16_t*)(ws + WS_XA); bf16_t* H = (bf16_t*)(ws + WS_H);
;     unsigned* ctr = (unsigned*)(ws + WS_CTL);
;     volatile LAS unsigned* bst = (volatile LAS unsigned*)(lds + MISC_OFF + 16);
;     if (threadIdx.x == 0) { bst[0] = 0u; bst[1] = 0u; }
;     __syncthreads();
;     const XcdBarrier xbar = xcd_barrier_post((unsigned*)(ws + WS_BAR), bst);
;     for (int ph = p.ph_lo; ph < p.ph_hi; ++ph) {
	.amdhsa_kernel _Z4mega6Params
		.amdhsa_group_segment_fixed_size 0
		.amdhsa_private_segment_fixed_size 0
		.amdhsa_kernarg_size 456
		.amdhsa_user_sgpr_count 2
		.amdhsa_user_sgpr_dispatch_ptr 0
		.amdhsa_user_sgpr_queue_ptr 0
		.amdhsa_user_sgpr_kernarg_segment_ptr 1
		.amdhsa_user_sgpr_dispatch_id 0
		.amdhsa_user_sgpr_kernarg_preload_length 0
		.amdhsa_user_sgpr_kernarg_preload_offset 0
		.amdhsa_user_sgpr_private_segment_size 0
		.amdhsa_uses_dynamic_stack 0
		.amdhsa_enable_private_segment 0
		.amdhsa_system_sgpr_workgroup_id_x 1
		.amdhsa_system_sgpr_workgroup_id_y 0
		.amdhsa_system_sgpr_workgroup_id_z 0
		.amdhsa_system_sgpr_workgroup_info 0
		.amdhsa_system_vgpr_workitem_id 2
		.amdhsa_next_free_vgpr 256
		.amdhsa_next_free_sgpr 102
		.amdhsa_accum_offset 256
		.amdhsa_reserve_vcc 1
		.amdhsa_float_round_mode_32 0
		.amdhsa_float_round_mode_16_64 0
		.amdhsa_float_denorm_mode_32 3
		.amdhsa_float_denorm_mode_16_64 3
		.amdhsa_dx10_clamp 1
		.amdhsa_ieee_mode 1
		.amdhsa_fp16_overflow 0
		.amdhsa_tg_split 0
		.amdhsa_exception_fp_ieee_invalid_op 0
		.amdhsa_exception_fp_denorm_src 0
		.amdhsa_exception_fp_ieee_div_zero 0
		.amdhsa_exception_fp_ieee_overflow 0
		.amdhsa_exception_fp_ieee_underflow 0
		.amdhsa_exception_fp_ieee_inexact 0
		.amdhsa_exception_int_div_zero 0
	.end_amdhsa_kernel

; #define LAS __attribute__((address_space(3)))
; __global__ void __launch_bounds__(NTHR) mega(Params p) {
;     extern __shared__ __attribute__((aligned(16))) unsigned char smem[];
;     LAS unsigned char* lds = (LAS unsigned char*)smem;
;     cg::grid_group grid = cg::this_grid();
;     unsigned char* ws = p.ws;
;     float* MOD = (float*)(ws + WS_MOD); bf16_t* XA = (bf16_t*)(ws + WS_XA); bf16_t* H = (bf16_t*)(ws + WS_H);
;     unsigned* ctr = (unsigned*)(ws + WS_CTL);
;     volatile LAS unsigned* bst = (volatile LAS unsigned*)(lds + MISC_OFF + 16);
;     if (threadIdx.x == 0) { bst[0] = 0u; bst[1] = 0u; }
;     __syncthreads();
;     const XcdBarrier xbar = xcd_barrier_post((unsigned*)(ws + WS_BAR), bst);
;     for (int ph = p.ph_lo; ph < p.ph_hi; ++ph) {
amdhsa.kernels:
  - .agpr_count:     0
    .args:
      - .offset:         0
        .size:           200
        .value_kind:     by_value
      - .offset:         200
        .size:           4
        .value_kind:     hidden_block_count_x
      - .offset:         204
        .size:           4
        .value_kind:     hidden_block_count_y
      - .offset:         208
        .size:           4
        .value_kind:     hidden_block_count_z
      - .offset:         212
        .size:           2
        .value_kind:     hidden_group_size_x
      - .offset:         214
        .size:           2
        .value_kind:     hidden_group_size_y
      - .offset:         216
        .size:           2
        .value_kind:     hidden_group_size_z
      - .offset:         218
        .size:           2
        .value_kind:     hidden_remainder_x
      - .offset:         220
        .size:           2
        .value_kind:     hidden_remainder_y
      - .offset:         222
        .size:           2
        .value_kind:     hidden_remainder_z
      - .offset:         240
        .size:           8
        .value_kind:     hidden_global_offset_x
      - .offset:         248
        .size:           8
        .value_kind:     hidden_global_offset_y
      - .offset:         256
        .size:           8
        .value_kind:     hidden_global_offset_z
      - .offset:         264
        .size:           2
        .value_kind:     hidden_grid_dims
      - .offset:         288
        .size:           8
        .value_kind:     hidden_multigrid_sync_arg
      - .offset:         320
        .size:           4
        .value_kind:     hidden_dynamic_lds_size
    .group_segment_fixed_size: 0
    .kernarg_segment_align: 8
    .kernarg_segment_size: 456
    .language:       OpenCL C
    .language_version:
      - 2
      - 0
    .max_flat_workgroup_size: 512
    .name:           _Z4mega6Params
    .private_segment_fixed_size: 0
    .sgpr_count:     108
    .sgpr_spill_count: 279
    .symbol:         _Z4mega6Params.kd
    .uniform_work_group_size: 1
    .uses_dynamic_stack: false
    .vgpr_count:     256
    .vgpr_spill_count: 0
    .wavefront_size: 64
